# v14 with k order alternating per accumulator (every MFMA shares accumulator or one operand quad with its predecessor)
# speedup vs baseline: 1.0027x; 1.0027x over previous
; #define PG8_STAGE(bufoff, gbase, voff) do { _Pragma("unroll") for (int _i = 0; _i < 2; ++_i) \
;         __builtin_amdgcn_global_load_lds((const unsigned*)((const char*)(gbase) + (voff)[_i]), (PG8_LAS unsigned*)(lds + (bufoff) + ldsw + _i * 8192), 16, 0, 0); } while (0)
; #define PG8_LDA(dst, b, h) do { _Pragma("unroll") for (int m = 0; m < 4; ++m) _Pragma("unroll") for (int k = 0; k < 2; ++k) dst[m][k] = *(const PG8_LAS bf16x8*)(lds + PG8_SA(b, h) + aoff + m * 2048 + k * 1024); } while (0)
; #define PG8_LDB(dst, b, h) do { _Pragma("unroll") for (int n = 0; n < 2; ++n) _Pragma("unroll") for (int k = 0; k < 2; ++k) dst[n][k] = *(const PG8_LAS bf16x8*)(lds + PG8_SB(b, h) + boff + n * 2048 + k * 1024); } while (0)
; #define PG8_MMA(ai, bj, At, Bt) do { __builtin_amdgcn_s_setprio(1); _Pragma("unroll") for (int m = 0; m < 4; ++m) _Pragma("unroll") for (int n = 0; n < 2; ++n) _Pragma("unroll") for (int k = 0; k < 2; ++k) \
;         acc[ai][bj][m][n] = __builtin_amdgcn_mfma_f32_16x16x32_bf16(Bt[n][k], At[m][k], acc[ai][bj][m][n], 0, 0, 0); __builtin_amdgcn_s_setprio(0); } while (0)
; #define PG8_WAIT_V(n) asm volatile("s_waitcnt vmcnt(" #n ")" ::: "memory")
; #define PG8_WAIT_L(n) asm volatile("s_waitcnt lgkmcnt(" #n ")" ::: "memory")
; #define PG8_BAR __builtin_amdgcn_s_barrier()
; template <class Epi, class Sched, bool ALIGN_EPI = false, bool SP2 = false>
; __device__ __forceinline__ void gemm_phase(PG8_LAS unsigned char* lds, const Gemm g, const Sched& S, const Epi& E) {
;     ...
;             const char* a1 = cA + (size_t)(t + 1) * kstep;
;             const char* a2 = last ? nA : cA + (size_t)(t + 2) * kstep; const char* b2 = last ? nB : cB + (size_t)(t + 2) * kstep;
;             const char* a3 = a2 + kstep; const char* b3 = b2 + kstep;
;             if (last && has_next) S.a_ready(nxt);
;             if constexpr (SP2) {
;             PG8_LDB(B0, 0, 0); PG8_LDB(B1, 0, 1); PG8_SCHED; PG8_LDA(At, 0, 0); PG8_STAGE(PG8_SA(1, 1), a1 + hstep, voffA);
;             PG8_WAIT_V(8); PG8_WAIT_L(0); PG8_BAR; PG8_MMA(0, 0, At, B0); PG8_MMA(0, 1, At, B1); PG8_BAR; PG8_SCHED;
;             PG8_LDA(At, 0, 1); PG8_STAGE(PG8_SB(0, 0), b2, voffB); PG8_STAGE(PG8_SB(0, 1), b2 + hstep, voffB); PG8_STAGE(PG8_SA(0, 0), a2, voffA);
;             PG8_WAIT_V(8); PG8_WAIT_L(0); PG8_BAR; PG8_MMA(1, 0, At, B0); PG8_MMA(1, 1, At, B1); PG8_BAR; PG8_SCHED;
.LBB0_115:
	ds_read_b128 v[154:157], v150
	ds_read_b128 v[158:161], v150 offset:1024
	ds_read_b128 v[162:165], v150 offset:2048
	ds_read_b128 v[166:169], v150 offset:3072
	ds_read_b128 v[170:173], v151
	ds_read_b128 v[174:177], v151 offset:1024
	ds_read_b128 v[180:183], v151 offset:2048
	ds_read_b128 v[184:187], v151 offset:3072
	s_add_u32 s50, s48, 0x4000
	s_addc_u32 s51, s49, 0
	s_cmp_eq_u32 s76, 60
	s_cselect_b32 s74, s64, s50
	s_cselect_b32 s75, s25, s51
	s_cselect_b32 s72, s65, s68
	s_cselect_b32 s73, s19, s69
	s_add_u32 s50, s74, 0x8000
	s_addc_u32 s51, s75, 0
	s_sub_u32 s50, s48, 0x4000
	s_subb_u32 s51, s49, 0
	s_mov_b32 m0, s58
	s_nop 0
	global_load_lds_dwordx4 v130, s[50:51]
	s_mov_b32 m0, s59
	s_nop 0
	global_load_lds_dwordx4 v134, s[50:51]
	s_add_i32 m0, s28, 0xc000
	ds_read_b128 v[188:191], v152
	ds_read_b128 v[196:199], v152 offset:1024
	ds_read_b128 v[200:203], v152 offset:2048
	ds_read_b128 v[204:207], v152 offset:3072
	ds_read_b128 v[208:211], v152 offset:4096
	ds_read_b128 v[212:215], v152 offset:5120
	ds_read_b128 v[216:219], v152 offset:6144
	ds_read_b128 v[220:223], v152 offset:7168
	global_load_lds_dwordx4 v140, s[48:49]
	s_add_i32 m0, s28, 0xe000
	s_nop 0
	global_load_lds_dwordx4 v142, s[48:49]
	s_waitcnt vmcnt(8)
	s_waitcnt lgkmcnt(0)
	s_barrier
	s_waitcnt lgkmcnt(0)
	v_mfma_f32_16x16x32_bf16 v[126:129], v[154:157], v[188:191], v[126:129]
	v_mfma_f32_16x16x32_bf16 v[126:129], v[158:161], v[196:199], v[126:129]
	v_mfma_f32_16x16x32_bf16 v[110:113], v[158:161], v[204:207], v[110:113]
	v_mfma_f32_16x16x32_bf16 v[110:113], v[154:157], v[200:203], v[110:113]
	v_mfma_f32_16x16x32_bf16 v[94:97], v[154:157], v[208:211], v[94:97]
	v_mfma_f32_16x16x32_bf16 v[94:97], v[158:161], v[212:215], v[94:97]
	v_mfma_f32_16x16x32_bf16 v[78:81], v[158:161], v[220:223], v[78:81]
	v_mfma_f32_16x16x32_bf16 v[78:81], v[154:157], v[216:219], v[78:81]
	v_mfma_f32_16x16x32_bf16 v[70:73], v[162:165], v[216:219], v[70:73]
	v_mfma_f32_16x16x32_bf16 v[70:73], v[166:169], v[220:223], v[70:73]
	v_mfma_f32_16x16x32_bf16 v[86:89], v[166:169], v[212:215], v[86:89]
	v_mfma_f32_16x16x32_bf16 v[86:89], v[162:165], v[208:211], v[86:89]
	v_mfma_f32_16x16x32_bf16 v[102:105], v[162:165], v[200:203], v[102:105]
	v_mfma_f32_16x16x32_bf16 v[102:105], v[166:169], v[204:207], v[102:105]
	v_mfma_f32_16x16x32_bf16 v[118:121], v[166:169], v[196:199], v[118:121]
	v_mfma_f32_16x16x32_bf16 v[118:121], v[162:165], v[188:191], v[118:121]
	v_mfma_f32_16x16x32_bf16 v[122:125], v[170:173], v[188:191], v[122:125]
	v_mfma_f32_16x16x32_bf16 v[122:125], v[174:177], v[196:199], v[122:125]
	v_mfma_f32_16x16x32_bf16 v[106:109], v[174:177], v[204:207], v[106:109]
	v_mfma_f32_16x16x32_bf16 v[106:109], v[170:173], v[200:203], v[106:109]
	v_mfma_f32_16x16x32_bf16 v[90:93], v[170:173], v[208:211], v[90:93]
	v_mfma_f32_16x16x32_bf16 v[90:93], v[174:177], v[212:215], v[90:93]
	v_mfma_f32_16x16x32_bf16 v[74:77], v[174:177], v[220:223], v[74:77]
	v_mfma_f32_16x16x32_bf16 v[74:77], v[170:173], v[216:219], v[74:77]
	v_mfma_f32_16x16x32_bf16 v[66:69], v[180:183], v[216:219], v[66:69]
	v_mfma_f32_16x16x32_bf16 v[66:69], v[184:187], v[220:223], v[66:69]
	v_mfma_f32_16x16x32_bf16 v[82:85], v[184:187], v[212:215], v[82:85]
	v_mfma_f32_16x16x32_bf16 v[82:85], v[180:183], v[208:211], v[82:85]
	v_mfma_f32_16x16x32_bf16 v[98:101], v[180:183], v[200:203], v[98:101]
	v_mfma_f32_16x16x32_bf16 v[98:101], v[184:187], v[204:207], v[98:101]
	v_mfma_f32_16x16x32_bf16 v[114:117], v[184:187], v[196:199], v[114:117]
	v_mfma_f32_16x16x32_bf16 v[114:117], v[180:183], v[188:191], v[114:117]
	s_barrier
	s_add_i32 s77, s61, s3
	s_mov_b32 m0, s77
	ds_read_b128 v[188:191], v152 offset:16384
	ds_read_b128 v[196:199], v152 offset:17408
	ds_read_b128 v[200:203], v152 offset:18432
	ds_read_b128 v[204:207], v152 offset:19456
	ds_read_b128 v[208:211], v152 offset:20480
	ds_read_b128 v[212:215], v152 offset:21504
	ds_read_b128 v[216:219], v152 offset:22528
	ds_read_b128 v[220:223], v152 offset:23552
	global_load_lds_dwordx4 v132, s[72:73]
	s_add_i32 m0, s77, 0x2000
	s_add_u32 s78, s72, 0x4000
	s_addc_u32 s79, s73, 0
	s_add_i32 s77, s62, s3
	global_load_lds_dwordx4 v136, s[72:73]
	s_mov_b32 m0, s77
	s_nop 0
	global_load_lds_dwordx4 v132, s[78:79]
	s_add_i32 m0, s77, 0x2000
	s_nop 0
	global_load_lds_dwordx4 v136, s[78:79]
	s_waitcnt vmcnt(6)
	s_waitcnt lgkmcnt(0)
	s_barrier
	s_waitcnt lgkmcnt(0)
	v_mfma_f32_16x16x32_bf16 v[62:65], v[154:157], v[188:191], v[62:65]
	v_mfma_f32_16x16x32_bf16 v[62:65], v[158:161], v[196:199], v[62:65]
	v_mfma_f32_16x16x32_bf16 v[46:49], v[158:161], v[204:207], v[46:49]
	v_mfma_f32_16x16x32_bf16 v[46:49], v[154:157], v[200:203], v[46:49]
	v_mfma_f32_16x16x32_bf16 v[30:33], v[154:157], v[208:211], v[30:33]
	v_mfma_f32_16x16x32_bf16 v[30:33], v[158:161], v[212:215], v[30:33]
	v_mfma_f32_16x16x32_bf16 v[14:17], v[158:161], v[220:223], v[14:17]
	v_mfma_f32_16x16x32_bf16 v[14:17], v[154:157], v[216:219], v[14:17]
	v_mfma_f32_16x16x32_bf16 v[6:9], v[162:165], v[216:219], v[6:9]
	v_mfma_f32_16x16x32_bf16 v[6:9], v[166:169], v[220:223], v[6:9]
	v_mfma_f32_16x16x32_bf16 v[22:25], v[166:169], v[212:215], v[22:25]
	v_mfma_f32_16x16x32_bf16 v[22:25], v[162:165], v[208:211], v[22:25]
	v_mfma_f32_16x16x32_bf16 v[38:41], v[162:165], v[200:203], v[38:41]
	v_mfma_f32_16x16x32_bf16 v[38:41], v[166:169], v[204:207], v[38:41]
	v_mfma_f32_16x16x32_bf16 v[54:57], v[166:169], v[196:199], v[54:57]
	v_mfma_f32_16x16x32_bf16 v[54:57], v[162:165], v[188:191], v[54:57]
	v_mfma_f32_16x16x32_bf16 v[58:61], v[170:173], v[188:191], v[58:61]
	v_mfma_f32_16x16x32_bf16 v[58:61], v[174:177], v[196:199], v[58:61]
	v_mfma_f32_16x16x32_bf16 v[42:45], v[174:177], v[204:207], v[42:45]
	v_mfma_f32_16x16x32_bf16 v[42:45], v[170:173], v[200:203], v[42:45]
	v_mfma_f32_16x16x32_bf16 v[26:29], v[170:173], v[208:211], v[26:29]
	v_mfma_f32_16x16x32_bf16 v[26:29], v[174:177], v[212:215], v[26:29]
	v_mfma_f32_16x16x32_bf16 v[10:13], v[174:177], v[220:223], v[10:13]
	v_mfma_f32_16x16x32_bf16 v[10:13], v[170:173], v[216:219], v[10:13]
	v_mfma_f32_16x16x32_bf16 v[2:5], v[180:183], v[216:219], v[2:5]
	v_mfma_f32_16x16x32_bf16 v[2:5], v[184:187], v[220:223], v[2:5]
	v_mfma_f32_16x16x32_bf16 v[18:21], v[184:187], v[212:215], v[18:21]
	v_mfma_f32_16x16x32_bf16 v[18:21], v[180:183], v[208:211], v[18:21]
	v_mfma_f32_16x16x32_bf16 v[34:37], v[180:183], v[200:203], v[34:37]
	v_mfma_f32_16x16x32_bf16 v[34:37], v[184:187], v[204:207], v[34:37]
	v_mfma_f32_16x16x32_bf16 v[50:53], v[184:187], v[196:199], v[50:53]
	v_mfma_f32_16x16x32_bf16 v[50:53], v[180:183], v[188:191], v[50:53]
	s_barrier
; #define PG8_STAGE(bufoff, gbase, voff) do { _Pragma("unroll") for (int _i = 0; _i < 2; ++_i) \
;         __builtin_amdgcn_global_load_lds((const unsigned*)((const char*)(gbase) + (voff)[_i]), (PG8_LAS unsigned*)(lds + (bufoff) + ldsw + _i * 8192), 16, 0, 0); } while (0)
; #define PG8_LDA(dst, b, h) do { _Pragma("unroll") for (int m = 0; m < 4; ++m) _Pragma("unroll") for (int k = 0; k < 2; ++k) dst[m][k] = *(const PG8_LAS bf16x8*)(lds + PG8_SA(b, h) + aoff + m * 2048 + k * 1024); } while (0)
; #define PG8_LDB(dst, b, h) do { _Pragma("unroll") for (int n = 0; n < 2; ++n) _Pragma("unroll") for (int k = 0; k < 2; ++k) dst[n][k] = *(const PG8_LAS bf16x8*)(lds + PG8_SB(b, h) + boff + n * 2048 + k * 1024); } while (0)
; #define PG8_MMA(ai, bj, At, Bt) do { __builtin_amdgcn_s_setprio(1); _Pragma("unroll") for (int m = 0; m < 4; ++m) _Pragma("unroll") for (int n = 0; n < 2; ++n) _Pragma("unroll") for (int k = 0; k < 2; ++k) \
;         acc[ai][bj][m][n] = __builtin_amdgcn_mfma_f32_16x16x32_bf16(Bt[n][k], At[m][k], acc[ai][bj][m][n], 0, 0, 0); __builtin_amdgcn_s_setprio(0); } while (0)
; #define PG8_WAIT_V(n) asm volatile("s_waitcnt vmcnt(" #n ")" ::: "memory")
; #define PG8_WAIT_L(n) asm volatile("s_waitcnt lgkmcnt(" #n ")" ::: "memory")
; #define PG8_BAR __builtin_amdgcn_s_barrier()
; #define PG8_SCHED __builtin_amdgcn_sched_barrier(0)
; template <class Epi, class Sched, bool ALIGN_EPI = false, bool SP2 = false>
; __device__ __forceinline__ void gemm_phase(PG8_LAS unsigned char* lds, const Gemm g, const Sched& S, const Epi& E) {
;     ...
;             PG8_LDB(B0, 1, 0); PG8_LDB(B1, 1, 1); PG8_SCHED; PG8_LDA(At, 1, 0); PG8_STAGE(PG8_SA(0, 1), a2 + hstep, voffA);
;             PG8_WAIT_V(8); PG8_WAIT_L(0); PG8_BAR; PG8_MMA(0, 0, At, B0); PG8_MMA(0, 1, At, B1); PG8_BAR; PG8_SCHED;
;             PG8_LDA(At, 1, 1); PG8_STAGE(PG8_SB(1, 0), b3, voffB); PG8_STAGE(PG8_SB(1, 1), b3 + hstep, voffB); PG8_STAGE(PG8_SA(1, 0), a3, voffA);
;             PG8_WAIT_V(8); PG8_WAIT_L(0); PG8_BAR; PG8_MMA(1, 0, At, B0); PG8_MMA(1, 1, At, B1); PG8_BAR; PG8_SCHED;
	s_add_i32 s77, 0, 0x18000
	v_add_u32_e32 v138, s77, v148
	s_add_i32 s78, 0, 0x1c000
	ds_read_b128 v[154:157], v138
	ds_read_b128 v[158:161], v138 offset:1024
	ds_read_b128 v[162:165], v138 offset:2048
	ds_read_b128 v[166:169], v138 offset:3072
	v_add_u32_e32 v138, s78, v148
	ds_read_b128 v[170:173], v138
	ds_read_b128 v[174:177], v138 offset:1024
	ds_read_b128 v[180:183], v138 offset:2048
	ds_read_b128 v[184:187], v138 offset:3072
	s_mov_b32 m0, s28
	s_nop 0
	global_load_lds_dwordx4 v130, s[74:75]
	s_mov_b32 m0, s29
	s_nop 0
	global_load_lds_dwordx4 v134, s[74:75]
	s_add_u32 s74, s74, 0x4000
	s_addc_u32 s75, s75, 0
	s_mov_b32 m0, s30
	ds_read_b128 v[188:191], v152 offset:32768
	ds_read_b128 v[196:199], v152 offset:33792
	ds_read_b128 v[200:203], v152 offset:34816
	ds_read_b128 v[204:207], v152 offset:35840
	ds_read_b128 v[208:211], v152 offset:36864
	ds_read_b128 v[212:215], v152 offset:37888
	ds_read_b128 v[216:219], v152 offset:38912
	ds_read_b128 v[220:223], v152 offset:39936
	global_load_lds_dwordx4 v130, s[74:75]
	s_mov_b32 m0, s31
	s_nop 0
	global_load_lds_dwordx4 v134, s[74:75]
	s_waitcnt vmcnt(8)
	s_waitcnt lgkmcnt(0)
	s_barrier
	s_waitcnt lgkmcnt(0)
	v_mfma_f32_16x16x32_bf16 v[126:129], v[154:157], v[188:191], v[126:129]
	v_mfma_f32_16x16x32_bf16 v[126:129], v[158:161], v[196:199], v[126:129]
	v_mfma_f32_16x16x32_bf16 v[110:113], v[158:161], v[204:207], v[110:113]
	v_mfma_f32_16x16x32_bf16 v[110:113], v[154:157], v[200:203], v[110:113]
	v_mfma_f32_16x16x32_bf16 v[94:97], v[154:157], v[208:211], v[94:97]
	v_mfma_f32_16x16x32_bf16 v[94:97], v[158:161], v[212:215], v[94:97]
	v_mfma_f32_16x16x32_bf16 v[78:81], v[158:161], v[220:223], v[78:81]
	v_mfma_f32_16x16x32_bf16 v[78:81], v[154:157], v[216:219], v[78:81]
	v_mfma_f32_16x16x32_bf16 v[70:73], v[162:165], v[216:219], v[70:73]
	v_mfma_f32_16x16x32_bf16 v[70:73], v[166:169], v[220:223], v[70:73]
	v_mfma_f32_16x16x32_bf16 v[86:89], v[166:169], v[212:215], v[86:89]
	v_mfma_f32_16x16x32_bf16 v[86:89], v[162:165], v[208:211], v[86:89]
	v_mfma_f32_16x16x32_bf16 v[102:105], v[162:165], v[200:203], v[102:105]
	v_mfma_f32_16x16x32_bf16 v[102:105], v[166:169], v[204:207], v[102:105]
	v_mfma_f32_16x16x32_bf16 v[118:121], v[166:169], v[196:199], v[118:121]
	v_mfma_f32_16x16x32_bf16 v[118:121], v[162:165], v[188:191], v[118:121]
	v_mfma_f32_16x16x32_bf16 v[122:125], v[170:173], v[188:191], v[122:125]
	v_mfma_f32_16x16x32_bf16 v[122:125], v[174:177], v[196:199], v[122:125]
	v_mfma_f32_16x16x32_bf16 v[106:109], v[174:177], v[204:207], v[106:109]
	v_mfma_f32_16x16x32_bf16 v[106:109], v[170:173], v[200:203], v[106:109]
	v_mfma_f32_16x16x32_bf16 v[90:93], v[170:173], v[208:211], v[90:93]
	v_mfma_f32_16x16x32_bf16 v[90:93], v[174:177], v[212:215], v[90:93]
	v_mfma_f32_16x16x32_bf16 v[74:77], v[174:177], v[220:223], v[74:77]
	v_mfma_f32_16x16x32_bf16 v[74:77], v[170:173], v[216:219], v[74:77]
	v_mfma_f32_16x16x32_bf16 v[66:69], v[180:183], v[216:219], v[66:69]
	v_mfma_f32_16x16x32_bf16 v[66:69], v[184:187], v[220:223], v[66:69]
	v_mfma_f32_16x16x32_bf16 v[82:85], v[184:187], v[212:215], v[82:85]
	v_mfma_f32_16x16x32_bf16 v[82:85], v[180:183], v[208:211], v[82:85]
	v_mfma_f32_16x16x32_bf16 v[98:101], v[180:183], v[200:203], v[98:101]
	v_mfma_f32_16x16x32_bf16 v[98:101], v[184:187], v[204:207], v[98:101]
	v_mfma_f32_16x16x32_bf16 v[114:117], v[184:187], v[196:199], v[114:117]
	v_mfma_f32_16x16x32_bf16 v[114:117], v[180:183], v[188:191], v[114:117]
	s_barrier
	s_add_u32 s74, s72, 0x8000
	s_addc_u32 s75, s73, 0
	s_add_i32 s77, s77, s3
	s_mov_b32 m0, s77
	ds_read_b128 v[188:191], v152 offset:49152
	ds_read_b128 v[196:199], v152 offset:50176
	ds_read_b128 v[200:203], v152 offset:51200
	ds_read_b128 v[204:207], v152 offset:52224
	ds_read_b128 v[208:211], v152 offset:53248
	ds_read_b128 v[212:215], v152 offset:54272
	ds_read_b128 v[216:219], v152 offset:55296
	ds_read_b128 v[220:223], v152 offset:56320
	global_load_lds_dwordx4 v132, s[74:75]
	s_add_i32 m0, s77, 0x2000
	s_add_u32 s72, s72, 0xc000
	v_lshl_add_u64 v[224:225], s[74:75], 0, v[136:137]
	s_addc_u32 s73, s73, 0
	s_add_i32 s74, s78, s3
	global_load_lds_dwordx4 v[224:225], off
	s_mov_b32 m0, s74
	s_nop 0
	global_load_lds_dwordx4 v132, s[72:73]
	s_add_i32 m0, s74, 0x2000
	s_nop 0
	global_load_lds_dwordx4 v136, s[72:73]
	s_waitcnt vmcnt(6)
	s_waitcnt lgkmcnt(0)
	s_barrier
	s_waitcnt lgkmcnt(0)
	v_mfma_f32_16x16x32_bf16 v[62:65], v[154:157], v[188:191], v[62:65]
	v_mfma_f32_16x16x32_bf16 v[62:65], v[158:161], v[196:199], v[62:65]
	v_mfma_f32_16x16x32_bf16 v[46:49], v[158:161], v[204:207], v[46:49]
	v_mfma_f32_16x16x32_bf16 v[46:49], v[154:157], v[200:203], v[46:49]
	v_mfma_f32_16x16x32_bf16 v[30:33], v[154:157], v[208:211], v[30:33]
	v_mfma_f32_16x16x32_bf16 v[30:33], v[158:161], v[212:215], v[30:33]
	v_mfma_f32_16x16x32_bf16 v[14:17], v[158:161], v[220:223], v[14:17]
	v_mfma_f32_16x16x32_bf16 v[14:17], v[154:157], v[216:219], v[14:17]
	v_mfma_f32_16x16x32_bf16 v[6:9], v[162:165], v[216:219], v[6:9]
	v_mfma_f32_16x16x32_bf16 v[6:9], v[166:169], v[220:223], v[6:9]
	v_mfma_f32_16x16x32_bf16 v[22:25], v[166:169], v[212:215], v[22:25]
	v_mfma_f32_16x16x32_bf16 v[22:25], v[162:165], v[208:211], v[22:25]
	v_mfma_f32_16x16x32_bf16 v[38:41], v[162:165], v[200:203], v[38:41]
	v_mfma_f32_16x16x32_bf16 v[38:41], v[166:169], v[204:207], v[38:41]
	v_mfma_f32_16x16x32_bf16 v[54:57], v[166:169], v[196:199], v[54:57]
	v_mfma_f32_16x16x32_bf16 v[54:57], v[162:165], v[188:191], v[54:57]
	v_mfma_f32_16x16x32_bf16 v[58:61], v[170:173], v[188:191], v[58:61]
	v_mfma_f32_16x16x32_bf16 v[58:61], v[174:177], v[196:199], v[58:61]
	v_mfma_f32_16x16x32_bf16 v[42:45], v[174:177], v[204:207], v[42:45]
	v_mfma_f32_16x16x32_bf16 v[42:45], v[170:173], v[200:203], v[42:45]
	v_mfma_f32_16x16x32_bf16 v[26:29], v[170:173], v[208:211], v[26:29]
	v_mfma_f32_16x16x32_bf16 v[26:29], v[174:177], v[212:215], v[26:29]
	v_mfma_f32_16x16x32_bf16 v[10:13], v[174:177], v[220:223], v[10:13]
	v_mfma_f32_16x16x32_bf16 v[10:13], v[170:173], v[216:219], v[10:13]
	v_mfma_f32_16x16x32_bf16 v[2:5], v[180:183], v[216:219], v[2:5]
	v_mfma_f32_16x16x32_bf16 v[2:5], v[184:187], v[220:223], v[2:5]
	v_mfma_f32_16x16x32_bf16 v[18:21], v[184:187], v[212:215], v[18:21]
	v_mfma_f32_16x16x32_bf16 v[18:21], v[180:183], v[208:211], v[18:21]
	v_mfma_f32_16x16x32_bf16 v[34:37], v[180:183], v[200:203], v[34:37]
	v_mfma_f32_16x16x32_bf16 v[34:37], v[184:187], v[204:207], v[34:37]
	v_mfma_f32_16x16x32_bf16 v[50:53], v[184:187], v[196:199], v[50:53]
	v_mfma_f32_16x16x32_bf16 v[50:53], v[180:183], v[188:191], v[50:53]
	s_barrier
	s_add_i32 s76, s76, 2
	s_add_u32 s48, s48, 0x10000
	s_addc_u32 s49, s49, 0
	s_add_u32 s68, s68, 0x10000
	s_addc_u32 s69, s69, 0
	s_cmp_gt_u32 s76, 61
	s_cbranch_scc0 .LBB0_115
	s_and_b64 vcc, exec, s[14:15]
	s_cbranch_vccz .LBB0_118
	s_barrier

; #define PG8_STAGE(bufoff, gbase, voff) do { _Pragma("unroll") for (int _i = 0; _i < 2; ++_i) \
;         __builtin_amdgcn_global_load_lds((const unsigned*)((const char*)(gbase) + (voff)[_i]), (PG8_LAS unsigned*)(lds + (bufoff) + ldsw + _i * 8192), 16, 0, 0); } while (0)
; #define PG8_LDA(dst, b, h) do { _Pragma("unroll") for (int m = 0; m < 4; ++m) _Pragma("unroll") for (int k = 0; k < 2; ++k) dst[m][k] = *(const PG8_LAS bf16x8*)(lds + PG8_SA(b, h) + aoff + m * 2048 + k * 1024); } while (0)
; #define PG8_LDB(dst, b, h) do { _Pragma("unroll") for (int n = 0; n < 2; ++n) _Pragma("unroll") for (int k = 0; k < 2; ++k) dst[n][k] = *(const PG8_LAS bf16x8*)(lds + PG8_SB(b, h) + boff + n * 2048 + k * 1024); } while (0)
; #define PG8_MMA(ai, bj, At, Bt) do { __builtin_amdgcn_s_setprio(1); _Pragma("unroll") for (int m = 0; m < 4; ++m) _Pragma("unroll") for (int n = 0; n < 2; ++n) _Pragma("unroll") for (int k = 0; k < 2; ++k) \
;         acc[ai][bj][m][n] = __builtin_amdgcn_mfma_f32_16x16x32_bf16(Bt[n][k], At[m][k], acc[ai][bj][m][n], 0, 0, 0); __builtin_amdgcn_s_setprio(0); } while (0)
; #define PG8_WAIT_V(n) asm volatile("s_waitcnt vmcnt(" #n ")" ::: "memory")
; #define PG8_WAIT_L(n) asm volatile("s_waitcnt lgkmcnt(" #n ")" ::: "memory")
; #define PG8_BAR __builtin_amdgcn_s_barrier()
; template <class Epi, class Sched, bool ALIGN_EPI = false, bool SP2 = false>
; __device__ __forceinline__ void gemm_phase(PG8_LAS unsigned char* lds, const Gemm g, const Sched& S, const Epi& E) {
;     ...
;             const char* a1 = cA + (size_t)(t + 1) * kstep;
;             const char* a2 = last ? nA : cA + (size_t)(t + 2) * kstep; const char* b2 = last ? nB : cB + (size_t)(t + 2) * kstep;
;             const char* a3 = a2 + kstep; const char* b3 = b2 + kstep;
;             if (last && has_next) S.a_ready(nxt);
;             if constexpr (SP2) {
;             PG8_LDB(B0, 0, 0); PG8_LDB(B1, 0, 1); PG8_SCHED; PG8_LDA(At, 0, 0); PG8_STAGE(PG8_SA(1, 1), a1 + hstep, voffA);
;             PG8_WAIT_V(8); PG8_WAIT_L(0); PG8_BAR; PG8_MMA(0, 0, At, B0); PG8_MMA(0, 1, At, B1); PG8_BAR; PG8_SCHED;
;             PG8_LDA(At, 0, 1); PG8_STAGE(PG8_SB(0, 0), b2, voffB); PG8_STAGE(PG8_SB(0, 1), b2 + hstep, voffB); PG8_STAGE(PG8_SA(0, 0), a2, voffA);
;             PG8_WAIT_V(8); PG8_WAIT_L(0); PG8_BAR; PG8_MMA(1, 0, At, B0); PG8_MMA(1, 1, At, B1); PG8_BAR; PG8_SCHED;
.LBB0_200:
	ds_read_b128 v[148:151], v154
	ds_read_b128 v[158:161], v154 offset:1024
	ds_read_b128 v[162:165], v154 offset:2048
	ds_read_b128 v[166:169], v154 offset:3072
	ds_read_b128 v[170:173], v155
	ds_read_b128 v[174:177], v155 offset:1024
	ds_read_b128 v[180:183], v155 offset:2048
	ds_read_b128 v[184:187], v155 offset:3072
	s_add_u32 s46, s44, 0x4000
	s_addc_u32 s47, s45, 0
	s_cmpk_eq_i32 s76, 0xa8
	s_cselect_b32 s50, s6, s46
	s_cselect_b32 s51, s7, s47
	s_cselect_b32 s48, s24, s74
	s_cselect_b32 s49, s25, s75
	s_add_u32 s46, s50, 0x8000
	s_addc_u32 s47, s51, 0
	s_sub_u32 s46, s44, 0x4000
	s_subb_u32 s47, s45, 0
	s_mov_b32 m0, s57
	s_nop 0
	global_load_lds_dwordx4 v130, s[46:47]
	s_mov_b32 m0, s58
	s_nop 0
	global_load_lds_dwordx4 v134, s[46:47]
	s_add_i32 m0, s26, 0xc000
	ds_read_b128 v[188:191], v156
	ds_read_b128 v[196:199], v156 offset:1024
	ds_read_b128 v[200:203], v156 offset:2048
	ds_read_b128 v[204:207], v156 offset:3072
	ds_read_b128 v[208:211], v156 offset:4096
	ds_read_b128 v[212:215], v156 offset:5120
	ds_read_b128 v[216:219], v156 offset:6144
	ds_read_b128 v[220:223], v156 offset:7168
	global_load_lds_dwordx4 v140, s[44:45]
	s_add_i32 m0, s26, 0xe000
	s_nop 0
	global_load_lds_dwordx4 v142, s[44:45]
	s_waitcnt vmcnt(8)
	s_waitcnt lgkmcnt(0)
	s_barrier
	s_waitcnt lgkmcnt(0)
	v_mfma_f32_16x16x32_bf16 v[126:129], v[148:151], v[188:191], v[126:129]
	v_mfma_f32_16x16x32_bf16 v[126:129], v[158:161], v[196:199], v[126:129]
	v_mfma_f32_16x16x32_bf16 v[110:113], v[158:161], v[204:207], v[110:113]
	v_mfma_f32_16x16x32_bf16 v[110:113], v[148:151], v[200:203], v[110:113]
	v_mfma_f32_16x16x32_bf16 v[94:97], v[148:151], v[208:211], v[94:97]
	v_mfma_f32_16x16x32_bf16 v[94:97], v[158:161], v[212:215], v[94:97]
	v_mfma_f32_16x16x32_bf16 v[78:81], v[158:161], v[220:223], v[78:81]
	v_mfma_f32_16x16x32_bf16 v[78:81], v[148:151], v[216:219], v[78:81]
	v_mfma_f32_16x16x32_bf16 v[74:77], v[162:165], v[216:219], v[74:77]
	v_mfma_f32_16x16x32_bf16 v[74:77], v[166:169], v[220:223], v[74:77]
	v_mfma_f32_16x16x32_bf16 v[90:93], v[166:169], v[212:215], v[90:93]
	v_mfma_f32_16x16x32_bf16 v[90:93], v[162:165], v[208:211], v[90:93]
	v_mfma_f32_16x16x32_bf16 v[106:109], v[162:165], v[200:203], v[106:109]
	v_mfma_f32_16x16x32_bf16 v[106:109], v[166:169], v[204:207], v[106:109]
	v_mfma_f32_16x16x32_bf16 v[122:125], v[166:169], v[196:199], v[122:125]
	v_mfma_f32_16x16x32_bf16 v[122:125], v[162:165], v[188:191], v[122:125]
	v_mfma_f32_16x16x32_bf16 v[118:121], v[170:173], v[188:191], v[118:121]
	v_mfma_f32_16x16x32_bf16 v[118:121], v[174:177], v[196:199], v[118:121]
	v_mfma_f32_16x16x32_bf16 v[102:105], v[174:177], v[204:207], v[102:105]
	v_mfma_f32_16x16x32_bf16 v[102:105], v[170:173], v[200:203], v[102:105]
	v_mfma_f32_16x16x32_bf16 v[86:89], v[170:173], v[208:211], v[86:89]
	v_mfma_f32_16x16x32_bf16 v[86:89], v[174:177], v[212:215], v[86:89]
	v_mfma_f32_16x16x32_bf16 v[70:73], v[174:177], v[220:223], v[70:73]
	v_mfma_f32_16x16x32_bf16 v[70:73], v[170:173], v[216:219], v[70:73]
	v_mfma_f32_16x16x32_bf16 v[66:69], v[180:183], v[216:219], v[66:69]
	v_mfma_f32_16x16x32_bf16 v[66:69], v[184:187], v[220:223], v[66:69]
	v_mfma_f32_16x16x32_bf16 v[82:85], v[184:187], v[212:215], v[82:85]
	v_mfma_f32_16x16x32_bf16 v[82:85], v[180:183], v[208:211], v[82:85]
	v_mfma_f32_16x16x32_bf16 v[98:101], v[180:183], v[200:203], v[98:101]
	v_mfma_f32_16x16x32_bf16 v[98:101], v[184:187], v[204:207], v[98:101]
	v_mfma_f32_16x16x32_bf16 v[114:117], v[184:187], v[196:199], v[114:117]
	v_mfma_f32_16x16x32_bf16 v[114:117], v[180:183], v[188:191], v[114:117]
	s_barrier
	s_add_i32 s77, s59, s3
	s_mov_b32 m0, s77
	ds_read_b128 v[188:191], v156 offset:16384
	ds_read_b128 v[196:199], v156 offset:17408
	ds_read_b128 v[200:203], v156 offset:18432
	ds_read_b128 v[204:207], v156 offset:19456
	ds_read_b128 v[208:211], v156 offset:20480
	ds_read_b128 v[212:215], v156 offset:21504
	ds_read_b128 v[216:219], v156 offset:22528
	ds_read_b128 v[220:223], v156 offset:23552
	global_load_lds_dwordx4 v132, s[48:49]
	s_add_i32 m0, s77, 0x2000
	s_add_u32 s78, s48, 0x4000
	s_addc_u32 s79, s49, 0
	s_add_i32 s77, s61, s3
	global_load_lds_dwordx4 v136, s[48:49]
	s_mov_b32 m0, s77
	s_nop 0
	global_load_lds_dwordx4 v132, s[78:79]
	s_add_i32 m0, s77, 0x2000
	s_nop 0
	global_load_lds_dwordx4 v136, s[78:79]
	s_waitcnt vmcnt(6)
	s_waitcnt lgkmcnt(0)
	s_barrier
	s_waitcnt lgkmcnt(0)
	v_mfma_f32_16x16x32_bf16 v[62:65], v[148:151], v[188:191], v[62:65]
	v_mfma_f32_16x16x32_bf16 v[62:65], v[158:161], v[196:199], v[62:65]
	v_mfma_f32_16x16x32_bf16 v[46:49], v[158:161], v[204:207], v[46:49]
	v_mfma_f32_16x16x32_bf16 v[46:49], v[148:151], v[200:203], v[46:49]
	v_mfma_f32_16x16x32_bf16 v[30:33], v[148:151], v[208:211], v[30:33]
	v_mfma_f32_16x16x32_bf16 v[30:33], v[158:161], v[212:215], v[30:33]
	v_mfma_f32_16x16x32_bf16 v[14:17], v[158:161], v[220:223], v[14:17]
	v_mfma_f32_16x16x32_bf16 v[14:17], v[148:151], v[216:219], v[14:17]
	v_mfma_f32_16x16x32_bf16 v[10:13], v[162:165], v[216:219], v[10:13]
	v_mfma_f32_16x16x32_bf16 v[10:13], v[166:169], v[220:223], v[10:13]
	v_mfma_f32_16x16x32_bf16 v[26:29], v[166:169], v[212:215], v[26:29]
	v_mfma_f32_16x16x32_bf16 v[26:29], v[162:165], v[208:211], v[26:29]
	v_mfma_f32_16x16x32_bf16 v[42:45], v[162:165], v[200:203], v[42:45]
	v_mfma_f32_16x16x32_bf16 v[42:45], v[166:169], v[204:207], v[42:45]
	v_mfma_f32_16x16x32_bf16 v[58:61], v[166:169], v[196:199], v[58:61]
	v_mfma_f32_16x16x32_bf16 v[58:61], v[162:165], v[188:191], v[58:61]
	v_mfma_f32_16x16x32_bf16 v[54:57], v[170:173], v[188:191], v[54:57]
	v_mfma_f32_16x16x32_bf16 v[54:57], v[174:177], v[196:199], v[54:57]
	v_mfma_f32_16x16x32_bf16 v[38:41], v[174:177], v[204:207], v[38:41]
	v_mfma_f32_16x16x32_bf16 v[38:41], v[170:173], v[200:203], v[38:41]
	v_mfma_f32_16x16x32_bf16 v[22:25], v[170:173], v[208:211], v[22:25]
	v_mfma_f32_16x16x32_bf16 v[22:25], v[174:177], v[212:215], v[22:25]
	v_mfma_f32_16x16x32_bf16 v[6:9], v[174:177], v[220:223], v[6:9]
	v_mfma_f32_16x16x32_bf16 v[6:9], v[170:173], v[216:219], v[6:9]
	v_mfma_f32_16x16x32_bf16 v[2:5], v[180:183], v[216:219], v[2:5]
	v_mfma_f32_16x16x32_bf16 v[2:5], v[184:187], v[220:223], v[2:5]
	v_mfma_f32_16x16x32_bf16 v[18:21], v[184:187], v[212:215], v[18:21]
	v_mfma_f32_16x16x32_bf16 v[18:21], v[180:183], v[208:211], v[18:21]
	v_mfma_f32_16x16x32_bf16 v[34:37], v[180:183], v[200:203], v[34:37]
	v_mfma_f32_16x16x32_bf16 v[34:37], v[184:187], v[204:207], v[34:37]
	v_mfma_f32_16x16x32_bf16 v[50:53], v[184:187], v[196:199], v[50:53]
	v_mfma_f32_16x16x32_bf16 v[50:53], v[180:183], v[188:191], v[50:53]
	s_barrier
; #define PG8_STAGE(bufoff, gbase, voff) do { _Pragma("unroll") for (int _i = 0; _i < 2; ++_i) \
;         __builtin_amdgcn_global_load_lds((const unsigned*)((const char*)(gbase) + (voff)[_i]), (PG8_LAS unsigned*)(lds + (bufoff) + ldsw + _i * 8192), 16, 0, 0); } while (0)
; #define PG8_LDA(dst, b, h) do { _Pragma("unroll") for (int m = 0; m < 4; ++m) _Pragma("unroll") for (int k = 0; k < 2; ++k) dst[m][k] = *(const PG8_LAS bf16x8*)(lds + PG8_SA(b, h) + aoff + m * 2048 + k * 1024); } while (0)
; #define PG8_LDB(dst, b, h) do { _Pragma("unroll") for (int n = 0; n < 2; ++n) _Pragma("unroll") for (int k = 0; k < 2; ++k) dst[n][k] = *(const PG8_LAS bf16x8*)(lds + PG8_SB(b, h) + boff + n * 2048 + k * 1024); } while (0)
; #define PG8_MMA(ai, bj, At, Bt) do { __builtin_amdgcn_s_setprio(1); _Pragma("unroll") for (int m = 0; m < 4; ++m) _Pragma("unroll") for (int n = 0; n < 2; ++n) _Pragma("unroll") for (int k = 0; k < 2; ++k) \
;         acc[ai][bj][m][n] = __builtin_amdgcn_mfma_f32_16x16x32_bf16(Bt[n][k], At[m][k], acc[ai][bj][m][n], 0, 0, 0); __builtin_amdgcn_s_setprio(0); } while (0)
; #define PG8_WAIT_V(n) asm volatile("s_waitcnt vmcnt(" #n ")" ::: "memory")
; #define PG8_WAIT_L(n) asm volatile("s_waitcnt lgkmcnt(" #n ")" ::: "memory")
; #define PG8_BAR __builtin_amdgcn_s_barrier()
; #define PG8_SCHED __builtin_amdgcn_sched_barrier(0)
; template <class Epi, class Sched, bool ALIGN_EPI = false, bool SP2 = false>
; __device__ __forceinline__ void gemm_phase(PG8_LAS unsigned char* lds, const Gemm g, const Sched& S, const Epi& E) {
;     ...
;             PG8_LDB(B0, 1, 0); PG8_LDB(B1, 1, 1); PG8_SCHED; PG8_LDA(At, 1, 0); PG8_STAGE(PG8_SA(0, 1), a2 + hstep, voffA);
;             PG8_WAIT_V(8); PG8_WAIT_L(0); PG8_BAR; PG8_MMA(0, 0, At, B0); PG8_MMA(0, 1, At, B1); PG8_BAR; PG8_SCHED;
;             PG8_LDA(At, 1, 1); PG8_STAGE(PG8_SB(1, 0), b3, voffB); PG8_STAGE(PG8_SB(1, 1), b3 + hstep, voffB); PG8_STAGE(PG8_SA(1, 0), a3, voffA);
;             PG8_WAIT_V(8); PG8_WAIT_L(0); PG8_BAR; PG8_MMA(1, 0, At, B0); PG8_MMA(1, 1, At, B1); PG8_BAR; PG8_SCHED;
	s_add_i32 s77, 0, 0x18000
	v_add_u32_e32 v138, s77, v153
	s_add_i32 s78, 0, 0x1c000
	ds_read_b128 v[148:151], v138
	ds_read_b128 v[158:161], v138 offset:1024
	ds_read_b128 v[162:165], v138 offset:2048
	ds_read_b128 v[166:169], v138 offset:3072
	v_add_u32_e32 v138, s78, v153
	ds_read_b128 v[170:173], v138
	ds_read_b128 v[174:177], v138 offset:1024
	ds_read_b128 v[180:183], v138 offset:2048
	ds_read_b128 v[184:187], v138 offset:3072
	s_mov_b32 m0, s26
	s_nop 0
	global_load_lds_dwordx4 v130, s[50:51]
	s_mov_b32 m0, s27
	s_nop 0
	global_load_lds_dwordx4 v134, s[50:51]
	s_add_u32 s50, s50, 0x4000
	s_addc_u32 s51, s51, 0
	s_mov_b32 m0, s28
	ds_read_b128 v[188:191], v156 offset:32768
	ds_read_b128 v[196:199], v156 offset:33792
	ds_read_b128 v[200:203], v156 offset:34816
	ds_read_b128 v[204:207], v156 offset:35840
	ds_read_b128 v[208:211], v156 offset:36864
	ds_read_b128 v[212:215], v156 offset:37888
	ds_read_b128 v[216:219], v156 offset:38912
	ds_read_b128 v[220:223], v156 offset:39936
	global_load_lds_dwordx4 v130, s[50:51]
	s_mov_b32 m0, s29
	s_nop 0
	global_load_lds_dwordx4 v134, s[50:51]
	s_waitcnt vmcnt(8)
	s_waitcnt lgkmcnt(0)
	s_barrier
	s_waitcnt lgkmcnt(0)
	v_mfma_f32_16x16x32_bf16 v[126:129], v[148:151], v[188:191], v[126:129]
	v_mfma_f32_16x16x32_bf16 v[126:129], v[158:161], v[196:199], v[126:129]
	v_mfma_f32_16x16x32_bf16 v[110:113], v[158:161], v[204:207], v[110:113]
	v_mfma_f32_16x16x32_bf16 v[110:113], v[148:151], v[200:203], v[110:113]
	v_mfma_f32_16x16x32_bf16 v[94:97], v[148:151], v[208:211], v[94:97]
	v_mfma_f32_16x16x32_bf16 v[94:97], v[158:161], v[212:215], v[94:97]
	v_mfma_f32_16x16x32_bf16 v[78:81], v[158:161], v[220:223], v[78:81]
	v_mfma_f32_16x16x32_bf16 v[78:81], v[148:151], v[216:219], v[78:81]
	v_mfma_f32_16x16x32_bf16 v[74:77], v[162:165], v[216:219], v[74:77]
	v_mfma_f32_16x16x32_bf16 v[74:77], v[166:169], v[220:223], v[74:77]
	v_mfma_f32_16x16x32_bf16 v[90:93], v[166:169], v[212:215], v[90:93]
	v_mfma_f32_16x16x32_bf16 v[90:93], v[162:165], v[208:211], v[90:93]
	v_mfma_f32_16x16x32_bf16 v[106:109], v[162:165], v[200:203], v[106:109]
	v_mfma_f32_16x16x32_bf16 v[106:109], v[166:169], v[204:207], v[106:109]
	v_mfma_f32_16x16x32_bf16 v[122:125], v[166:169], v[196:199], v[122:125]
	v_mfma_f32_16x16x32_bf16 v[122:125], v[162:165], v[188:191], v[122:125]
	v_mfma_f32_16x16x32_bf16 v[118:121], v[170:173], v[188:191], v[118:121]
	v_mfma_f32_16x16x32_bf16 v[118:121], v[174:177], v[196:199], v[118:121]
	v_mfma_f32_16x16x32_bf16 v[102:105], v[174:177], v[204:207], v[102:105]
	v_mfma_f32_16x16x32_bf16 v[102:105], v[170:173], v[200:203], v[102:105]
	v_mfma_f32_16x16x32_bf16 v[86:89], v[170:173], v[208:211], v[86:89]
	v_mfma_f32_16x16x32_bf16 v[86:89], v[174:177], v[212:215], v[86:89]
	v_mfma_f32_16x16x32_bf16 v[70:73], v[174:177], v[220:223], v[70:73]
	v_mfma_f32_16x16x32_bf16 v[70:73], v[170:173], v[216:219], v[70:73]
	v_mfma_f32_16x16x32_bf16 v[66:69], v[180:183], v[216:219], v[66:69]
	v_mfma_f32_16x16x32_bf16 v[66:69], v[184:187], v[220:223], v[66:69]
	v_mfma_f32_16x16x32_bf16 v[82:85], v[184:187], v[212:215], v[82:85]
	v_mfma_f32_16x16x32_bf16 v[82:85], v[180:183], v[208:211], v[82:85]
	v_mfma_f32_16x16x32_bf16 v[98:101], v[180:183], v[200:203], v[98:101]
	v_mfma_f32_16x16x32_bf16 v[98:101], v[184:187], v[204:207], v[98:101]
	v_mfma_f32_16x16x32_bf16 v[114:117], v[184:187], v[196:199], v[114:117]
	v_mfma_f32_16x16x32_bf16 v[114:117], v[180:183], v[188:191], v[114:117]
	s_barrier
	s_add_u32 s50, s48, 0x8000
	s_addc_u32 s51, s49, 0
	s_add_i32 s77, s77, s3
	s_mov_b32 m0, s77
	ds_read_b128 v[188:191], v156 offset:49152
	ds_read_b128 v[196:199], v156 offset:50176
	ds_read_b128 v[200:203], v156 offset:51200
	ds_read_b128 v[204:207], v156 offset:52224
	ds_read_b128 v[208:211], v156 offset:53248
	ds_read_b128 v[212:215], v156 offset:54272
	ds_read_b128 v[216:219], v156 offset:55296
	ds_read_b128 v[220:223], v156 offset:56320
	global_load_lds_dwordx4 v132, s[50:51]
	s_add_i32 m0, s77, 0x2000
	s_add_u32 s48, s48, 0xc000
	v_lshl_add_u64 v[224:225], s[50:51], 0, v[136:137]
	s_addc_u32 s49, s49, 0
	s_add_i32 s50, s78, s3
	global_load_lds_dwordx4 v[224:225], off
	s_mov_b32 m0, s50
	s_nop 0
	global_load_lds_dwordx4 v132, s[48:49]
	s_add_i32 m0, s50, 0x2000
	s_nop 0
	global_load_lds_dwordx4 v136, s[48:49]
	s_waitcnt vmcnt(6)
	s_waitcnt lgkmcnt(0)
	s_barrier
	s_waitcnt lgkmcnt(0)
	v_mfma_f32_16x16x32_bf16 v[62:65], v[148:151], v[188:191], v[62:65]
	v_mfma_f32_16x16x32_bf16 v[62:65], v[158:161], v[196:199], v[62:65]
	v_mfma_f32_16x16x32_bf16 v[46:49], v[158:161], v[204:207], v[46:49]
	v_mfma_f32_16x16x32_bf16 v[46:49], v[148:151], v[200:203], v[46:49]
	v_mfma_f32_16x16x32_bf16 v[30:33], v[148:151], v[208:211], v[30:33]
	v_mfma_f32_16x16x32_bf16 v[30:33], v[158:161], v[212:215], v[30:33]
	v_mfma_f32_16x16x32_bf16 v[14:17], v[158:161], v[220:223], v[14:17]
	v_mfma_f32_16x16x32_bf16 v[14:17], v[148:151], v[216:219], v[14:17]
	v_mfma_f32_16x16x32_bf16 v[10:13], v[162:165], v[216:219], v[10:13]
	v_mfma_f32_16x16x32_bf16 v[10:13], v[166:169], v[220:223], v[10:13]
	v_mfma_f32_16x16x32_bf16 v[26:29], v[166:169], v[212:215], v[26:29]
	v_mfma_f32_16x16x32_bf16 v[26:29], v[162:165], v[208:211], v[26:29]
	v_mfma_f32_16x16x32_bf16 v[42:45], v[162:165], v[200:203], v[42:45]
	v_mfma_f32_16x16x32_bf16 v[42:45], v[166:169], v[204:207], v[42:45]
	v_mfma_f32_16x16x32_bf16 v[58:61], v[166:169], v[196:199], v[58:61]
	v_mfma_f32_16x16x32_bf16 v[58:61], v[162:165], v[188:191], v[58:61]
	v_mfma_f32_16x16x32_bf16 v[54:57], v[170:173], v[188:191], v[54:57]
	v_mfma_f32_16x16x32_bf16 v[54:57], v[174:177], v[196:199], v[54:57]
	v_mfma_f32_16x16x32_bf16 v[38:41], v[174:177], v[204:207], v[38:41]
	v_mfma_f32_16x16x32_bf16 v[38:41], v[170:173], v[200:203], v[38:41]
	v_mfma_f32_16x16x32_bf16 v[22:25], v[170:173], v[208:211], v[22:25]
	v_mfma_f32_16x16x32_bf16 v[22:25], v[174:177], v[212:215], v[22:25]
	v_mfma_f32_16x16x32_bf16 v[6:9], v[174:177], v[220:223], v[6:9]
	v_mfma_f32_16x16x32_bf16 v[6:9], v[170:173], v[216:219], v[6:9]
	v_mfma_f32_16x16x32_bf16 v[2:5], v[180:183], v[216:219], v[2:5]
	v_mfma_f32_16x16x32_bf16 v[2:5], v[184:187], v[220:223], v[2:5]
	v_mfma_f32_16x16x32_bf16 v[18:21], v[184:187], v[212:215], v[18:21]
	v_mfma_f32_16x16x32_bf16 v[18:21], v[180:183], v[208:211], v[18:21]
	v_mfma_f32_16x16x32_bf16 v[34:37], v[180:183], v[200:203], v[34:37]
	v_mfma_f32_16x16x32_bf16 v[34:37], v[184:187], v[204:207], v[34:37]
	v_mfma_f32_16x16x32_bf16 v[50:53], v[184:187], v[196:199], v[50:53]
	v_mfma_f32_16x16x32_bf16 v[50:53], v[180:183], v[188:191], v[50:53]
	s_barrier
	s_add_i32 s76, s76, 2
	s_add_u32 s44, s44, 0x10000
	s_addc_u32 s45, s45, 0
	s_add_u32 s74, s74, 0x10000
	s_addc_u32 s75, s75, 0
	s_cmpk_gt_u32 s76, 0xa9
	s_cbranch_scc0 .LBB0_200
	s_and_b64 vcc, exec, s[18:19]
	s_cbranch_vccz .LBB0_203
	s_barrier

; #define PG8_STAGE(bufoff, gbase, voff) do { _Pragma("unroll") for (int _i = 0; _i < 2; ++_i) \
;         __builtin_amdgcn_global_load_lds((const unsigned*)((const char*)(gbase) + (voff)[_i]), (PG8_LAS unsigned*)(lds + (bufoff) + ldsw + _i * 8192), 16, 0, 0); } while (0)
; #define PG8_LDA(dst, b, h) do { _Pragma("unroll") for (int m = 0; m < 4; ++m) _Pragma("unroll") for (int k = 0; k < 2; ++k) dst[m][k] = *(const PG8_LAS bf16x8*)(lds + PG8_SA(b, h) + aoff + m * 2048 + k * 1024); } while (0)
; #define PG8_LDB(dst, b, h) do { _Pragma("unroll") for (int n = 0; n < 2; ++n) _Pragma("unroll") for (int k = 0; k < 2; ++k) dst[n][k] = *(const PG8_LAS bf16x8*)(lds + PG8_SB(b, h) + boff + n * 2048 + k * 1024); } while (0)
; #define PG8_MMA(ai, bj, At, Bt) do { __builtin_amdgcn_s_setprio(1); _Pragma("unroll") for (int m = 0; m < 4; ++m) _Pragma("unroll") for (int n = 0; n < 2; ++n) _Pragma("unroll") for (int k = 0; k < 2; ++k) \
;         acc[ai][bj][m][n] = __builtin_amdgcn_mfma_f32_16x16x32_bf16(Bt[n][k], At[m][k], acc[ai][bj][m][n], 0, 0, 0); __builtin_amdgcn_s_setprio(0); } while (0)
; #define PG8_WAIT_V(n) asm volatile("s_waitcnt vmcnt(" #n ")" ::: "memory")
; #define PG8_WAIT_L(n) asm volatile("s_waitcnt lgkmcnt(" #n ")" ::: "memory")
; #define PG8_BAR __builtin_amdgcn_s_barrier()
; template <class Epi, class Sched, bool ALIGN_EPI = false, bool SP2 = false>
; __device__ __forceinline__ void gemm_phase(PG8_LAS unsigned char* lds, const Gemm g, const Sched& S, const Epi& E) {
;     ...
;             const char* a1 = cA + (size_t)(t + 1) * kstep;
;             const char* a2 = last ? nA : cA + (size_t)(t + 2) * kstep; const char* b2 = last ? nB : cB + (size_t)(t + 2) * kstep;
;             const char* a3 = a2 + kstep; const char* b3 = b2 + kstep;
;             if (last && has_next) S.a_ready(nxt);
;             if constexpr (SP2) {
;             PG8_LDB(B0, 0, 0); PG8_LDB(B1, 0, 1); PG8_SCHED; PG8_LDA(At, 0, 0); PG8_STAGE(PG8_SA(1, 1), a1 + hstep, voffA);
;             PG8_WAIT_V(8); PG8_WAIT_L(0); PG8_BAR; PG8_MMA(0, 0, At, B0); PG8_MMA(0, 1, At, B1); PG8_BAR; PG8_SCHED;
;             PG8_LDA(At, 0, 1); PG8_STAGE(PG8_SB(0, 0), b2, voffB); PG8_STAGE(PG8_SB(0, 1), b2 + hstep, voffB); PG8_STAGE(PG8_SA(0, 0), a2, voffA);
;             PG8_WAIT_V(8); PG8_WAIT_L(0); PG8_BAR; PG8_MMA(1, 0, At, B0); PG8_MMA(1, 1, At, B1); PG8_BAR; PG8_SCHED;
.LBB0_290:
	ds_read_b128 v[146:149], v162
	ds_read_b128 v[150:153], v162 offset:1024
	ds_read_b128 v[154:157], v162 offset:2048
	ds_read_b128 v[168:171], v162 offset:3072
	ds_read_b128 v[172:175], v163
	ds_read_b128 v[180:183], v163 offset:1024
	ds_read_b128 v[184:187], v163 offset:2048
	ds_read_b128 v[188:191], v163 offset:3072
	s_add_u32 s59, s72, 0x4000
	s_addc_u32 s62, s73, 0
	s_cmp_eq_u32 s58, 60
	s_cselect_b32 s78, s19, s59
	s_cselect_b32 s79, s5, s62
	s_cselect_b32 s76, s26, s33
	s_cselect_b32 s77, s17, s56
	s_add_u32 s74, s78, 0x8000
	s_addc_u32 s75, s79, 0
	s_sub_u32 s74, s72, 0x4000
	s_subb_u32 s75, s73, 0
	s_mov_b32 m0, s51
	s_nop 0
	global_load_lds_dwordx4 v130, s[74:75]
	s_mov_b32 m0, s57
	s_nop 0
	global_load_lds_dwordx4 v134, s[74:75]
	s_add_i32 m0, s15, 0xc000
	ds_read_b128 v[198:201], v164
	ds_read_b128 v[202:205], v164 offset:1024
	ds_read_b128 v[206:209], v164 offset:2048
	ds_read_b128 v[210:213], v164 offset:3072
	ds_read_b128 v[214:217], v164 offset:4096
	ds_read_b128 v[218:221], v164 offset:5120
	ds_read_b128 v[222:225], v164 offset:6144
	ds_read_b128 v[226:229], v164 offset:7168
	global_load_lds_dwordx4 v138, s[72:73]
	s_add_i32 m0, s15, 0xe000
	s_nop 0
	global_load_lds_dwordx4 v140, s[72:73]
	s_waitcnt vmcnt(8)
	s_waitcnt lgkmcnt(0)
	s_barrier
	s_waitcnt lgkmcnt(0)
	v_mfma_f32_16x16x32_bf16 v[126:129], v[146:149], v[198:201], v[126:129]
	v_mfma_f32_16x16x32_bf16 v[126:129], v[150:153], v[202:205], v[126:129]
	v_mfma_f32_16x16x32_bf16 v[110:113], v[150:153], v[210:213], v[110:113]
	v_mfma_f32_16x16x32_bf16 v[110:113], v[146:149], v[206:209], v[110:113]
	v_mfma_f32_16x16x32_bf16 v[94:97], v[146:149], v[214:217], v[94:97]
	v_mfma_f32_16x16x32_bf16 v[94:97], v[150:153], v[218:221], v[94:97]
	v_mfma_f32_16x16x32_bf16 v[78:81], v[150:153], v[226:229], v[78:81]
	v_mfma_f32_16x16x32_bf16 v[78:81], v[146:149], v[222:225], v[78:81]
	v_mfma_f32_16x16x32_bf16 v[74:77], v[154:157], v[222:225], v[74:77]
	v_mfma_f32_16x16x32_bf16 v[74:77], v[168:171], v[226:229], v[74:77]
	v_mfma_f32_16x16x32_bf16 v[90:93], v[168:171], v[218:221], v[90:93]
	v_mfma_f32_16x16x32_bf16 v[90:93], v[154:157], v[214:217], v[90:93]
	v_mfma_f32_16x16x32_bf16 v[106:109], v[154:157], v[206:209], v[106:109]
	v_mfma_f32_16x16x32_bf16 v[106:109], v[168:171], v[210:213], v[106:109]
	v_mfma_f32_16x16x32_bf16 v[122:125], v[168:171], v[202:205], v[122:125]
	v_mfma_f32_16x16x32_bf16 v[122:125], v[154:157], v[198:201], v[122:125]
	v_mfma_f32_16x16x32_bf16 v[118:121], v[172:175], v[198:201], v[118:121]
	v_mfma_f32_16x16x32_bf16 v[118:121], v[180:183], v[202:205], v[118:121]
	v_mfma_f32_16x16x32_bf16 v[102:105], v[180:183], v[210:213], v[102:105]
	v_mfma_f32_16x16x32_bf16 v[102:105], v[172:175], v[206:209], v[102:105]
	v_mfma_f32_16x16x32_bf16 v[86:89], v[172:175], v[214:217], v[86:89]
	v_mfma_f32_16x16x32_bf16 v[86:89], v[180:183], v[218:221], v[86:89]
	v_mfma_f32_16x16x32_bf16 v[70:73], v[180:183], v[226:229], v[70:73]
	v_mfma_f32_16x16x32_bf16 v[70:73], v[172:175], v[222:225], v[70:73]
	v_mfma_f32_16x16x32_bf16 v[66:69], v[184:187], v[222:225], v[66:69]
	v_mfma_f32_16x16x32_bf16 v[66:69], v[188:191], v[226:229], v[66:69]
	v_mfma_f32_16x16x32_bf16 v[82:85], v[188:191], v[218:221], v[82:85]
	v_mfma_f32_16x16x32_bf16 v[82:85], v[184:187], v[214:217], v[82:85]
	v_mfma_f32_16x16x32_bf16 v[98:101], v[184:187], v[206:209], v[98:101]
	v_mfma_f32_16x16x32_bf16 v[98:101], v[188:191], v[210:213], v[98:101]
	v_mfma_f32_16x16x32_bf16 v[114:117], v[188:191], v[202:205], v[114:117]
	v_mfma_f32_16x16x32_bf16 v[114:117], v[184:187], v[198:201], v[114:117]
	s_barrier
	s_add_i32 s59, s81, s3
	s_mov_b32 m0, s59
	ds_read_b128 v[198:201], v164 offset:16384
	ds_read_b128 v[202:205], v164 offset:17408
	ds_read_b128 v[206:209], v164 offset:18432
	ds_read_b128 v[210:213], v164 offset:19456
	ds_read_b128 v[214:217], v164 offset:20480
	ds_read_b128 v[218:221], v164 offset:21504
	ds_read_b128 v[222:225], v164 offset:22528
	ds_read_b128 v[226:229], v164 offset:23552
	global_load_lds_dwordx4 v132, s[76:77]
	s_add_i32 m0, s59, 0x2000
	s_add_u32 s62, s76, 0x4000
	s_addc_u32 s63, s77, 0
	s_add_i32 s59, s82, s3
	global_load_lds_dwordx4 v136, s[76:77]
	s_mov_b32 m0, s59
	s_nop 0
	global_load_lds_dwordx4 v132, s[62:63]
	s_add_i32 m0, s59, 0x2000
	s_nop 0
	global_load_lds_dwordx4 v136, s[62:63]
	s_waitcnt vmcnt(6)
	s_waitcnt lgkmcnt(0)
	s_barrier
	s_waitcnt lgkmcnt(0)
	v_mfma_f32_16x16x32_bf16 v[62:65], v[146:149], v[198:201], v[62:65]
	v_mfma_f32_16x16x32_bf16 v[62:65], v[150:153], v[202:205], v[62:65]
	v_mfma_f32_16x16x32_bf16 v[46:49], v[150:153], v[210:213], v[46:49]
	v_mfma_f32_16x16x32_bf16 v[46:49], v[146:149], v[206:209], v[46:49]
	v_mfma_f32_16x16x32_bf16 v[30:33], v[146:149], v[214:217], v[30:33]
	v_mfma_f32_16x16x32_bf16 v[30:33], v[150:153], v[218:221], v[30:33]
	v_mfma_f32_16x16x32_bf16 v[14:17], v[150:153], v[226:229], v[14:17]
	v_mfma_f32_16x16x32_bf16 v[14:17], v[146:149], v[222:225], v[14:17]
	v_mfma_f32_16x16x32_bf16 v[10:13], v[154:157], v[222:225], v[10:13]
	v_mfma_f32_16x16x32_bf16 v[10:13], v[168:171], v[226:229], v[10:13]
	v_mfma_f32_16x16x32_bf16 v[26:29], v[168:171], v[218:221], v[26:29]
	v_mfma_f32_16x16x32_bf16 v[26:29], v[154:157], v[214:217], v[26:29]
	v_mfma_f32_16x16x32_bf16 v[42:45], v[154:157], v[206:209], v[42:45]
	v_mfma_f32_16x16x32_bf16 v[42:45], v[168:171], v[210:213], v[42:45]
	v_mfma_f32_16x16x32_bf16 v[58:61], v[168:171], v[202:205], v[58:61]
	v_mfma_f32_16x16x32_bf16 v[58:61], v[154:157], v[198:201], v[58:61]
	v_mfma_f32_16x16x32_bf16 v[54:57], v[172:175], v[198:201], v[54:57]
	v_mfma_f32_16x16x32_bf16 v[54:57], v[180:183], v[202:205], v[54:57]
	v_mfma_f32_16x16x32_bf16 v[38:41], v[180:183], v[210:213], v[38:41]
	v_mfma_f32_16x16x32_bf16 v[38:41], v[172:175], v[206:209], v[38:41]
	v_mfma_f32_16x16x32_bf16 v[22:25], v[172:175], v[214:217], v[22:25]
	v_mfma_f32_16x16x32_bf16 v[22:25], v[180:183], v[218:221], v[22:25]
	v_mfma_f32_16x16x32_bf16 v[6:9], v[180:183], v[226:229], v[6:9]
	v_mfma_f32_16x16x32_bf16 v[6:9], v[172:175], v[222:225], v[6:9]
	v_mfma_f32_16x16x32_bf16 v[2:5], v[184:187], v[222:225], v[2:5]
	v_mfma_f32_16x16x32_bf16 v[2:5], v[188:191], v[226:229], v[2:5]
	v_mfma_f32_16x16x32_bf16 v[18:21], v[188:191], v[218:221], v[18:21]
	v_mfma_f32_16x16x32_bf16 v[18:21], v[184:187], v[214:217], v[18:21]
	v_mfma_f32_16x16x32_bf16 v[34:37], v[184:187], v[206:209], v[34:37]
	v_mfma_f32_16x16x32_bf16 v[34:37], v[188:191], v[210:213], v[34:37]
	v_mfma_f32_16x16x32_bf16 v[50:53], v[188:191], v[202:205], v[50:53]
	v_mfma_f32_16x16x32_bf16 v[50:53], v[184:187], v[198:201], v[50:53]
	s_barrier
; #define PG8_STAGE(bufoff, gbase, voff) do { _Pragma("unroll") for (int _i = 0; _i < 2; ++_i) \
;         __builtin_amdgcn_global_load_lds((const unsigned*)((const char*)(gbase) + (voff)[_i]), (PG8_LAS unsigned*)(lds + (bufoff) + ldsw + _i * 8192), 16, 0, 0); } while (0)
; #define PG8_LDA(dst, b, h) do { _Pragma("unroll") for (int m = 0; m < 4; ++m) _Pragma("unroll") for (int k = 0; k < 2; ++k) dst[m][k] = *(const PG8_LAS bf16x8*)(lds + PG8_SA(b, h) + aoff + m * 2048 + k * 1024); } while (0)
; #define PG8_LDB(dst, b, h) do { _Pragma("unroll") for (int n = 0; n < 2; ++n) _Pragma("unroll") for (int k = 0; k < 2; ++k) dst[n][k] = *(const PG8_LAS bf16x8*)(lds + PG8_SB(b, h) + boff + n * 2048 + k * 1024); } while (0)
; #define PG8_MMA(ai, bj, At, Bt) do { __builtin_amdgcn_s_setprio(1); _Pragma("unroll") for (int m = 0; m < 4; ++m) _Pragma("unroll") for (int n = 0; n < 2; ++n) _Pragma("unroll") for (int k = 0; k < 2; ++k) \
;         acc[ai][bj][m][n] = __builtin_amdgcn_mfma_f32_16x16x32_bf16(Bt[n][k], At[m][k], acc[ai][bj][m][n], 0, 0, 0); __builtin_amdgcn_s_setprio(0); } while (0)
; #define PG8_WAIT_V(n) asm volatile("s_waitcnt vmcnt(" #n ")" ::: "memory")
; #define PG8_WAIT_L(n) asm volatile("s_waitcnt lgkmcnt(" #n ")" ::: "memory")
; #define PG8_BAR __builtin_amdgcn_s_barrier()
; #define PG8_SCHED __builtin_amdgcn_sched_barrier(0)
; template <class Epi, class Sched, bool ALIGN_EPI = false, bool SP2 = false>
; __device__ __forceinline__ void gemm_phase(PG8_LAS unsigned char* lds, const Gemm g, const Sched& S, const Epi& E) {
;     ...
;             PG8_LDB(B0, 1, 0); PG8_LDB(B1, 1, 1); PG8_SCHED; PG8_LDA(At, 1, 0); PG8_STAGE(PG8_SA(0, 1), a2 + hstep, voffA);
;             PG8_WAIT_V(8); PG8_WAIT_L(0); PG8_BAR; PG8_MMA(0, 0, At, B0); PG8_MMA(0, 1, At, B1); PG8_BAR; PG8_SCHED;
;             PG8_LDA(At, 1, 1); PG8_STAGE(PG8_SB(1, 0), b3, voffB); PG8_STAGE(PG8_SB(1, 1), b3 + hstep, voffB); PG8_STAGE(PG8_SA(1, 0), a3, voffA);
;             PG8_WAIT_V(8); PG8_WAIT_L(0); PG8_BAR; PG8_MMA(1, 0, At, B0); PG8_MMA(1, 1, At, B1); PG8_BAR; PG8_SCHED;
	s_add_i32 s59, 0, 0x18000
	v_add_u32_e32 v158, s59, v160
	s_add_i32 s64, 0, 0x1c000
	ds_read_b128 v[146:149], v158
	ds_read_b128 v[150:153], v158 offset:1024
	ds_read_b128 v[154:157], v158 offset:2048
	ds_read_b128 v[168:171], v158 offset:3072
	v_add_u32_e32 v158, s64, v160
	ds_read_b128 v[172:175], v158
	ds_read_b128 v[180:183], v158 offset:1024
	ds_read_b128 v[184:187], v158 offset:2048
	ds_read_b128 v[188:191], v158 offset:3072
	s_mov_b32 m0, s15
	s_nop 0
	global_load_lds_dwordx4 v130, s[78:79]
	s_mov_b32 m0, s27
	s_nop 0
	global_load_lds_dwordx4 v134, s[78:79]
	s_add_u32 s62, s78, 0x4000
	s_addc_u32 s63, s79, 0
	s_mov_b32 m0, s28
	ds_read_b128 v[198:201], v164 offset:32768
	ds_read_b128 v[202:205], v164 offset:33792
	ds_read_b128 v[206:209], v164 offset:34816
	ds_read_b128 v[210:213], v164 offset:35840
	ds_read_b128 v[214:217], v164 offset:36864
	ds_read_b128 v[218:221], v164 offset:37888
	ds_read_b128 v[222:225], v164 offset:38912
	ds_read_b128 v[226:229], v164 offset:39936
	global_load_lds_dwordx4 v130, s[62:63]
	s_mov_b32 m0, s29
	s_nop 0
	global_load_lds_dwordx4 v134, s[62:63]
	s_waitcnt vmcnt(8)
	s_waitcnt lgkmcnt(0)
	s_barrier
	s_waitcnt lgkmcnt(0)
	v_mfma_f32_16x16x32_bf16 v[126:129], v[146:149], v[198:201], v[126:129]
	v_mfma_f32_16x16x32_bf16 v[126:129], v[150:153], v[202:205], v[126:129]
	v_mfma_f32_16x16x32_bf16 v[110:113], v[150:153], v[210:213], v[110:113]
	v_mfma_f32_16x16x32_bf16 v[110:113], v[146:149], v[206:209], v[110:113]
	v_mfma_f32_16x16x32_bf16 v[94:97], v[146:149], v[214:217], v[94:97]
	v_mfma_f32_16x16x32_bf16 v[94:97], v[150:153], v[218:221], v[94:97]
	v_mfma_f32_16x16x32_bf16 v[78:81], v[150:153], v[226:229], v[78:81]
	v_mfma_f32_16x16x32_bf16 v[78:81], v[146:149], v[222:225], v[78:81]
	v_mfma_f32_16x16x32_bf16 v[74:77], v[154:157], v[222:225], v[74:77]
	v_mfma_f32_16x16x32_bf16 v[74:77], v[168:171], v[226:229], v[74:77]
	v_mfma_f32_16x16x32_bf16 v[90:93], v[168:171], v[218:221], v[90:93]
	v_mfma_f32_16x16x32_bf16 v[90:93], v[154:157], v[214:217], v[90:93]
	v_mfma_f32_16x16x32_bf16 v[106:109], v[154:157], v[206:209], v[106:109]
	v_mfma_f32_16x16x32_bf16 v[106:109], v[168:171], v[210:213], v[106:109]
	v_mfma_f32_16x16x32_bf16 v[122:125], v[168:171], v[202:205], v[122:125]
	v_mfma_f32_16x16x32_bf16 v[122:125], v[154:157], v[198:201], v[122:125]
	v_mfma_f32_16x16x32_bf16 v[118:121], v[172:175], v[198:201], v[118:121]
	v_mfma_f32_16x16x32_bf16 v[118:121], v[180:183], v[202:205], v[118:121]
	v_mfma_f32_16x16x32_bf16 v[102:105], v[180:183], v[210:213], v[102:105]
	v_mfma_f32_16x16x32_bf16 v[102:105], v[172:175], v[206:209], v[102:105]
	v_mfma_f32_16x16x32_bf16 v[86:89], v[172:175], v[214:217], v[86:89]
	v_mfma_f32_16x16x32_bf16 v[86:89], v[180:183], v[218:221], v[86:89]
	v_mfma_f32_16x16x32_bf16 v[70:73], v[180:183], v[226:229], v[70:73]
	v_mfma_f32_16x16x32_bf16 v[70:73], v[172:175], v[222:225], v[70:73]
	v_mfma_f32_16x16x32_bf16 v[66:69], v[184:187], v[222:225], v[66:69]
	v_mfma_f32_16x16x32_bf16 v[66:69], v[188:191], v[226:229], v[66:69]
	v_mfma_f32_16x16x32_bf16 v[82:85], v[188:191], v[218:221], v[82:85]
	v_mfma_f32_16x16x32_bf16 v[82:85], v[184:187], v[214:217], v[82:85]
	v_mfma_f32_16x16x32_bf16 v[98:101], v[184:187], v[206:209], v[98:101]
	v_mfma_f32_16x16x32_bf16 v[98:101], v[188:191], v[210:213], v[98:101]
	v_mfma_f32_16x16x32_bf16 v[114:117], v[188:191], v[202:205], v[114:117]
	v_mfma_f32_16x16x32_bf16 v[114:117], v[184:187], v[198:201], v[114:117]
	s_barrier
	s_add_u32 s62, s76, 0x8000
	s_addc_u32 s63, s77, 0
	s_add_i32 s59, s59, s3
	s_mov_b32 m0, s59
	ds_read_b128 v[198:201], v164 offset:49152
	ds_read_b128 v[202:205], v164 offset:50176
	ds_read_b128 v[206:209], v164 offset:51200
	ds_read_b128 v[210:213], v164 offset:52224
	ds_read_b128 v[214:217], v164 offset:53248
	ds_read_b128 v[218:221], v164 offset:54272
	ds_read_b128 v[222:225], v164 offset:55296
	ds_read_b128 v[226:229], v164 offset:56320
	global_load_lds_dwordx4 v132, s[62:63]
	s_add_i32 m0, s59, 0x2000
	v_lshl_add_u64 v[158:159], s[62:63], 0, v[136:137]
	s_add_u32 s62, s76, 0xc000
	s_addc_u32 s63, s77, 0
	s_add_i32 s59, s64, s3
	global_load_lds_dwordx4 v[158:159], off
	s_mov_b32 m0, s59
	s_nop 0
	global_load_lds_dwordx4 v132, s[62:63]
	s_add_i32 m0, s59, 0x2000
	s_nop 0
	global_load_lds_dwordx4 v136, s[62:63]
	s_waitcnt vmcnt(6)
	s_waitcnt lgkmcnt(0)
	s_barrier
	s_waitcnt lgkmcnt(0)
	v_mfma_f32_16x16x32_bf16 v[62:65], v[146:149], v[198:201], v[62:65]
	v_mfma_f32_16x16x32_bf16 v[62:65], v[150:153], v[202:205], v[62:65]
	v_mfma_f32_16x16x32_bf16 v[46:49], v[150:153], v[210:213], v[46:49]
	v_mfma_f32_16x16x32_bf16 v[46:49], v[146:149], v[206:209], v[46:49]
	v_mfma_f32_16x16x32_bf16 v[30:33], v[146:149], v[214:217], v[30:33]
	v_mfma_f32_16x16x32_bf16 v[30:33], v[150:153], v[218:221], v[30:33]
	v_mfma_f32_16x16x32_bf16 v[14:17], v[150:153], v[226:229], v[14:17]
	v_mfma_f32_16x16x32_bf16 v[14:17], v[146:149], v[222:225], v[14:17]
	v_mfma_f32_16x16x32_bf16 v[10:13], v[154:157], v[222:225], v[10:13]
	v_mfma_f32_16x16x32_bf16 v[10:13], v[168:171], v[226:229], v[10:13]
	v_mfma_f32_16x16x32_bf16 v[26:29], v[168:171], v[218:221], v[26:29]
	v_mfma_f32_16x16x32_bf16 v[26:29], v[154:157], v[214:217], v[26:29]
	v_mfma_f32_16x16x32_bf16 v[42:45], v[154:157], v[206:209], v[42:45]
	v_mfma_f32_16x16x32_bf16 v[42:45], v[168:171], v[210:213], v[42:45]
	v_mfma_f32_16x16x32_bf16 v[58:61], v[168:171], v[202:205], v[58:61]
	v_mfma_f32_16x16x32_bf16 v[58:61], v[154:157], v[198:201], v[58:61]
	v_mfma_f32_16x16x32_bf16 v[54:57], v[172:175], v[198:201], v[54:57]
	v_mfma_f32_16x16x32_bf16 v[54:57], v[180:183], v[202:205], v[54:57]
	v_mfma_f32_16x16x32_bf16 v[38:41], v[180:183], v[210:213], v[38:41]
	v_mfma_f32_16x16x32_bf16 v[38:41], v[172:175], v[206:209], v[38:41]
	v_mfma_f32_16x16x32_bf16 v[22:25], v[172:175], v[214:217], v[22:25]
	v_mfma_f32_16x16x32_bf16 v[22:25], v[180:183], v[218:221], v[22:25]
	v_mfma_f32_16x16x32_bf16 v[6:9], v[180:183], v[226:229], v[6:9]
	v_mfma_f32_16x16x32_bf16 v[6:9], v[172:175], v[222:225], v[6:9]
	v_mfma_f32_16x16x32_bf16 v[2:5], v[184:187], v[222:225], v[2:5]
	v_mfma_f32_16x16x32_bf16 v[2:5], v[188:191], v[226:229], v[2:5]
	v_mfma_f32_16x16x32_bf16 v[18:21], v[188:191], v[218:221], v[18:21]
	v_mfma_f32_16x16x32_bf16 v[18:21], v[184:187], v[214:217], v[18:21]
	v_mfma_f32_16x16x32_bf16 v[34:37], v[184:187], v[206:209], v[34:37]
	v_mfma_f32_16x16x32_bf16 v[34:37], v[188:191], v[210:213], v[34:37]
	v_mfma_f32_16x16x32_bf16 v[50:53], v[188:191], v[202:205], v[50:53]
	v_mfma_f32_16x16x32_bf16 v[50:53], v[184:187], v[198:201], v[50:53]
	s_barrier
	s_add_i32 s58, s58, 2
	s_add_u32 s72, s72, 0x10000
	s_addc_u32 s73, s73, 0
	s_add_u32 s33, s33, 0x10000
	s_addc_u32 s56, s56, 0
	s_cmp_gt_u32 s58, 61
	s_cbranch_scc0 .LBB0_290
	s_and_b64 vcc, exec, s[12:13]
	s_cbranch_vccz .LBB0_293
	s_barrier

; #define PG8_STAGE(bufoff, gbase, voff) do { _Pragma("unroll") for (int _i = 0; _i < 2; ++_i) \
;         __builtin_amdgcn_global_load_lds((const unsigned*)((const char*)(gbase) + (voff)[_i]), (PG8_LAS unsigned*)(lds + (bufoff) + ldsw + _i * 8192), 16, 0, 0); } while (0)
; #define PG8_LDA(dst, b, h) do { _Pragma("unroll") for (int m = 0; m < 4; ++m) _Pragma("unroll") for (int k = 0; k < 2; ++k) dst[m][k] = *(const PG8_LAS bf16x8*)(lds + PG8_SA(b, h) + aoff + m * 2048 + k * 1024); } while (0)
; #define PG8_LDB(dst, b, h) do { _Pragma("unroll") for (int n = 0; n < 2; ++n) _Pragma("unroll") for (int k = 0; k < 2; ++k) dst[n][k] = *(const PG8_LAS bf16x8*)(lds + PG8_SB(b, h) + boff + n * 2048 + k * 1024); } while (0)
; #define PG8_MMA(ai, bj, At, Bt) do { __builtin_amdgcn_s_setprio(1); _Pragma("unroll") for (int m = 0; m < 4; ++m) _Pragma("unroll") for (int n = 0; n < 2; ++n) _Pragma("unroll") for (int k = 0; k < 2; ++k) \
;         acc[ai][bj][m][n] = __builtin_amdgcn_mfma_f32_16x16x32_bf16(Bt[n][k], At[m][k], acc[ai][bj][m][n], 0, 0, 0); __builtin_amdgcn_s_setprio(0); } while (0)
; #define PG8_WAIT_V(n) asm volatile("s_waitcnt vmcnt(" #n ")" ::: "memory")
; #define PG8_WAIT_L(n) asm volatile("s_waitcnt lgkmcnt(" #n ")" ::: "memory")
; #define PG8_BAR __builtin_amdgcn_s_barrier()
; #define PG8_SCHED __builtin_amdgcn_sched_barrier(0)
; template <class Epi, class Sched, bool ALIGN_EPI = false, bool SP2 = false>
; __device__ __forceinline__ void gemm_phase(PG8_LAS unsigned char* lds, const Gemm g, const Sched& S, const Epi& E) {
;     ...
;             PG8_LDB(B0, 0, 0); PG8_LDB(B1, 0, 1); PG8_SCHED; PG8_LDA(At, 0, 0); PG8_STAGE(PG8_SA(1, 1), a1 + hstep, voffA);
;             PG8_WAIT_V(8); PG8_WAIT_L(0); PG8_BAR; PG8_MMA(0, 0, At, B0); PG8_MMA(0, 1, At, B1); PG8_BAR; PG8_SCHED;
;             PG8_LDA(At, 0, 1); PG8_STAGE(PG8_SB(0, 0), b2, voffB); PG8_STAGE(PG8_SB(0, 1), b2 + hstep, voffB); PG8_STAGE(PG8_SA(0, 0), a2, voffA);
;             PG8_WAIT_V(8); PG8_WAIT_L(0); PG8_BAR; PG8_MMA(1, 0, At, B0); PG8_MMA(1, 1, At, B1); PG8_BAR; PG8_SCHED;
.LBB0_682:
	ds_read_b128 v[166:169], v163
	ds_read_b128 v[170:173], v163 offset:1024
	ds_read_b128 v[174:177], v163 offset:2048
	ds_read_b128 v[180:183], v163 offset:3072
	ds_read_b128 v[184:187], v164
	ds_read_b128 v[188:191], v164 offset:1024
	ds_read_b128 v[198:201], v164 offset:2048
	ds_read_b128 v[202:205], v164 offset:3072
	v_lshl_add_u64 v[242:243], v[130:131], 0, s[44:45]
	s_add_i32 s83, s29, 0xc000
	v_lshl_add_u64 v[238:239], v[242:243], 0, s[10:11]
	s_mov_b32 m0, s83
	v_lshl_add_u64 v[244:245], v[132:133], 0, s[44:45]
	s_add_i32 s84, s29, 0xe000
	ds_read_b128 v[206:209], v165
	ds_read_b128 v[210:213], v165 offset:1024
	ds_read_b128 v[214:217], v165 offset:2048
	ds_read_b128 v[218:221], v165 offset:3072
	ds_read_b128 v[222:225], v165 offset:4096
	ds_read_b128 v[226:229], v165 offset:5120
	ds_read_b128 v[230:233], v165 offset:6144
	ds_read_b128 v[234:237], v165 offset:7168
	global_load_lds_dwordx4 v[238:239], off
	v_lshl_add_u64 v[238:239], v[244:245], 0, s[10:11]
	s_mov_b32 m0, s84
	s_nop 0
	global_load_lds_dwordx4 v[238:239], off
	s_waitcnt vmcnt(8)
	s_waitcnt lgkmcnt(0)
	s_barrier
	s_waitcnt lgkmcnt(0)
	v_mfma_f32_16x16x32_bf16 v[14:17], v[166:169], v[206:209], v[14:17]
	v_mfma_f32_16x16x32_bf16 v[14:17], v[170:173], v[210:213], v[14:17]
	v_mfma_f32_16x16x32_bf16 v[38:41], v[170:173], v[218:221], v[38:41]
	v_mfma_f32_16x16x32_bf16 v[38:41], v[166:169], v[214:217], v[38:41]
	v_mfma_f32_16x16x32_bf16 v[70:73], v[166:169], v[222:225], v[70:73]
	v_mfma_f32_16x16x32_bf16 v[70:73], v[170:173], v[226:229], v[70:73]
	v_mfma_f32_16x16x32_bf16 v[94:97], v[170:173], v[234:237], v[94:97]
	v_mfma_f32_16x16x32_bf16 v[94:97], v[166:169], v[230:233], v[94:97]
	v_mfma_f32_16x16x32_bf16 v[90:93], v[174:177], v[230:233], v[90:93]
	v_mfma_f32_16x16x32_bf16 v[90:93], v[180:183], v[234:237], v[90:93]
	v_mfma_f32_16x16x32_bf16 v[66:69], v[180:183], v[226:229], v[66:69]
	v_mfma_f32_16x16x32_bf16 v[66:69], v[174:177], v[222:225], v[66:69]
	v_mfma_f32_16x16x32_bf16 v[34:37], v[174:177], v[214:217], v[34:37]
	v_mfma_f32_16x16x32_bf16 v[34:37], v[180:183], v[218:221], v[34:37]
	v_mfma_f32_16x16x32_bf16 v[10:13], v[180:183], v[210:213], v[10:13]
	v_mfma_f32_16x16x32_bf16 v[10:13], v[174:177], v[206:209], v[10:13]
	v_mfma_f32_16x16x32_bf16 v[30:33], v[184:187], v[206:209], v[30:33]
	v_mfma_f32_16x16x32_bf16 v[30:33], v[188:191], v[210:213], v[30:33]
	v_mfma_f32_16x16x32_bf16 v[54:57], v[188:191], v[218:221], v[54:57]
	v_mfma_f32_16x16x32_bf16 v[54:57], v[184:187], v[214:217], v[54:57]
	v_mfma_f32_16x16x32_bf16 v[86:89], v[184:187], v[222:225], v[86:89]
	v_mfma_f32_16x16x32_bf16 v[86:89], v[188:191], v[226:229], v[86:89]
	v_mfma_f32_16x16x32_bf16 v[110:113], v[188:191], v[234:237], v[110:113]
	v_mfma_f32_16x16x32_bf16 v[110:113], v[184:187], v[230:233], v[110:113]
	v_mfma_f32_16x16x32_bf16 v[106:109], v[198:201], v[230:233], v[106:109]
	v_mfma_f32_16x16x32_bf16 v[106:109], v[202:205], v[234:237], v[106:109]
	v_mfma_f32_16x16x32_bf16 v[82:85], v[202:205], v[226:229], v[82:85]
	v_mfma_f32_16x16x32_bf16 v[82:85], v[198:201], v[222:225], v[82:85]
	v_mfma_f32_16x16x32_bf16 v[50:53], v[198:201], v[214:217], v[50:53]
	v_mfma_f32_16x16x32_bf16 v[50:53], v[202:205], v[218:221], v[50:53]
	v_mfma_f32_16x16x32_bf16 v[26:29], v[202:205], v[210:213], v[26:29]
	v_mfma_f32_16x16x32_bf16 v[26:29], v[198:201], v[206:209], v[26:29]
	s_barrier
	v_lshl_add_u64 v[246:247], v[156:157], 0, s[44:45]
	s_add_i32 s85, s80, s28
	v_lshl_add_u64 v[238:239], v[246:247], 0, s[14:15]
	s_mov_b32 m0, s85
	v_lshl_add_u64 v[248:249], v[158:159], 0, s[44:45]
	s_add_i32 s86, s85, 0x2000
	ds_read_b128 v[206:209], v165 offset:16384
	ds_read_b128 v[210:213], v165 offset:17408
	ds_read_b128 v[214:217], v165 offset:18432
	ds_read_b128 v[218:221], v165 offset:19456
	ds_read_b128 v[222:225], v165 offset:20480
	ds_read_b128 v[226:229], v165 offset:21504
	ds_read_b128 v[230:233], v165 offset:22528
	ds_read_b128 v[234:237], v165 offset:23552
	global_load_lds_dwordx4 v[238:239], off
	v_lshl_add_u64 v[238:239], v[248:249], 0, s[14:15]
	s_mov_b32 m0, s86
	s_add_i32 s87, s81, s28
	global_load_lds_dwordx4 v[238:239], off
	v_lshl_add_u64 v[238:239], v[246:247], 0, s[16:17]
	s_mov_b32 m0, s87
	s_add_i32 s88, s87, 0x2000
	global_load_lds_dwordx4 v[238:239], off
	v_lshl_add_u64 v[238:239], v[248:249], 0, s[16:17]
	s_mov_b32 m0, s88
	s_nop 0
	global_load_lds_dwordx4 v[238:239], off
	v_lshl_add_u64 v[238:239], v[242:243], 0, s[14:15]
	s_mov_b32 m0, s29
	s_nop 0
	global_load_lds_dwordx4 v[238:239], off
	v_lshl_add_u64 v[238:239], v[244:245], 0, s[14:15]
	s_mov_b32 m0, s30
	s_nop 0
	global_load_lds_dwordx4 v[238:239], off
	s_waitcnt vmcnt(8)
	s_waitcnt lgkmcnt(0)
	s_barrier
; #define PG8_STAGE(bufoff, gbase, voff) do { _Pragma("unroll") for (int _i = 0; _i < 2; ++_i) \
;         __builtin_amdgcn_global_load_lds((const unsigned*)((const char*)(gbase) + (voff)[_i]), (PG8_LAS unsigned*)(lds + (bufoff) + ldsw + _i * 8192), 16, 0, 0); } while (0)
; #define PG8_LDA(dst, b, h) do { _Pragma("unroll") for (int m = 0; m < 4; ++m) _Pragma("unroll") for (int k = 0; k < 2; ++k) dst[m][k] = *(const PG8_LAS bf16x8*)(lds + PG8_SA(b, h) + aoff + m * 2048 + k * 1024); } while (0)
; #define PG8_LDB(dst, b, h) do { _Pragma("unroll") for (int n = 0; n < 2; ++n) _Pragma("unroll") for (int k = 0; k < 2; ++k) dst[n][k] = *(const PG8_LAS bf16x8*)(lds + PG8_SB(b, h) + boff + n * 2048 + k * 1024); } while (0)
; #define PG8_MMA(ai, bj, At, Bt) do { __builtin_amdgcn_s_setprio(1); _Pragma("unroll") for (int m = 0; m < 4; ++m) _Pragma("unroll") for (int n = 0; n < 2; ++n) _Pragma("unroll") for (int k = 0; k < 2; ++k) \
;         acc[ai][bj][m][n] = __builtin_amdgcn_mfma_f32_16x16x32_bf16(Bt[n][k], At[m][k], acc[ai][bj][m][n], 0, 0, 0); __builtin_amdgcn_s_setprio(0); } while (0)
; #define PG8_WAIT_V(n) asm volatile("s_waitcnt vmcnt(" #n ")" ::: "memory")
; #define PG8_WAIT_L(n) asm volatile("s_waitcnt lgkmcnt(" #n ")" ::: "memory")
; #define PG8_BAR __builtin_amdgcn_s_barrier()
; #define PG8_SCHED __builtin_amdgcn_sched_barrier(0)
; template <class Epi, class Sched, bool ALIGN_EPI = false, bool SP2 = false>
; __device__ __forceinline__ void gemm_phase(PG8_LAS unsigned char* lds, const Gemm g, const Sched& S, const Epi& E) {
;     ...
;             PG8_WAIT_V(8); PG8_WAIT_L(0); PG8_BAR; PG8_MMA(1, 0, At, B0); PG8_MMA(1, 1, At, B1); PG8_BAR; PG8_SCHED;
;             PG8_LDB(B0, 1, 0); PG8_LDB(B1, 1, 1); PG8_SCHED; PG8_LDA(At, 1, 0); PG8_STAGE(PG8_SA(0, 1), a2 + hstep, voffA);
;             PG8_WAIT_V(8); PG8_WAIT_L(0); PG8_BAR; PG8_MMA(0, 0, At, B0); PG8_MMA(0, 1, At, B1); PG8_BAR; PG8_SCHED;
;             PG8_LDA(At, 1, 1); PG8_STAGE(PG8_SB(1, 0), b3, voffB); PG8_STAGE(PG8_SB(1, 1), b3 + hstep, voffB); PG8_STAGE(PG8_SA(1, 0), a3, voffA);
	s_waitcnt lgkmcnt(0)
	v_mfma_f32_16x16x32_bf16 v[126:129], v[166:169], v[206:209], v[126:129]
	v_mfma_f32_16x16x32_bf16 v[126:129], v[170:173], v[210:213], v[126:129]
	v_mfma_f32_16x16x32_bf16 v[102:105], v[170:173], v[218:221], v[102:105]
	v_mfma_f32_16x16x32_bf16 v[102:105], v[166:169], v[214:217], v[102:105]
	v_mfma_f32_16x16x32_bf16 v[62:65], v[166:169], v[222:225], v[62:65]
	v_mfma_f32_16x16x32_bf16 v[62:65], v[170:173], v[226:229], v[62:65]
	v_mfma_f32_16x16x32_bf16 v[22:25], v[170:173], v[234:237], v[22:25]
	v_mfma_f32_16x16x32_bf16 v[22:25], v[166:169], v[230:233], v[22:25]
	v_mfma_f32_16x16x32_bf16 v[18:21], v[174:177], v[230:233], v[18:21]
	v_mfma_f32_16x16x32_bf16 v[18:21], v[180:183], v[234:237], v[18:21]
	v_mfma_f32_16x16x32_bf16 v[58:61], v[180:183], v[226:229], v[58:61]
	v_mfma_f32_16x16x32_bf16 v[58:61], v[174:177], v[222:225], v[58:61]
	v_mfma_f32_16x16x32_bf16 v[98:101], v[174:177], v[214:217], v[98:101]
	v_mfma_f32_16x16x32_bf16 v[98:101], v[180:183], v[218:221], v[98:101]
	v_mfma_f32_16x16x32_bf16 v[122:125], v[180:183], v[210:213], v[122:125]
	v_mfma_f32_16x16x32_bf16 v[122:125], v[174:177], v[206:209], v[122:125]
	v_mfma_f32_16x16x32_bf16 v[118:121], v[184:187], v[206:209], v[118:121]
	v_mfma_f32_16x16x32_bf16 v[118:121], v[188:191], v[210:213], v[118:121]
	v_mfma_f32_16x16x32_bf16 v[78:81], v[188:191], v[218:221], v[78:81]
	v_mfma_f32_16x16x32_bf16 v[78:81], v[184:187], v[214:217], v[78:81]
	v_mfma_f32_16x16x32_bf16 v[46:49], v[184:187], v[222:225], v[46:49]
	v_mfma_f32_16x16x32_bf16 v[46:49], v[188:191], v[226:229], v[46:49]
	v_mfma_f32_16x16x32_bf16 v[6:9], v[188:191], v[234:237], v[6:9]
	v_mfma_f32_16x16x32_bf16 v[6:9], v[184:187], v[230:233], v[6:9]
	v_mfma_f32_16x16x32_bf16 v[2:5], v[198:201], v[230:233], v[2:5]
	v_mfma_f32_16x16x32_bf16 v[2:5], v[202:205], v[234:237], v[2:5]
	v_mfma_f32_16x16x32_bf16 v[42:45], v[202:205], v[226:229], v[42:45]
	v_mfma_f32_16x16x32_bf16 v[42:45], v[198:201], v[222:225], v[42:45]
	v_mfma_f32_16x16x32_bf16 v[74:77], v[198:201], v[214:217], v[74:77]
	v_mfma_f32_16x16x32_bf16 v[74:77], v[202:205], v[218:221], v[74:77]
	v_mfma_f32_16x16x32_bf16 v[114:117], v[202:205], v[210:213], v[114:117]
	v_mfma_f32_16x16x32_bf16 v[114:117], v[198:201], v[206:209], v[114:117]
	s_barrier
	s_add_i32 s89, 0, 0x18000
	s_add_i32 s91, 0, 0x1c000
	v_add_u32_e32 v142, s89, v161
	v_add_u32_e32 v167, s91, v161
	ds_read_b128 v[168:171], v142
	ds_read_b128 v[172:175], v142 offset:1024
	ds_read_b128 v[180:183], v142 offset:2048
	ds_read_b128 v[184:187], v142 offset:3072
	ds_read_b128 v[188:191], v167
	ds_read_b128 v[198:201], v167 offset:1024
	ds_read_b128 v[202:205], v167 offset:2048
	ds_read_b128 v[206:209], v167 offset:3072
	s_mov_b32 m0, s31
	v_lshl_add_u64 v[176:177], v[242:243], 0, s[16:17]
	ds_read_b128 v[210:213], v165 offset:32768
	ds_read_b128 v[214:217], v165 offset:33792
	ds_read_b128 v[218:221], v165 offset:34816
	ds_read_b128 v[222:225], v165 offset:35840
	ds_read_b128 v[226:229], v165 offset:36864
	ds_read_b128 v[230:233], v165 offset:37888
	ds_read_b128 v[234:237], v165 offset:38912
	ds_read_b128 v[238:241], v165 offset:39936
	global_load_lds_dwordx4 v[176:177], off
	v_lshl_add_u64 v[176:177], v[244:245], 0, s[16:17]
	s_mov_b32 m0, s35
	s_nop 0
	global_load_lds_dwordx4 v[176:177], off
	s_waitcnt vmcnt(8)
	s_waitcnt lgkmcnt(0)
	s_barrier
	s_waitcnt lgkmcnt(0)
	v_mfma_f32_16x16x32_bf16 v[14:17], v[168:171], v[210:213], v[14:17]
	v_mfma_f32_16x16x32_bf16 v[14:17], v[172:175], v[214:217], v[14:17]
	v_mfma_f32_16x16x32_bf16 v[38:41], v[172:175], v[222:225], v[38:41]
	v_mfma_f32_16x16x32_bf16 v[38:41], v[168:171], v[218:221], v[38:41]
	v_mfma_f32_16x16x32_bf16 v[70:73], v[168:171], v[226:229], v[70:73]
	v_mfma_f32_16x16x32_bf16 v[70:73], v[172:175], v[230:233], v[70:73]
	v_mfma_f32_16x16x32_bf16 v[94:97], v[172:175], v[238:241], v[94:97]
	v_mfma_f32_16x16x32_bf16 v[94:97], v[168:171], v[234:237], v[94:97]
	v_mfma_f32_16x16x32_bf16 v[90:93], v[180:183], v[234:237], v[90:93]
	v_mfma_f32_16x16x32_bf16 v[90:93], v[184:187], v[238:241], v[90:93]
	v_mfma_f32_16x16x32_bf16 v[66:69], v[184:187], v[230:233], v[66:69]
	v_mfma_f32_16x16x32_bf16 v[66:69], v[180:183], v[226:229], v[66:69]
	v_mfma_f32_16x16x32_bf16 v[34:37], v[180:183], v[218:221], v[34:37]
	v_mfma_f32_16x16x32_bf16 v[34:37], v[184:187], v[222:225], v[34:37]
	v_mfma_f32_16x16x32_bf16 v[10:13], v[184:187], v[214:217], v[10:13]
	v_mfma_f32_16x16x32_bf16 v[10:13], v[180:183], v[210:213], v[10:13]
	v_mfma_f32_16x16x32_bf16 v[30:33], v[188:191], v[210:213], v[30:33]
	v_mfma_f32_16x16x32_bf16 v[30:33], v[198:201], v[214:217], v[30:33]
	v_mfma_f32_16x16x32_bf16 v[54:57], v[198:201], v[222:225], v[54:57]
	v_mfma_f32_16x16x32_bf16 v[54:57], v[188:191], v[218:221], v[54:57]
	v_mfma_f32_16x16x32_bf16 v[86:89], v[188:191], v[226:229], v[86:89]
	v_mfma_f32_16x16x32_bf16 v[86:89], v[198:201], v[230:233], v[86:89]
	v_mfma_f32_16x16x32_bf16 v[110:113], v[198:201], v[238:241], v[110:113]
	v_mfma_f32_16x16x32_bf16 v[110:113], v[188:191], v[234:237], v[110:113]
	v_mfma_f32_16x16x32_bf16 v[106:109], v[202:205], v[234:237], v[106:109]
	v_mfma_f32_16x16x32_bf16 v[106:109], v[206:209], v[238:241], v[106:109]
	v_mfma_f32_16x16x32_bf16 v[82:85], v[206:209], v[230:233], v[82:85]
	v_mfma_f32_16x16x32_bf16 v[82:85], v[202:205], v[226:229], v[82:85]
	v_mfma_f32_16x16x32_bf16 v[50:53], v[202:205], v[218:221], v[50:53]
	v_mfma_f32_16x16x32_bf16 v[50:53], v[206:209], v[222:225], v[50:53]
	v_mfma_f32_16x16x32_bf16 v[26:29], v[206:209], v[214:217], v[26:29]
	v_mfma_f32_16x16x32_bf16 v[26:29], v[202:205], v[210:213], v[26:29]
	s_barrier
; __device__ __forceinline__ float bflo(unsigned w) { return __uint_as_float(w << 16); }
; __device__ __forceinline__ float bfhi(unsigned w) { return __uint_as_float(w & 0xffff0000u); }
; #define PG8_STAGE(bufoff, gbase, voff) do { _Pragma("unroll") for (int _i = 0; _i < 2; ++_i) \
;         __builtin_amdgcn_global_load_lds((const unsigned*)((const char*)(gbase) + (voff)[_i]), (PG8_LAS unsigned*)(lds + (bufoff) + ldsw + _i * 8192), 16, 0, 0); } while (0)
; #define PG8_LDA(dst, b, h) do { _Pragma("unroll") for (int m = 0; m < 4; ++m) _Pragma("unroll") for (int k = 0; k < 2; ++k) dst[m][k] = *(const PG8_LAS bf16x8*)(lds + PG8_SA(b, h) + aoff + m * 2048 + k * 1024); } while (0)
; #define PG8_BAR __builtin_amdgcn_s_barrier()
;     __device__ __forceinline__ void mid(f32x4 (&acc)[2][2][4][2], const Unit& u, int wr, int wc, int fr, int fq) const {
;         int row0 = u.pm * BM + wr * 64 + fr; const int col0 = u.pn * BM + wc * 32 + 8 * fq;
;         asm volatile("" : "+v"(row0));
; #pragma unroll
;         for (int ai = 0; ai < 2; ++ai)
; #pragma unroll
;             for (int m = 0; m < 4; ++m) { const bf16_t* pr = P + (size_t)(row0 + ai * HALF + m * 16) * NP + col0;
; #pragma unroll
;                 for (int bj = 0; bj < 2; ++bj) { const u32x4 a = *(const u32x4*)(pr + PC_GA + bj * HALF), b = *(const u32x4*)(pr + PC_GB + bj * HALF);
;                     const f32x4 b0 = {bflo(b.x), bfhi(b.x), bflo(b.y), bfhi(b.y)}, b1 = {bflo(b.z), bfhi(b.z), bflo(b.w), bfhi(b.w)};
;                     const f32x4 a0 = {bflo(a.x), bfhi(a.x), bflo(a.y), bfhi(a.y)}, a1 = {bflo(a.z), bfhi(a.z), bflo(a.w), bfhi(a.w)};
;                     f32x4 r0, r1;
; #pragma unroll
;                     for (int j = 0; j < 4; ++j) { r0[j] = a0[j] * __builtin_amdgcn_rcpf(fmaxf(b0[j], 1e-30f)); r1[j] = a1[j] * __builtin_amdgcn_rcpf(fmaxf(b1[j], 1e-30f)); }
;                     acc[ai][bj][m][0] *= r0; acc[ai][bj][m][1] *= r1; }
; template <class Epi, class Sched, bool ALIGN_EPI = false, bool SP2 = false>
; __device__ __forceinline__ void gemm_phase(PG8_LAS unsigned char* lds, const Gemm g, const Sched& S, const Epi& E) {
;     ...
;             PG8_LDA(At, 1, 1); PG8_STAGE(PG8_SB(1, 0), b3, voffB); PG8_STAGE(PG8_SB(1, 1), b3 + hstep, voffB); PG8_STAGE(PG8_SA(1, 0), a3, voffA);
;             PG8_WAIT_V(8); PG8_WAIT_L(0); PG8_BAR; PG8_MMA(1, 0, At, B0); PG8_MMA(1, 1, At, B1); PG8_BAR; PG8_SCHED;
	s_add_i32 s89, s89, s28
	v_lshl_add_u64 v[176:177], v[246:247], 0, s[22:23]
	s_mov_b32 m0, s89
	s_add_i32 s90, s89, 0x2000
	ds_read_b128 v[210:213], v165 offset:49152
	ds_read_b128 v[214:217], v165 offset:50176
	ds_read_b128 v[218:221], v165 offset:51200
	ds_read_b128 v[222:225], v165 offset:52224
	ds_read_b128 v[226:229], v165 offset:53248
	ds_read_b128 v[230:233], v165 offset:54272
	ds_read_b128 v[234:237], v165 offset:55296
	ds_read_b128 v[238:241], v165 offset:56320
	global_load_lds_dwordx4 v[176:177], off
	v_lshl_add_u64 v[176:177], v[248:249], 0, s[22:23]
	s_mov_b32 m0, s90
	s_add_i32 s91, s91, s28
	global_load_lds_dwordx4 v[176:177], off
	v_lshl_add_u64 v[176:177], v[246:247], 0, s[36:37]
	s_mov_b32 m0, s91
	s_add_i32 s92, s91, 0x2000
	global_load_lds_dwordx4 v[176:177], off
	v_lshl_add_u64 v[176:177], v[248:249], 0, s[36:37]
	s_mov_b32 m0, s92
	s_nop 0
	global_load_lds_dwordx4 v[176:177], off
	v_lshl_add_u64 v[176:177], v[242:243], 0, s[22:23]
	s_mov_b32 m0, s75
	s_nop 0
	global_load_lds_dwordx4 v[176:177], off
	v_lshl_add_u64 v[176:177], v[244:245], 0, s[22:23]
	s_mov_b32 m0, s76
	s_nop 0
	global_load_lds_dwordx4 v[176:177], off
	s_waitcnt vmcnt(8)
	s_waitcnt lgkmcnt(0)
	s_barrier
	s_waitcnt lgkmcnt(0)
	v_mfma_f32_16x16x32_bf16 v[126:129], v[168:171], v[210:213], v[126:129]
	v_mfma_f32_16x16x32_bf16 v[126:129], v[172:175], v[214:217], v[126:129]
	v_mfma_f32_16x16x32_bf16 v[102:105], v[172:175], v[222:225], v[102:105]
	v_mfma_f32_16x16x32_bf16 v[102:105], v[168:171], v[218:221], v[102:105]
	v_mfma_f32_16x16x32_bf16 v[62:65], v[168:171], v[226:229], v[62:65]
	v_mfma_f32_16x16x32_bf16 v[62:65], v[172:175], v[230:233], v[62:65]
	v_mfma_f32_16x16x32_bf16 v[22:25], v[172:175], v[238:241], v[22:25]
	v_mfma_f32_16x16x32_bf16 v[22:25], v[168:171], v[234:237], v[22:25]
	v_mfma_f32_16x16x32_bf16 v[18:21], v[180:183], v[234:237], v[18:21]
	v_mfma_f32_16x16x32_bf16 v[18:21], v[184:187], v[238:241], v[18:21]
	v_mfma_f32_16x16x32_bf16 v[58:61], v[184:187], v[230:233], v[58:61]
	v_mfma_f32_16x16x32_bf16 v[58:61], v[180:183], v[226:229], v[58:61]
	v_mfma_f32_16x16x32_bf16 v[98:101], v[180:183], v[218:221], v[98:101]
	v_mfma_f32_16x16x32_bf16 v[98:101], v[184:187], v[222:225], v[98:101]
	v_mfma_f32_16x16x32_bf16 v[122:125], v[184:187], v[214:217], v[122:125]
	v_mfma_f32_16x16x32_bf16 v[122:125], v[180:183], v[210:213], v[122:125]
	v_mfma_f32_16x16x32_bf16 v[118:121], v[188:191], v[210:213], v[118:121]
	v_mfma_f32_16x16x32_bf16 v[118:121], v[198:201], v[214:217], v[118:121]
	v_mfma_f32_16x16x32_bf16 v[78:81], v[198:201], v[222:225], v[78:81]
	v_mfma_f32_16x16x32_bf16 v[78:81], v[188:191], v[218:221], v[78:81]
	v_mfma_f32_16x16x32_bf16 v[46:49], v[188:191], v[226:229], v[46:49]
	v_mfma_f32_16x16x32_bf16 v[46:49], v[198:201], v[230:233], v[46:49]
	v_mfma_f32_16x16x32_bf16 v[6:9], v[198:201], v[238:241], v[6:9]
	v_mfma_f32_16x16x32_bf16 v[6:9], v[188:191], v[234:237], v[6:9]
	v_mfma_f32_16x16x32_bf16 v[2:5], v[202:205], v[234:237], v[2:5]
	v_mfma_f32_16x16x32_bf16 v[2:5], v[206:209], v[238:241], v[2:5]
	v_mfma_f32_16x16x32_bf16 v[42:45], v[206:209], v[230:233], v[42:45]
	v_mfma_f32_16x16x32_bf16 v[42:45], v[202:205], v[226:229], v[42:45]
	v_mfma_f32_16x16x32_bf16 v[74:77], v[202:205], v[218:221], v[74:77]
	v_mfma_f32_16x16x32_bf16 v[74:77], v[206:209], v[222:225], v[74:77]
	v_mfma_f32_16x16x32_bf16 v[114:117], v[206:209], v[214:217], v[114:117]
	v_mfma_f32_16x16x32_bf16 v[114:117], v[202:205], v[210:213], v[114:117]
	s_barrier
	s_add_i32 s27, s27, 2
	s_add_u32 s44, s44, 0x10000
	s_addc_u32 s45, s45, 0
	s_cmp_lt_u32 s27, 30
	s_cbranch_scc1 .LBB0_682
	s_ashr_i32 s41, s40, 31
	s_lshl_b64 s[44:45], s[40:41], 21
	s_add_u32 s44, s18, s44
	s_addc_u32 s45, s19, s45
	s_ashr_i32 s39, s38, 31
	s_lshl_b64 s[46:47], s[38:39], 21
	v_readlane_b32 s58, v255, 15
	v_readlane_b32 s59, v255, 16
	s_add_u32 s46, s58, s46
	s_addc_u32 s47, s59, s47
	s_lshl_b32 s39, s26, 8
	v_or_b32_e32 v130, s39, v162
	v_ashrrev_i32_e32 v131, 31, v130
	v_lshl_add_u32 v166, s70, 8, v160
	v_lshl_add_u64 v[156:157], v[130:131], 1, s[24:25]
	v_mov_b32_e32 v168, v166
	s_and_b64 s[26:27], s[0:1], exec
	v_mad_i64_i32 v[158:159], s[58:59], v168, s78, v[156:157]
	v_add_co_u32_e32 v174, vcc, s61, v158
	s_cselect_b32 s41, s45, s51
	s_nop 0
	v_addc_co_u32_e32 v175, vcc, 0, v159, vcc
	v_add_co_u32_e32 v158, vcc, s77, v158
	global_load_dwordx4 v[130:133], v[174:175], off
	s_nop 0
	v_addc_co_u32_e32 v159, vcc, 0, v159, vcc
	global_load_dwordx4 v[170:173], v[158:159], off
	s_cselect_b32 s93, s44, s50
	s_cselect_b32 s27, s47, s49
	s_cselect_b32 s97, s46, s48
	s_add_u32 s50, s50, 0x10c000
	s_addc_u32 s51, s51, 0
	s_add_u32 s26, s48, 0x110000
	s_addc_u32 s33, s49, 0
	s_mov_b32 s56, 30
	s_waitcnt vmcnt(0)
	v_and_b32_e32 v177, 0xffff0000, v130
	v_lshlrev_b32_e32 v169, 16, v170
	v_max_f32_e32 v169, v169, v169
	v_lshlrev_b32_e32 v178, 16, v171
	v_and_b32_e32 v179, 0xffff0000, v171
	v_lshlrev_b32_e32 v171, 16, v172
	v_max_f32_e32 v169, 0xda24260, v169
	v_and_b32_e32 v176, 0xffff0000, v170
	v_rcp_f32_e32 v170, v169
	v_max_f32_e32 v169, v171, v171
	v_max_f32_e32 v169, 0xda24260, v169
	v_and_b32_e32 v180, 0xffff0000, v172
	v_rcp_f32_e32 v172, v169
	v_max_f32_e32 v169, v176, v176
	v_max_f32_e32 v169, 0xda24260, v169
	v_lshlrev_b32_e32 v176, 16, v130
	v_max_f32_e32 v130, v180, v180
	v_rcp_f32_e32 v171, v169
	v_max_f32_e32 v130, 0xda24260, v130
	v_lshlrev_b32_e32 v181, 16, v173
	v_and_b32_e32 v182, 0xffff0000, v173
	v_rcp_f32_e32 v173, v130
	v_max_f32_e32 v130, v178, v178
	v_pk_mul_f32 v[170:171], v[170:171], v[176:177]
	v_lshlrev_b32_e32 v176, 16, v132
	v_and_b32_e32 v177, 0xffff0000, v132
	v_max_f32_e32 v130, 0xda24260, v130
	v_pk_mul_f32 v[172:173], v[172:173], v[176:177]
	v_rcp_f32_e32 v176, v130
	v_max_f32_e32 v130, v181, v181
	v_lshlrev_b32_e32 v180, 16, v131
	v_and_b32_e32 v181, 0xffff0000, v131
	v_max_f32_e32 v131, v182, v182
	v_max_f32_e32 v130, 0xda24260, v130
	v_max_f32_e32 v131, 0xda24260, v131
	v_rcp_f32_e32 v130, v130
	v_rcp_f32_e32 v131, v131
	v_max_f32_e32 v132, v179, v179
	v_max_f32_e32 v132, 0xda24260, v132
	v_rcp_f32_e32 v177, v132
	v_lshlrev_b32_e32 v132, 16, v133
	v_and_b32_e32 v133, 0xffff0000, v133
	v_pk_mul_f32 v[130:131], v[130:131], v[132:133]
	v_pk_mul_f32 v[14:15], v[14:15], v[170:171]
	v_pk_mul_f32 v[12:13], v[12:13], v[130:131]
	v_pk_mul_f32 v[10:11], v[10:11], v[172:173]
	global_load_dwordx4 v[130:133], v[174:175], off offset:256
	global_load_dwordx4 v[170:173], v[158:159], off offset:256
	v_pk_mul_f32 v[176:177], v[176:177], v[180:181]
	s_waitcnt vmcnt(0)
; __device__ __forceinline__ float bflo(unsigned w) { return __uint_as_float(w << 16); }
; __device__ __forceinline__ float bfhi(unsigned w) { return __uint_as_float(w & 0xffff0000u); }
;     __device__ __forceinline__ void mid(f32x4 (&acc)[2][2][4][2], const Unit& u, int wr, int wc, int fr, int fq) const {
;     ...
;             for (int m = 0; m < 4; ++m) { const bf16_t* pr = P + (size_t)(row0 + ai * HALF + m * 16) * NP + col0;
; #pragma unroll
;                 for (int bj = 0; bj < 2; ++bj) { const u32x4 a = *(const u32x4*)(pr + PC_GA + bj * HALF), b = *(const u32x4*)(pr + PC_GB + bj * HALF);
;                     const f32x4 b0 = {bflo(b.x), bfhi(b.x), bflo(b.y), bfhi(b.y)}, b1 = {bflo(b.z), bfhi(b.z), bflo(b.w), bfhi(b.w)};
;                     const f32x4 a0 = {bflo(a.x), bfhi(a.x), bflo(a.y), bfhi(a.y)}, a1 = {bflo(a.z), bfhi(a.z), bflo(a.w), bfhi(a.w)};
;                     f32x4 r0, r1;
; #pragma unroll
;                     for (int j = 0; j < 4; ++j) { r0[j] = a0[j] * __builtin_amdgcn_rcpf(fmaxf(b0[j], 1e-30f)); r1[j] = a1[j] * __builtin_amdgcn_rcpf(fmaxf(b1[j], 1e-30f)); }
;                     acc[ai][bj][m][0] *= r0; acc[ai][bj][m][1] *= r1; }
	v_lshlrev_b32_e32 v158, 16, v170
	v_and_b32_e32 v159, 0xffff0000, v170
	v_lshlrev_b32_e32 v169, 16, v171
	v_and_b32_e32 v174, 0xffff0000, v171
	v_lshlrev_b32_e32 v170, 16, v172
	v_and_b32_e32 v171, 0xffff0000, v172
	v_max_f32_e32 v158, v158, v158
	v_max_f32_e32 v159, v159, v159
	v_pk_mul_f32 v[16:17], v[16:17], v[176:177]
	v_lshlrev_b32_e32 v175, 16, v173
	v_and_b32_e32 v176, 0xffff0000, v173
	v_max_f32_e32 v158, 0xda24260, v158
	v_max_f32_e32 v170, v170, v170
	v_max_f32_e32 v159, 0xda24260, v159
	v_lshlrev_b32_e32 v172, 16, v130
	v_and_b32_e32 v173, 0xffff0000, v130
	v_max_f32_e32 v130, v171, v171
	v_rcp_f32_e32 v158, v158
	v_max_f32_e32 v170, 0xda24260, v170
	v_rcp_f32_e32 v159, v159
	v_max_f32_e32 v130, 0xda24260, v130
	v_rcp_f32_e32 v170, v170
	v_rcp_f32_e32 v171, v130
	v_max_f32_e32 v130, v169, v169
	v_pk_mul_f32 v[158:159], v[158:159], v[172:173]
	v_lshlrev_b32_e32 v172, 16, v132
	v_and_b32_e32 v173, 0xffff0000, v132
	v_max_f32_e32 v130, 0xda24260, v130
	v_pk_mul_f32 v[170:171], v[170:171], v[172:173]
	v_rcp_f32_e32 v172, v130
	v_max_f32_e32 v130, v175, v175
	v_max_f32_e32 v132, v174, v174
	v_lshlrev_b32_e32 v174, 16, v131
	v_and_b32_e32 v175, 0xffff0000, v131
	v_max_f32_e32 v131, v176, v176
	v_max_f32_e32 v130, 0xda24260, v130
	v_max_f32_e32 v131, 0xda24260, v131
	v_rcp_f32_e32 v130, v130
	v_rcp_f32_e32 v131, v131
	v_max_f32_e32 v132, 0xda24260, v132
	v_rcp_f32_e32 v173, v132
	v_lshlrev_b32_e32 v132, 16, v133
	v_and_b32_e32 v133, 0xffff0000, v133
	v_pk_mul_f32 v[130:131], v[130:131], v[132:133]
	v_pk_mul_f32 v[30:31], v[30:31], v[158:159]
	v_pk_mul_f32 v[28:29], v[28:29], v[130:131]
	v_add_u32_e32 v130, 16, v168
	v_mad_i64_i32 v[158:159], s[58:59], v130, s78, v[156:157]
	v_pk_mul_f32 v[172:173], v[172:173], v[174:175]
	v_add_co_u32_e32 v174, vcc, s61, v158
	v_pk_mul_f32 v[32:33], v[32:33], v[172:173]
	s_nop 0
	v_addc_co_u32_e32 v175, vcc, 0, v159, vcc
	v_add_co_u32_e32 v158, vcc, s77, v158
	v_pk_mul_f32 v[26:27], v[26:27], v[170:171]
	s_nop 0
	v_addc_co_u32_e32 v159, vcc, 0, v159, vcc
	global_load_dwordx4 v[130:133], v[174:175], off
	global_load_dwordx4 v[170:173], v[158:159], off
	s_waitcnt vmcnt(1)
	v_and_b32_e32 v177, 0xffff0000, v130
	s_waitcnt vmcnt(0)
	v_lshlrev_b32_e32 v169, 16, v170
	v_max_f32_e32 v169, v169, v169
	v_lshlrev_b32_e32 v178, 16, v171
	v_and_b32_e32 v179, 0xffff0000, v171
	v_lshlrev_b32_e32 v171, 16, v172
	v_max_f32_e32 v169, 0xda24260, v169
	v_and_b32_e32 v176, 0xffff0000, v170
	v_rcp_f32_e32 v170, v169
	v_max_f32_e32 v169, v171, v171
	v_max_f32_e32 v169, 0xda24260, v169
	v_and_b32_e32 v180, 0xffff0000, v172
	v_rcp_f32_e32 v172, v169
	v_max_f32_e32 v169, v176, v176
	v_max_f32_e32 v169, 0xda24260, v169
	v_lshlrev_b32_e32 v176, 16, v130
	v_max_f32_e32 v130, v180, v180
	v_rcp_f32_e32 v171, v169
	v_max_f32_e32 v130, 0xda24260, v130
	v_lshlrev_b32_e32 v181, 16, v173
	v_and_b32_e32 v182, 0xffff0000, v173
	v_rcp_f32_e32 v173, v130
	v_max_f32_e32 v130, v178, v178
	v_pk_mul_f32 v[170:171], v[170:171], v[176:177]
	v_lshlrev_b32_e32 v176, 16, v132
	v_and_b32_e32 v177, 0xffff0000, v132
	v_max_f32_e32 v130, 0xda24260, v130
	v_pk_mul_f32 v[172:173], v[172:173], v[176:177]
	v_rcp_f32_e32 v176, v130
	v_max_f32_e32 v130, v181, v181
	v_lshlrev_b32_e32 v180, 16, v131
	v_and_b32_e32 v181, 0xffff0000, v131
	v_max_f32_e32 v131, v182, v182
	v_max_f32_e32 v130, 0xda24260, v130
	v_max_f32_e32 v131, 0xda24260, v131
	v_rcp_f32_e32 v130, v130
	v_rcp_f32_e32 v131, v131
	v_max_f32_e32 v132, v179, v179
	v_max_f32_e32 v132, 0xda24260, v132
	v_rcp_f32_e32 v177, v132
	v_lshlrev_b32_e32 v132, 16, v133
	v_and_b32_e32 v133, 0xffff0000, v133
	v_pk_mul_f32 v[130:131], v[130:131], v[132:133]
	v_pk_mul_f32 v[38:39], v[38:39], v[170:171]
	v_pk_mul_f32 v[36:37], v[36:37], v[130:131]
	v_pk_mul_f32 v[34:35], v[34:35], v[172:173]
	global_load_dwordx4 v[130:133], v[174:175], off offset:256
	global_load_dwordx4 v[170:173], v[158:159], off offset:256
	v_pk_mul_f32 v[176:177], v[176:177], v[180:181]
	s_waitcnt vmcnt(0)
	v_lshlrev_b32_e32 v158, 16, v170
	v_and_b32_e32 v159, 0xffff0000, v170
	v_lshlrev_b32_e32 v169, 16, v171
	v_and_b32_e32 v174, 0xffff0000, v171
	v_lshlrev_b32_e32 v170, 16, v172
	v_and_b32_e32 v171, 0xffff0000, v172
	v_max_f32_e32 v158, v158, v158
	v_max_f32_e32 v159, v159, v159
	v_pk_mul_f32 v[40:41], v[40:41], v[176:177]
	v_lshlrev_b32_e32 v175, 16, v173
	v_and_b32_e32 v176, 0xffff0000, v173
	v_max_f32_e32 v158, 0xda24260, v158
	v_max_f32_e32 v170, v170, v170
	v_max_f32_e32 v159, 0xda24260, v159
	v_lshlrev_b32_e32 v172, 16, v130
	v_and_b32_e32 v173, 0xffff0000, v130
	v_max_f32_e32 v130, v171, v171
	v_rcp_f32_e32 v158, v158
	v_max_f32_e32 v170, 0xda24260, v170
	v_rcp_f32_e32 v159, v159
	v_max_f32_e32 v130, 0xda24260, v130
	v_rcp_f32_e32 v170, v170
	v_rcp_f32_e32 v171, v130
	v_max_f32_e32 v130, v169, v169
	v_pk_mul_f32 v[158:159], v[158:159], v[172:173]
	v_lshlrev_b32_e32 v172, 16, v132
	v_and_b32_e32 v173, 0xffff0000, v132
	v_max_f32_e32 v130, 0xda24260, v130
	v_pk_mul_f32 v[170:171], v[170:171], v[172:173]
	v_rcp_f32_e32 v172, v130
	v_max_f32_e32 v130, v175, v175
	v_max_f32_e32 v132, v174, v174
	v_lshlrev_b32_e32 v174, 16, v131
	v_and_b32_e32 v175, 0xffff0000, v131
	v_max_f32_e32 v131, v176, v176
	v_max_f32_e32 v130, 0xda24260, v130
	v_max_f32_e32 v131, 0xda24260, v131
	v_rcp_f32_e32 v130, v130
	v_rcp_f32_e32 v131, v131
	v_max_f32_e32 v132, 0xda24260, v132
	v_rcp_f32_e32 v173, v132
	v_lshlrev_b32_e32 v132, 16, v133
	v_and_b32_e32 v133, 0xffff0000, v133
	v_pk_mul_f32 v[130:131], v[130:131], v[132:133]
	v_pk_mul_f32 v[54:55], v[54:55], v[158:159]
	v_pk_mul_f32 v[52:53], v[52:53], v[130:131]
	v_add_u32_e32 v130, 32, v168
	v_mad_i64_i32 v[158:159], s[58:59], v130, s78, v[156:157]
	v_pk_mul_f32 v[172:173], v[172:173], v[174:175]
	v_add_co_u32_e32 v174, vcc, s61, v158
	v_pk_mul_f32 v[56:57], v[56:57], v[172:173]
	s_nop 0
	v_addc_co_u32_e32 v175, vcc, 0, v159, vcc
	v_add_co_u32_e32 v158, vcc, s77, v158
	v_pk_mul_f32 v[50:51], v[50:51], v[170:171]
	s_nop 0
	v_addc_co_u32_e32 v159, vcc, 0, v159, vcc
	global_load_dwordx4 v[130:133], v[174:175], off
	global_load_dwordx4 v[170:173], v[158:159], off
	s_waitcnt vmcnt(1)
; __device__ __forceinline__ float bflo(unsigned w) { return __uint_as_float(w << 16); }
; __device__ __forceinline__ float bfhi(unsigned w) { return __uint_as_float(w & 0xffff0000u); }
;     __device__ __forceinline__ void mid(f32x4 (&acc)[2][2][4][2], const Unit& u, int wr, int wc, int fr, int fq) const {
;         int row0 = u.pm * BM + wr * 64 + fr; const int col0 = u.pn * BM + wc * 32 + 8 * fq;
;         asm volatile("" : "+v"(row0));
; #pragma unroll
;         for (int ai = 0; ai < 2; ++ai)
; #pragma unroll
;             for (int m = 0; m < 4; ++m) { const bf16_t* pr = P + (size_t)(row0 + ai * HALF + m * 16) * NP + col0;
; #pragma unroll
;                 for (int bj = 0; bj < 2; ++bj) { const u32x4 a = *(const u32x4*)(pr + PC_GA + bj * HALF), b = *(const u32x4*)(pr + PC_GB + bj * HALF);
;                     const f32x4 b0 = {bflo(b.x), bfhi(b.x), bflo(b.y), bfhi(b.y)}, b1 = {bflo(b.z), bfhi(b.z), bflo(b.w), bfhi(b.w)};
;                     const f32x4 a0 = {bflo(a.x), bfhi(a.x), bflo(a.y), bfhi(a.y)}, a1 = {bflo(a.z), bfhi(a.z), bflo(a.w), bfhi(a.w)};
;                     f32x4 r0, r1;
; #pragma unroll
;                     for (int j = 0; j < 4; ++j) { r0[j] = a0[j] * __builtin_amdgcn_rcpf(fmaxf(b0[j], 1e-30f)); r1[j] = a1[j] * __builtin_amdgcn_rcpf(fmaxf(b1[j], 1e-30f)); }
;                     acc[ai][bj][m][0] *= r0; acc[ai][bj][m][1] *= r1; }
;                 asm volatile("" ::: "memory"); }
;     }
	v_and_b32_e32 v177, 0xffff0000, v130
	s_waitcnt vmcnt(0)
	v_lshlrev_b32_e32 v169, 16, v170
	v_max_f32_e32 v169, v169, v169
	v_lshlrev_b32_e32 v178, 16, v171
	v_and_b32_e32 v179, 0xffff0000, v171
	v_lshlrev_b32_e32 v171, 16, v172
	v_max_f32_e32 v169, 0xda24260, v169
	v_and_b32_e32 v176, 0xffff0000, v170
	v_rcp_f32_e32 v170, v169
	v_max_f32_e32 v169, v171, v171
	v_max_f32_e32 v169, 0xda24260, v169
	v_and_b32_e32 v180, 0xffff0000, v172
	v_rcp_f32_e32 v172, v169
	v_max_f32_e32 v169, v176, v176
	v_max_f32_e32 v169, 0xda24260, v169
	v_lshlrev_b32_e32 v176, 16, v130
	v_max_f32_e32 v130, v180, v180
	v_rcp_f32_e32 v171, v169
	v_max_f32_e32 v130, 0xda24260, v130
	v_lshlrev_b32_e32 v181, 16, v173
	v_and_b32_e32 v182, 0xffff0000, v173
	v_rcp_f32_e32 v173, v130
	v_max_f32_e32 v130, v178, v178
	v_pk_mul_f32 v[170:171], v[170:171], v[176:177]
	v_lshlrev_b32_e32 v176, 16, v132
	v_and_b32_e32 v177, 0xffff0000, v132
	v_max_f32_e32 v130, 0xda24260, v130
	v_pk_mul_f32 v[172:173], v[172:173], v[176:177]
	v_rcp_f32_e32 v176, v130
	v_max_f32_e32 v130, v181, v181
	v_lshlrev_b32_e32 v180, 16, v131
	v_and_b32_e32 v181, 0xffff0000, v131
	v_max_f32_e32 v131, v182, v182
	v_max_f32_e32 v130, 0xda24260, v130
	v_max_f32_e32 v131, 0xda24260, v131
	v_rcp_f32_e32 v130, v130
	v_rcp_f32_e32 v131, v131
	v_max_f32_e32 v132, v179, v179
	v_max_f32_e32 v132, 0xda24260, v132
	v_rcp_f32_e32 v177, v132
	v_lshlrev_b32_e32 v132, 16, v133
	v_and_b32_e32 v133, 0xffff0000, v133
	v_pk_mul_f32 v[130:131], v[130:131], v[132:133]
	v_pk_mul_f32 v[70:71], v[70:71], v[170:171]
	v_pk_mul_f32 v[68:69], v[68:69], v[130:131]
	v_pk_mul_f32 v[66:67], v[66:67], v[172:173]
	global_load_dwordx4 v[130:133], v[174:175], off offset:256
	global_load_dwordx4 v[170:173], v[158:159], off offset:256
	v_pk_mul_f32 v[176:177], v[176:177], v[180:181]
	s_waitcnt vmcnt(0)
	v_lshlrev_b32_e32 v158, 16, v170
	v_and_b32_e32 v159, 0xffff0000, v170
	v_lshlrev_b32_e32 v169, 16, v171
	v_and_b32_e32 v174, 0xffff0000, v171
	v_lshlrev_b32_e32 v170, 16, v172
	v_and_b32_e32 v171, 0xffff0000, v172
	v_max_f32_e32 v158, v158, v158
	v_max_f32_e32 v159, v159, v159
	v_pk_mul_f32 v[72:73], v[72:73], v[176:177]
	v_lshlrev_b32_e32 v175, 16, v173
	v_and_b32_e32 v176, 0xffff0000, v173
	v_max_f32_e32 v158, 0xda24260, v158
	v_max_f32_e32 v170, v170, v170
	v_max_f32_e32 v159, 0xda24260, v159
	v_lshlrev_b32_e32 v172, 16, v130
	v_and_b32_e32 v173, 0xffff0000, v130
	v_max_f32_e32 v130, v171, v171
	v_rcp_f32_e32 v158, v158
	v_max_f32_e32 v170, 0xda24260, v170
	v_rcp_f32_e32 v159, v159
	v_max_f32_e32 v130, 0xda24260, v130
	v_rcp_f32_e32 v170, v170
	v_rcp_f32_e32 v171, v130
	v_max_f32_e32 v130, v169, v169
	v_pk_mul_f32 v[158:159], v[158:159], v[172:173]
	v_lshlrev_b32_e32 v172, 16, v132
	v_and_b32_e32 v173, 0xffff0000, v132
	v_max_f32_e32 v130, 0xda24260, v130
	v_pk_mul_f32 v[170:171], v[170:171], v[172:173]
	v_rcp_f32_e32 v172, v130
	v_max_f32_e32 v130, v175, v175
	v_max_f32_e32 v132, v174, v174
	v_lshlrev_b32_e32 v174, 16, v131
	v_and_b32_e32 v175, 0xffff0000, v131
	v_max_f32_e32 v131, v176, v176
	v_max_f32_e32 v130, 0xda24260, v130
	v_max_f32_e32 v131, 0xda24260, v131
	v_rcp_f32_e32 v130, v130
	v_rcp_f32_e32 v131, v131
	v_max_f32_e32 v132, 0xda24260, v132
	v_rcp_f32_e32 v173, v132
	v_lshlrev_b32_e32 v132, 16, v133
	v_and_b32_e32 v133, 0xffff0000, v133
	v_pk_mul_f32 v[130:131], v[130:131], v[132:133]
	v_pk_mul_f32 v[86:87], v[86:87], v[158:159]
	v_pk_mul_f32 v[84:85], v[84:85], v[130:131]
	v_add_u32_e32 v130, 48, v168
	v_mad_i64_i32 v[158:159], s[58:59], v130, s78, v[156:157]
	v_pk_mul_f32 v[172:173], v[172:173], v[174:175]
	v_add_co_u32_e32 v174, vcc, s61, v158
	v_pk_mul_f32 v[88:89], v[88:89], v[172:173]
	s_nop 0
	v_addc_co_u32_e32 v175, vcc, 0, v159, vcc
	v_add_co_u32_e32 v158, vcc, s77, v158
	v_pk_mul_f32 v[82:83], v[82:83], v[170:171]
	s_nop 0
	v_addc_co_u32_e32 v159, vcc, 0, v159, vcc
	global_load_dwordx4 v[130:133], v[174:175], off
	global_load_dwordx4 v[170:173], v[158:159], off
	s_waitcnt vmcnt(1)
	v_and_b32_e32 v177, 0xffff0000, v130
	s_waitcnt vmcnt(0)
	v_lshlrev_b32_e32 v169, 16, v170
	v_max_f32_e32 v169, v169, v169
	v_lshlrev_b32_e32 v178, 16, v171
	v_and_b32_e32 v179, 0xffff0000, v171
	v_lshlrev_b32_e32 v171, 16, v172
	v_max_f32_e32 v169, 0xda24260, v169
	v_and_b32_e32 v176, 0xffff0000, v170
	v_rcp_f32_e32 v170, v169
	v_max_f32_e32 v169, v171, v171
	v_max_f32_e32 v169, 0xda24260, v169
	v_and_b32_e32 v180, 0xffff0000, v172
	v_rcp_f32_e32 v172, v169
	v_max_f32_e32 v169, v176, v176
	v_max_f32_e32 v169, 0xda24260, v169
	v_lshlrev_b32_e32 v176, 16, v130
	v_max_f32_e32 v130, v180, v180
	v_rcp_f32_e32 v171, v169
	v_max_f32_e32 v130, 0xda24260, v130
	v_lshlrev_b32_e32 v181, 16, v173
	v_and_b32_e32 v182, 0xffff0000, v173
	v_rcp_f32_e32 v173, v130
	v_max_f32_e32 v130, v178, v178
	v_pk_mul_f32 v[170:171], v[170:171], v[176:177]
	v_lshlrev_b32_e32 v176, 16, v132
	v_and_b32_e32 v177, 0xffff0000, v132
	v_max_f32_e32 v130, 0xda24260, v130
	v_pk_mul_f32 v[172:173], v[172:173], v[176:177]
	v_rcp_f32_e32 v176, v130
	v_max_f32_e32 v130, v181, v181
	v_lshlrev_b32_e32 v180, 16, v131
	v_and_b32_e32 v181, 0xffff0000, v131
	v_max_f32_e32 v131, v182, v182
	v_max_f32_e32 v130, 0xda24260, v130
	v_max_f32_e32 v131, 0xda24260, v131
	v_rcp_f32_e32 v130, v130
	v_rcp_f32_e32 v131, v131
	v_max_f32_e32 v132, v179, v179
	v_max_f32_e32 v132, 0xda24260, v132
	v_rcp_f32_e32 v177, v132
	v_lshlrev_b32_e32 v132, 16, v133
	v_and_b32_e32 v133, 0xffff0000, v133
	v_pk_mul_f32 v[130:131], v[130:131], v[132:133]
	v_pk_mul_f32 v[94:95], v[94:95], v[170:171]
	v_pk_mul_f32 v[92:93], v[92:93], v[130:131]
	v_pk_mul_f32 v[90:91], v[90:91], v[172:173]
	global_load_dwordx4 v[130:133], v[174:175], off offset:256
	global_load_dwordx4 v[170:173], v[158:159], off offset:256
	v_pk_mul_f32 v[176:177], v[176:177], v[180:181]
	s_waitcnt vmcnt(0)
; __device__ __forceinline__ float bflo(unsigned w) { return __uint_as_float(w << 16); }
; __device__ __forceinline__ float bfhi(unsigned w) { return __uint_as_float(w & 0xffff0000u); }
;     __device__ __forceinline__ void mid(f32x4 (&acc)[2][2][4][2], const Unit& u, int wr, int wc, int fr, int fq) const {
;         int row0 = u.pm * BM + wr * 64 + fr; const int col0 = u.pn * BM + wc * 32 + 8 * fq;
;         asm volatile("" : "+v"(row0));
; #pragma unroll
;         for (int ai = 0; ai < 2; ++ai)
; #pragma unroll
;             for (int m = 0; m < 4; ++m) { const bf16_t* pr = P + (size_t)(row0 + ai * HALF + m * 16) * NP + col0;
; #pragma unroll
;                 for (int bj = 0; bj < 2; ++bj) { const u32x4 a = *(const u32x4*)(pr + PC_GA + bj * HALF), b = *(const u32x4*)(pr + PC_GB + bj * HALF);
;                     const f32x4 b0 = {bflo(b.x), bfhi(b.x), bflo(b.y), bfhi(b.y)}, b1 = {bflo(b.z), bfhi(b.z), bflo(b.w), bfhi(b.w)};
;                     const f32x4 a0 = {bflo(a.x), bfhi(a.x), bflo(a.y), bfhi(a.y)}, a1 = {bflo(a.z), bfhi(a.z), bflo(a.w), bfhi(a.w)};
;                     f32x4 r0, r1;
; #pragma unroll
;                     for (int j = 0; j < 4; ++j) { r0[j] = a0[j] * __builtin_amdgcn_rcpf(fmaxf(b0[j], 1e-30f)); r1[j] = a1[j] * __builtin_amdgcn_rcpf(fmaxf(b1[j], 1e-30f)); }
;                     acc[ai][bj][m][0] *= r0; acc[ai][bj][m][1] *= r1; }
;                 asm volatile("" ::: "memory"); }
;     }
	v_lshlrev_b32_e32 v158, 16, v170
	v_and_b32_e32 v159, 0xffff0000, v170
	v_lshlrev_b32_e32 v169, 16, v171
	v_and_b32_e32 v174, 0xffff0000, v171
	v_lshlrev_b32_e32 v170, 16, v172
	v_and_b32_e32 v171, 0xffff0000, v172
	v_max_f32_e32 v158, v158, v158
	v_max_f32_e32 v159, v159, v159
	v_pk_mul_f32 v[96:97], v[96:97], v[176:177]
	v_lshlrev_b32_e32 v175, 16, v173
	v_and_b32_e32 v176, 0xffff0000, v173
	v_max_f32_e32 v158, 0xda24260, v158
	v_max_f32_e32 v170, v170, v170
	v_max_f32_e32 v159, 0xda24260, v159
	v_lshlrev_b32_e32 v172, 16, v130
	v_and_b32_e32 v173, 0xffff0000, v130
	v_max_f32_e32 v130, v171, v171
	v_rcp_f32_e32 v158, v158
	v_max_f32_e32 v170, 0xda24260, v170
	v_rcp_f32_e32 v159, v159
	v_max_f32_e32 v130, 0xda24260, v130
	v_rcp_f32_e32 v170, v170
	v_rcp_f32_e32 v171, v130
	v_max_f32_e32 v130, v169, v169
	v_pk_mul_f32 v[158:159], v[158:159], v[172:173]
	v_lshlrev_b32_e32 v172, 16, v132
	v_and_b32_e32 v173, 0xffff0000, v132
	v_max_f32_e32 v130, 0xda24260, v130
	v_pk_mul_f32 v[170:171], v[170:171], v[172:173]
	v_rcp_f32_e32 v172, v130
	v_max_f32_e32 v130, v175, v175
	v_max_f32_e32 v132, v174, v174
	v_lshlrev_b32_e32 v174, 16, v131
	v_and_b32_e32 v175, 0xffff0000, v131
	v_max_f32_e32 v131, v176, v176
	v_max_f32_e32 v130, 0xda24260, v130
	v_max_f32_e32 v131, 0xda24260, v131
	v_rcp_f32_e32 v130, v130
	v_rcp_f32_e32 v131, v131
	v_max_f32_e32 v132, 0xda24260, v132
	v_rcp_f32_e32 v173, v132
	v_lshlrev_b32_e32 v132, 16, v133
	v_and_b32_e32 v133, 0xffff0000, v133
	v_pk_mul_f32 v[130:131], v[130:131], v[132:133]
	v_pk_mul_f32 v[110:111], v[110:111], v[158:159]
	v_pk_mul_f32 v[108:109], v[108:109], v[130:131]
	v_add_u32_e32 v130, 0x80, v168
	v_mad_i64_i32 v[158:159], s[58:59], v130, s78, v[156:157]
	v_pk_mul_f32 v[172:173], v[172:173], v[174:175]
	v_add_co_u32_e32 v174, vcc, s61, v158
	v_pk_mul_f32 v[112:113], v[112:113], v[172:173]
	s_nop 0
	v_addc_co_u32_e32 v175, vcc, 0, v159, vcc
	v_add_co_u32_e32 v158, vcc, s77, v158
	v_pk_mul_f32 v[106:107], v[106:107], v[170:171]
	s_nop 0
	v_addc_co_u32_e32 v159, vcc, 0, v159, vcc
	global_load_dwordx4 v[130:133], v[174:175], off
	global_load_dwordx4 v[170:173], v[158:159], off
	s_waitcnt vmcnt(1)
	v_and_b32_e32 v177, 0xffff0000, v130
	s_waitcnt vmcnt(0)
	v_lshlrev_b32_e32 v169, 16, v170
	v_max_f32_e32 v169, v169, v169
	v_lshlrev_b32_e32 v178, 16, v171
	v_and_b32_e32 v179, 0xffff0000, v171
	v_lshlrev_b32_e32 v171, 16, v172
	v_max_f32_e32 v169, 0xda24260, v169
	v_and_b32_e32 v176, 0xffff0000, v170
	v_rcp_f32_e32 v170, v169
	v_max_f32_e32 v169, v171, v171
	v_max_f32_e32 v169, 0xda24260, v169
	v_and_b32_e32 v180, 0xffff0000, v172
	v_rcp_f32_e32 v172, v169
	v_max_f32_e32 v169, v176, v176
	v_max_f32_e32 v169, 0xda24260, v169
	v_lshlrev_b32_e32 v176, 16, v130
	v_max_f32_e32 v130, v180, v180
	v_rcp_f32_e32 v171, v169
	v_max_f32_e32 v130, 0xda24260, v130
	v_lshlrev_b32_e32 v181, 16, v173
	v_and_b32_e32 v182, 0xffff0000, v173
	v_rcp_f32_e32 v173, v130
	v_max_f32_e32 v130, v178, v178
	v_pk_mul_f32 v[170:171], v[170:171], v[176:177]
	v_lshlrev_b32_e32 v176, 16, v132
	v_and_b32_e32 v177, 0xffff0000, v132
	v_max_f32_e32 v130, 0xda24260, v130
	v_pk_mul_f32 v[172:173], v[172:173], v[176:177]
	v_rcp_f32_e32 v176, v130
	v_max_f32_e32 v130, v181, v181
	v_lshlrev_b32_e32 v180, 16, v131
	v_and_b32_e32 v181, 0xffff0000, v131
	v_max_f32_e32 v131, v182, v182
	v_max_f32_e32 v130, 0xda24260, v130
	v_max_f32_e32 v131, 0xda24260, v131
	v_rcp_f32_e32 v130, v130
	v_rcp_f32_e32 v131, v131
	v_max_f32_e32 v132, v179, v179
	v_max_f32_e32 v132, 0xda24260, v132
	v_rcp_f32_e32 v177, v132
	v_lshlrev_b32_e32 v132, 16, v133
	v_and_b32_e32 v133, 0xffff0000, v133
	v_pk_mul_f32 v[130:131], v[130:131], v[132:133]
	v_pk_mul_f32 v[126:127], v[126:127], v[170:171]
	v_pk_mul_f32 v[124:125], v[124:125], v[130:131]
	v_pk_mul_f32 v[122:123], v[122:123], v[172:173]
	global_load_dwordx4 v[130:133], v[174:175], off offset:256
	global_load_dwordx4 v[170:173], v[158:159], off offset:256
	v_pk_mul_f32 v[176:177], v[176:177], v[180:181]
	s_waitcnt vmcnt(0)
	v_lshlrev_b32_e32 v158, 16, v170
	v_and_b32_e32 v159, 0xffff0000, v170
	v_lshlrev_b32_e32 v169, 16, v171
	v_and_b32_e32 v174, 0xffff0000, v171
	v_lshlrev_b32_e32 v170, 16, v172
	v_and_b32_e32 v171, 0xffff0000, v172
	v_max_f32_e32 v158, v158, v158
	v_max_f32_e32 v159, v159, v159
	v_pk_mul_f32 v[128:129], v[128:129], v[176:177]
	v_lshlrev_b32_e32 v175, 16, v173
	v_and_b32_e32 v176, 0xffff0000, v173
	v_max_f32_e32 v158, 0xda24260, v158
	v_max_f32_e32 v170, v170, v170
	v_max_f32_e32 v159, 0xda24260, v159
	v_lshlrev_b32_e32 v172, 16, v130
	v_and_b32_e32 v173, 0xffff0000, v130
	v_max_f32_e32 v130, v171, v171
	v_rcp_f32_e32 v158, v158
	v_max_f32_e32 v170, 0xda24260, v170
	v_rcp_f32_e32 v159, v159
	v_max_f32_e32 v130, 0xda24260, v130
	v_rcp_f32_e32 v170, v170
	v_rcp_f32_e32 v171, v130
	v_max_f32_e32 v130, v169, v169
	v_pk_mul_f32 v[158:159], v[158:159], v[172:173]
	v_lshlrev_b32_e32 v172, 16, v132
	v_and_b32_e32 v173, 0xffff0000, v132
	v_max_f32_e32 v130, 0xda24260, v130
	v_pk_mul_f32 v[170:171], v[170:171], v[172:173]
	v_rcp_f32_e32 v172, v130
	v_max_f32_e32 v130, v175, v175
	v_max_f32_e32 v132, v174, v174
	v_lshlrev_b32_e32 v174, 16, v131
	v_and_b32_e32 v175, 0xffff0000, v131
	v_max_f32_e32 v131, v176, v176
	v_max_f32_e32 v130, 0xda24260, v130
	v_max_f32_e32 v131, 0xda24260, v131
	v_rcp_f32_e32 v130, v130
	v_rcp_f32_e32 v131, v131
	v_max_f32_e32 v132, 0xda24260, v132
	v_rcp_f32_e32 v173, v132
	v_lshlrev_b32_e32 v132, 16, v133
	v_and_b32_e32 v133, 0xffff0000, v133
	v_pk_mul_f32 v[130:131], v[130:131], v[132:133]
	v_pk_mul_f32 v[118:119], v[118:119], v[158:159]
	v_pk_mul_f32 v[116:117], v[116:117], v[130:131]
	v_add_u32_e32 v130, 0x90, v168
	v_mad_i64_i32 v[158:159], s[58:59], v130, s78, v[156:157]
	v_pk_mul_f32 v[172:173], v[172:173], v[174:175]
	v_add_co_u32_e32 v174, vcc, s61, v158
	v_pk_mul_f32 v[120:121], v[120:121], v[172:173]
	s_nop 0
	v_addc_co_u32_e32 v175, vcc, 0, v159, vcc
	v_add_co_u32_e32 v158, vcc, s77, v158
	v_pk_mul_f32 v[114:115], v[114:115], v[170:171]
	s_nop 0
	v_addc_co_u32_e32 v159, vcc, 0, v159, vcc
	global_load_dwordx4 v[130:133], v[174:175], off
	global_load_dwordx4 v[170:173], v[158:159], off
	s_waitcnt vmcnt(1)
; __device__ __forceinline__ float bflo(unsigned w) { return __uint_as_float(w << 16); }
; __device__ __forceinline__ float bfhi(unsigned w) { return __uint_as_float(w & 0xffff0000u); }
;     __device__ __forceinline__ void mid(f32x4 (&acc)[2][2][4][2], const Unit& u, int wr, int wc, int fr, int fq) const {
;         int row0 = u.pm * BM + wr * 64 + fr; const int col0 = u.pn * BM + wc * 32 + 8 * fq;
;         asm volatile("" : "+v"(row0));
; #pragma unroll
;         for (int ai = 0; ai < 2; ++ai)
; #pragma unroll
;             for (int m = 0; m < 4; ++m) { const bf16_t* pr = P + (size_t)(row0 + ai * HALF + m * 16) * NP + col0;
; #pragma unroll
;                 for (int bj = 0; bj < 2; ++bj) { const u32x4 a = *(const u32x4*)(pr + PC_GA + bj * HALF), b = *(const u32x4*)(pr + PC_GB + bj * HALF);
;                     const f32x4 b0 = {bflo(b.x), bfhi(b.x), bflo(b.y), bfhi(b.y)}, b1 = {bflo(b.z), bfhi(b.z), bflo(b.w), bfhi(b.w)};
;                     const f32x4 a0 = {bflo(a.x), bfhi(a.x), bflo(a.y), bfhi(a.y)}, a1 = {bflo(a.z), bfhi(a.z), bflo(a.w), bfhi(a.w)};
;                     f32x4 r0, r1;
; #pragma unroll
;                     for (int j = 0; j < 4; ++j) { r0[j] = a0[j] * __builtin_amdgcn_rcpf(fmaxf(b0[j], 1e-30f)); r1[j] = a1[j] * __builtin_amdgcn_rcpf(fmaxf(b1[j], 1e-30f)); }
;                     acc[ai][bj][m][0] *= r0; acc[ai][bj][m][1] *= r1; }
;                 asm volatile("" ::: "memory"); }
;     }
	v_and_b32_e32 v177, 0xffff0000, v130
	s_waitcnt vmcnt(0)
	v_lshlrev_b32_e32 v169, 16, v170
	v_max_f32_e32 v169, v169, v169
	v_lshlrev_b32_e32 v178, 16, v171
	v_and_b32_e32 v179, 0xffff0000, v171
	v_lshlrev_b32_e32 v171, 16, v172
	v_max_f32_e32 v169, 0xda24260, v169
	v_and_b32_e32 v176, 0xffff0000, v170
	v_rcp_f32_e32 v170, v169
	v_max_f32_e32 v169, v171, v171
	v_max_f32_e32 v169, 0xda24260, v169
	v_and_b32_e32 v180, 0xffff0000, v172
	v_rcp_f32_e32 v172, v169
	v_max_f32_e32 v169, v176, v176
	v_max_f32_e32 v169, 0xda24260, v169
	v_lshlrev_b32_e32 v176, 16, v130
	v_max_f32_e32 v130, v180, v180
	v_rcp_f32_e32 v171, v169
	v_max_f32_e32 v130, 0xda24260, v130
	v_lshlrev_b32_e32 v181, 16, v173
	v_and_b32_e32 v182, 0xffff0000, v173
	v_rcp_f32_e32 v173, v130
	v_max_f32_e32 v130, v178, v178
	v_pk_mul_f32 v[170:171], v[170:171], v[176:177]
	v_lshlrev_b32_e32 v176, 16, v132
	v_and_b32_e32 v177, 0xffff0000, v132
	v_max_f32_e32 v130, 0xda24260, v130
	v_pk_mul_f32 v[172:173], v[172:173], v[176:177]
	v_rcp_f32_e32 v176, v130
	v_max_f32_e32 v130, v181, v181
	v_lshlrev_b32_e32 v180, 16, v131
	v_and_b32_e32 v181, 0xffff0000, v131
	v_max_f32_e32 v131, v182, v182
	v_max_f32_e32 v130, 0xda24260, v130
	v_max_f32_e32 v131, 0xda24260, v131
	v_rcp_f32_e32 v130, v130
	v_rcp_f32_e32 v131, v131
	v_max_f32_e32 v132, v179, v179
	v_max_f32_e32 v132, 0xda24260, v132
	v_rcp_f32_e32 v177, v132
	v_lshlrev_b32_e32 v132, 16, v133
	v_and_b32_e32 v133, 0xffff0000, v133
	v_pk_mul_f32 v[130:131], v[130:131], v[132:133]
	v_pk_mul_f32 v[102:103], v[102:103], v[170:171]
	v_pk_mul_f32 v[100:101], v[100:101], v[130:131]
	v_pk_mul_f32 v[98:99], v[98:99], v[172:173]
	global_load_dwordx4 v[130:133], v[174:175], off offset:256
	global_load_dwordx4 v[170:173], v[158:159], off offset:256
	v_pk_mul_f32 v[176:177], v[176:177], v[180:181]
	s_waitcnt vmcnt(0)
	v_lshlrev_b32_e32 v158, 16, v170
	v_and_b32_e32 v159, 0xffff0000, v170
	v_lshlrev_b32_e32 v169, 16, v171
	v_and_b32_e32 v174, 0xffff0000, v171
	v_lshlrev_b32_e32 v170, 16, v172
	v_and_b32_e32 v171, 0xffff0000, v172
	v_max_f32_e32 v158, v158, v158
	v_max_f32_e32 v159, v159, v159
	v_pk_mul_f32 v[104:105], v[104:105], v[176:177]
	v_lshlrev_b32_e32 v175, 16, v173
	v_and_b32_e32 v176, 0xffff0000, v173
	v_max_f32_e32 v158, 0xda24260, v158
	v_max_f32_e32 v170, v170, v170
	v_max_f32_e32 v159, 0xda24260, v159
	v_lshlrev_b32_e32 v172, 16, v130
	v_and_b32_e32 v173, 0xffff0000, v130
	v_max_f32_e32 v130, v171, v171
	v_rcp_f32_e32 v158, v158
	v_max_f32_e32 v170, 0xda24260, v170
	v_rcp_f32_e32 v159, v159
	v_max_f32_e32 v130, 0xda24260, v130
	v_rcp_f32_e32 v170, v170
	v_rcp_f32_e32 v171, v130
	v_max_f32_e32 v130, v169, v169
	v_pk_mul_f32 v[158:159], v[158:159], v[172:173]
	v_lshlrev_b32_e32 v172, 16, v132
	v_and_b32_e32 v173, 0xffff0000, v132
	v_max_f32_e32 v130, 0xda24260, v130
	v_pk_mul_f32 v[170:171], v[170:171], v[172:173]
	v_rcp_f32_e32 v172, v130
	v_max_f32_e32 v130, v175, v175
	v_max_f32_e32 v132, v174, v174
	v_lshlrev_b32_e32 v174, 16, v131
	v_and_b32_e32 v175, 0xffff0000, v131
	v_max_f32_e32 v131, v176, v176
	v_max_f32_e32 v130, 0xda24260, v130
	v_max_f32_e32 v131, 0xda24260, v131
	v_rcp_f32_e32 v130, v130
	v_rcp_f32_e32 v131, v131
	v_max_f32_e32 v132, 0xda24260, v132
	v_rcp_f32_e32 v173, v132
	v_lshlrev_b32_e32 v132, 16, v133
	v_and_b32_e32 v133, 0xffff0000, v133
	v_pk_mul_f32 v[130:131], v[130:131], v[132:133]
	v_pk_mul_f32 v[78:79], v[78:79], v[158:159]
	v_pk_mul_f32 v[76:77], v[76:77], v[130:131]
	v_add_u32_e32 v130, 0xa0, v168
	v_mad_i64_i32 v[158:159], s[58:59], v130, s78, v[156:157]
	v_pk_mul_f32 v[172:173], v[172:173], v[174:175]
	v_add_co_u32_e32 v174, vcc, s61, v158
	v_pk_mul_f32 v[80:81], v[80:81], v[172:173]
	s_nop 0
	v_addc_co_u32_e32 v175, vcc, 0, v159, vcc
	v_add_co_u32_e32 v158, vcc, s77, v158
	v_pk_mul_f32 v[74:75], v[74:75], v[170:171]
	s_nop 0
	v_addc_co_u32_e32 v159, vcc, 0, v159, vcc
	global_load_dwordx4 v[130:133], v[174:175], off
	global_load_dwordx4 v[170:173], v[158:159], off
	s_waitcnt vmcnt(1)
	v_and_b32_e32 v177, 0xffff0000, v130
	s_waitcnt vmcnt(0)
	v_lshlrev_b32_e32 v169, 16, v170
	v_max_f32_e32 v169, v169, v169
	v_lshlrev_b32_e32 v178, 16, v171
	v_and_b32_e32 v179, 0xffff0000, v171
	v_lshlrev_b32_e32 v171, 16, v172
	v_max_f32_e32 v169, 0xda24260, v169
	v_and_b32_e32 v176, 0xffff0000, v170
	v_rcp_f32_e32 v170, v169
	v_max_f32_e32 v169, v171, v171
	v_max_f32_e32 v169, 0xda24260, v169
	v_and_b32_e32 v180, 0xffff0000, v172
	v_rcp_f32_e32 v172, v169
	v_max_f32_e32 v169, v176, v176
	v_max_f32_e32 v169, 0xda24260, v169
	v_lshlrev_b32_e32 v176, 16, v130
	v_max_f32_e32 v130, v180, v180
	v_rcp_f32_e32 v171, v169
	v_max_f32_e32 v130, 0xda24260, v130
	v_lshlrev_b32_e32 v181, 16, v173
	v_and_b32_e32 v182, 0xffff0000, v173
	v_rcp_f32_e32 v173, v130
	v_max_f32_e32 v130, v178, v178
	v_pk_mul_f32 v[170:171], v[170:171], v[176:177]
	v_lshlrev_b32_e32 v176, 16, v132
	v_and_b32_e32 v177, 0xffff0000, v132
	v_max_f32_e32 v130, 0xda24260, v130
	v_pk_mul_f32 v[172:173], v[172:173], v[176:177]
	v_rcp_f32_e32 v176, v130
	v_max_f32_e32 v130, v181, v181
	v_lshlrev_b32_e32 v180, 16, v131
	v_and_b32_e32 v181, 0xffff0000, v131
	v_max_f32_e32 v131, v182, v182
	v_max_f32_e32 v130, 0xda24260, v130
	v_max_f32_e32 v131, 0xda24260, v131
	v_rcp_f32_e32 v130, v130
	v_rcp_f32_e32 v131, v131
	v_max_f32_e32 v132, v179, v179
	v_max_f32_e32 v132, 0xda24260, v132
	v_rcp_f32_e32 v177, v132
	v_lshlrev_b32_e32 v132, 16, v133
	v_and_b32_e32 v133, 0xffff0000, v133
	v_pk_mul_f32 v[130:131], v[130:131], v[132:133]
	v_pk_mul_f32 v[62:63], v[62:63], v[170:171]
	v_pk_mul_f32 v[60:61], v[60:61], v[130:131]
	v_pk_mul_f32 v[58:59], v[58:59], v[172:173]
	global_load_dwordx4 v[130:133], v[174:175], off offset:256
	global_load_dwordx4 v[170:173], v[158:159], off offset:256
	v_pk_mul_f32 v[176:177], v[176:177], v[180:181]
	s_waitcnt vmcnt(0)
; __device__ __forceinline__ float bflo(unsigned w) { return __uint_as_float(w << 16); }
; __device__ __forceinline__ float bfhi(unsigned w) { return __uint_as_float(w & 0xffff0000u); }
;     __device__ __forceinline__ void mid(f32x4 (&acc)[2][2][4][2], const Unit& u, int wr, int wc, int fr, int fq) const {
;         int row0 = u.pm * BM + wr * 64 + fr; const int col0 = u.pn * BM + wc * 32 + 8 * fq;
;         asm volatile("" : "+v"(row0));
; #pragma unroll
;         for (int ai = 0; ai < 2; ++ai)
; #pragma unroll
;             for (int m = 0; m < 4; ++m) { const bf16_t* pr = P + (size_t)(row0 + ai * HALF + m * 16) * NP + col0;
; #pragma unroll
;                 for (int bj = 0; bj < 2; ++bj) { const u32x4 a = *(const u32x4*)(pr + PC_GA + bj * HALF), b = *(const u32x4*)(pr + PC_GB + bj * HALF);
;                     const f32x4 b0 = {bflo(b.x), bfhi(b.x), bflo(b.y), bfhi(b.y)}, b1 = {bflo(b.z), bfhi(b.z), bflo(b.w), bfhi(b.w)};
;                     const f32x4 a0 = {bflo(a.x), bfhi(a.x), bflo(a.y), bfhi(a.y)}, a1 = {bflo(a.z), bfhi(a.z), bflo(a.w), bfhi(a.w)};
;                     f32x4 r0, r1;
; #pragma unroll
;                     for (int j = 0; j < 4; ++j) { r0[j] = a0[j] * __builtin_amdgcn_rcpf(fmaxf(b0[j], 1e-30f)); r1[j] = a1[j] * __builtin_amdgcn_rcpf(fmaxf(b1[j], 1e-30f)); }
;                     acc[ai][bj][m][0] *= r0; acc[ai][bj][m][1] *= r1; }
;                 asm volatile("" ::: "memory"); }
;     }
	v_lshlrev_b32_e32 v158, 16, v170
	v_and_b32_e32 v159, 0xffff0000, v170
	v_lshlrev_b32_e32 v169, 16, v171
	v_and_b32_e32 v174, 0xffff0000, v171
	v_lshlrev_b32_e32 v170, 16, v172
	v_and_b32_e32 v171, 0xffff0000, v172
	v_max_f32_e32 v158, v158, v158
	v_max_f32_e32 v159, v159, v159
	v_pk_mul_f32 v[64:65], v[64:65], v[176:177]
	v_lshlrev_b32_e32 v175, 16, v173
	v_and_b32_e32 v176, 0xffff0000, v173
	v_max_f32_e32 v158, 0xda24260, v158
	v_max_f32_e32 v170, v170, v170
	v_max_f32_e32 v159, 0xda24260, v159
	v_lshlrev_b32_e32 v172, 16, v130
	v_and_b32_e32 v173, 0xffff0000, v130
	v_max_f32_e32 v130, v171, v171
	v_rcp_f32_e32 v158, v158
	v_max_f32_e32 v170, 0xda24260, v170
	v_rcp_f32_e32 v159, v159
	v_max_f32_e32 v130, 0xda24260, v130
	v_rcp_f32_e32 v170, v170
	v_rcp_f32_e32 v171, v130
	v_max_f32_e32 v130, v169, v169
	v_pk_mul_f32 v[158:159], v[158:159], v[172:173]
	v_lshlrev_b32_e32 v172, 16, v132
	v_and_b32_e32 v173, 0xffff0000, v132
	v_max_f32_e32 v130, 0xda24260, v130
	v_pk_mul_f32 v[170:171], v[170:171], v[172:173]
	v_rcp_f32_e32 v172, v130
	v_max_f32_e32 v130, v175, v175
	v_max_f32_e32 v132, v174, v174
	v_lshlrev_b32_e32 v174, 16, v131
	v_and_b32_e32 v175, 0xffff0000, v131
	v_max_f32_e32 v131, v176, v176
	v_max_f32_e32 v130, 0xda24260, v130
	v_max_f32_e32 v131, 0xda24260, v131
	v_rcp_f32_e32 v130, v130
	v_rcp_f32_e32 v131, v131
	v_max_f32_e32 v132, 0xda24260, v132
	v_rcp_f32_e32 v173, v132
	v_lshlrev_b32_e32 v132, 16, v133
	v_and_b32_e32 v133, 0xffff0000, v133
	v_pk_mul_f32 v[130:131], v[130:131], v[132:133]
	v_pk_mul_f32 v[46:47], v[46:47], v[158:159]
	v_pk_mul_f32 v[44:45], v[44:45], v[130:131]
	v_add_u32_e32 v130, 0xb0, v168
	v_mad_i64_i32 v[156:157], s[58:59], v130, s78, v[156:157]
	v_add_co_u32_e32 v158, vcc, s61, v156
	v_pk_mul_f32 v[42:43], v[42:43], v[170:171]
	s_nop 0
	v_addc_co_u32_e32 v159, vcc, 0, v157, vcc
	v_add_co_u32_e32 v156, vcc, s77, v156
	global_load_dwordx4 v[130:133], v[158:159], off
	s_nop 0
	v_addc_co_u32_e32 v157, vcc, 0, v157, vcc
	global_load_dwordx4 v[168:171], v[156:157], off
	v_pk_mul_f32 v[172:173], v[172:173], v[174:175]
	s_waitcnt vmcnt(0)
	v_lshlrev_b32_e32 v174, 16, v169
	v_and_b32_e32 v175, 0xffff0000, v169
	v_lshlrev_b32_e32 v169, 16, v170
	v_max_f32_e32 v169, v169, v169
	v_pk_mul_f32 v[48:49], v[48:49], v[172:173]
	v_lshlrev_b32_e32 v172, 16, v168
	v_and_b32_e32 v173, 0xffff0000, v168
	v_max_f32_e32 v169, 0xda24260, v169
	v_and_b32_e32 v176, 0xffff0000, v170
	v_max_f32_e32 v168, v172, v172
	v_rcp_f32_e32 v170, v169
	v_max_f32_e32 v169, v173, v173
	v_max_f32_e32 v168, 0xda24260, v168
	v_max_f32_e32 v169, 0xda24260, v169
	v_lshlrev_b32_e32 v172, 16, v130
	v_and_b32_e32 v173, 0xffff0000, v130
	v_max_f32_e32 v130, v176, v176
	v_rcp_f32_e32 v168, v168
	v_rcp_f32_e32 v169, v169
	v_max_f32_e32 v130, 0xda24260, v130
	v_lshlrev_b32_e32 v177, 16, v171
	v_and_b32_e32 v178, 0xffff0000, v171
	v_rcp_f32_e32 v171, v130
	v_max_f32_e32 v130, v174, v174
	v_pk_mul_f32 v[168:169], v[168:169], v[172:173]
	v_lshlrev_b32_e32 v172, 16, v132
	v_and_b32_e32 v173, 0xffff0000, v132
	v_max_f32_e32 v130, 0xda24260, v130
	v_pk_mul_f32 v[170:171], v[170:171], v[172:173]
	v_rcp_f32_e32 v172, v130
	v_max_f32_e32 v130, v177, v177
	v_max_f32_e32 v132, v175, v175
	v_lshlrev_b32_e32 v174, 16, v131
	v_and_b32_e32 v175, 0xffff0000, v131
	v_max_f32_e32 v131, v178, v178
	v_max_f32_e32 v130, 0xda24260, v130
	v_max_f32_e32 v131, 0xda24260, v131
	v_rcp_f32_e32 v130, v130
	v_rcp_f32_e32 v131, v131
	v_max_f32_e32 v132, 0xda24260, v132
	v_rcp_f32_e32 v173, v132
	v_lshlrev_b32_e32 v132, 16, v133
	v_and_b32_e32 v133, 0xffff0000, v133
	v_pk_mul_f32 v[130:131], v[130:131], v[132:133]
	v_pk_mul_f32 v[18:19], v[18:19], v[170:171]
	v_pk_mul_f32 v[20:21], v[20:21], v[130:131]
	global_load_dwordx4 v[130:133], v[158:159], off offset:256
	s_nop 0
	global_load_dwordx4 v[156:159], v[156:157], off offset:256
	v_pk_mul_f32 v[172:173], v[172:173], v[174:175]
	v_pk_mul_f32 v[22:23], v[22:23], v[168:169]
	v_pk_mul_f32 v[24:25], v[24:25], v[172:173]
	s_waitcnt vmcnt(0)
	v_lshlrev_b32_e32 v170, 16, v157
	v_and_b32_e32 v171, 0xffff0000, v157
	v_lshlrev_b32_e32 v157, 16, v158
	v_max_f32_e32 v157, v157, v157
	v_lshlrev_b32_e32 v168, 16, v156
	v_and_b32_e32 v169, 0xffff0000, v156
	v_max_f32_e32 v157, 0xda24260, v157
	v_and_b32_e32 v172, 0xffff0000, v158
	v_max_f32_e32 v156, v168, v168
	v_rcp_f32_e32 v158, v157
	v_max_f32_e32 v157, v169, v169
	v_max_f32_e32 v156, 0xda24260, v156
	v_max_f32_e32 v157, 0xda24260, v157
	v_lshlrev_b32_e32 v168, 16, v130
	v_and_b32_e32 v169, 0xffff0000, v130
	v_max_f32_e32 v130, v172, v172
	v_rcp_f32_e32 v156, v156
	v_rcp_f32_e32 v157, v157
	v_max_f32_e32 v130, 0xda24260, v130
	v_lshlrev_b32_e32 v173, 16, v159
	v_and_b32_e32 v174, 0xffff0000, v159
	v_rcp_f32_e32 v159, v130
	v_max_f32_e32 v130, v170, v170
	v_pk_mul_f32 v[156:157], v[156:157], v[168:169]
	v_lshlrev_b32_e32 v168, 16, v132
	v_and_b32_e32 v169, 0xffff0000, v132
	v_max_f32_e32 v130, 0xda24260, v130
	v_pk_mul_f32 v[158:159], v[158:159], v[168:169]
	v_rcp_f32_e32 v168, v130
	v_max_f32_e32 v130, v173, v173
	v_max_f32_e32 v132, v171, v171
	v_lshlrev_b32_e32 v170, 16, v131
	v_and_b32_e32 v171, 0xffff0000, v131
	v_max_f32_e32 v131, v174, v174
	v_max_f32_e32 v130, 0xda24260, v130
	v_max_f32_e32 v132, 0xda24260, v132
	v_max_f32_e32 v131, 0xda24260, v131
	v_rcp_f32_e32 v130, v130
	v_rcp_f32_e32 v169, v132
	v_rcp_f32_e32 v131, v131
	v_lshlrev_b32_e32 v132, 16, v133
	v_and_b32_e32 v133, 0xffff0000, v133
	v_pk_mul_f32 v[168:169], v[168:169], v[170:171]
	v_pk_mul_f32 v[130:131], v[130:131], v[132:133]
	v_pk_mul_f32 v[8:9], v[8:9], v[168:169]
	v_pk_mul_f32 v[6:7], v[6:7], v[156:157]
	v_pk_mul_f32 v[4:5], v[4:5], v[130:131]
	v_pk_mul_f32 v[2:3], v[2:3], v[158:159]
; #define PG8_STAGE(bufoff, gbase, voff) do { _Pragma("unroll") for (int _i = 0; _i < 2; ++_i) \
;         __builtin_amdgcn_global_load_lds((const unsigned*)((const char*)(gbase) + (voff)[_i]), (PG8_LAS unsigned*)(lds + (bufoff) + ldsw + _i * 8192), 16, 0, 0); } while (0)
; #define PG8_LDA(dst, b, h) do { _Pragma("unroll") for (int m = 0; m < 4; ++m) _Pragma("unroll") for (int k = 0; k < 2; ++k) dst[m][k] = *(const PG8_LAS bf16x8*)(lds + PG8_SA(b, h) + aoff + m * 2048 + k * 1024); } while (0)
; #define PG8_LDB(dst, b, h) do { _Pragma("unroll") for (int n = 0; n < 2; ++n) _Pragma("unroll") for (int k = 0; k < 2; ++k) dst[n][k] = *(const PG8_LAS bf16x8*)(lds + PG8_SB(b, h) + boff + n * 2048 + k * 1024); } while (0)
; #define PG8_MMA(ai, bj, At, Bt) do { __builtin_amdgcn_s_setprio(1); _Pragma("unroll") for (int m = 0; m < 4; ++m) _Pragma("unroll") for (int n = 0; n < 2; ++n) _Pragma("unroll") for (int k = 0; k < 2; ++k) \
;         acc[ai][bj][m][n] = __builtin_amdgcn_mfma_f32_16x16x32_bf16(Bt[n][k], At[m][k], acc[ai][bj][m][n], 0, 0, 0); __builtin_amdgcn_s_setprio(0); } while (0)
; #define PG8_WAIT_V(n) asm volatile("s_waitcnt vmcnt(" #n ")" ::: "memory")
; #define PG8_WAIT_L(n) asm volatile("s_waitcnt lgkmcnt(" #n ")" ::: "memory")
; #define PG8_BAR __builtin_amdgcn_s_barrier()
; #define PG8_SCHED __builtin_amdgcn_sched_barrier(0)
; template <class Epi, class Sched, bool ALIGN_EPI = false, bool SP2 = false>
; __device__ __forceinline__ void gemm_phase(PG8_LAS unsigned char* lds, const Gemm g, const Sched& S, const Epi& E) {
;     ...
;             PG8_LDB(B0, 0, 0); PG8_LDB(B1, 0, 1); PG8_SCHED; PG8_LDA(At, 0, 0); PG8_STAGE(PG8_SA(1, 1), a1 + hstep, voffA);
;             PG8_WAIT_V(8); PG8_WAIT_L(0); PG8_BAR; PG8_MMA(0, 0, At, B0); PG8_MMA(0, 1, At, B1); PG8_BAR; PG8_SCHED;
;             PG8_LDA(At, 0, 1); PG8_STAGE(PG8_SB(0, 0), b2, voffB); PG8_STAGE(PG8_SB(0, 1), b2 + hstep, voffB); PG8_STAGE(PG8_SA(0, 0), a2, voffA);
;             PG8_WAIT_V(8); PG8_WAIT_L(0); PG8_BAR; PG8_MMA(1, 0, At, B0); PG8_MMA(1, 1, At, B1); PG8_BAR; PG8_SCHED;
.LBB0_684:
	ds_read_b128 v[130:133], v163
	ds_read_b128 v[156:159], v163 offset:1024
	ds_read_b128 v[168:171], v163 offset:2048
	ds_read_b128 v[172:175], v163 offset:3072
	ds_read_b128 v[180:183], v164
	ds_read_b128 v[184:187], v164 offset:1024
	ds_read_b128 v[188:191], v164 offset:2048
	ds_read_b128 v[198:201], v164 offset:3072
	s_add_u32 s48, s50, 0x4000
	s_addc_u32 s49, s51, 0
	s_cmp_eq_u32 s56, 60
	s_cselect_b32 s72, s93, s48
	s_cselect_b32 s73, s41, s49
	s_cselect_b32 s70, s97, s26
	s_cselect_b32 s71, s27, s33
	s_add_u32 s48, s72, 0x8000
	s_addc_u32 s49, s73, 0
	s_mov_b32 m0, s83
	ds_read_b128 v[202:205], v165
	ds_read_b128 v[206:209], v165 offset:1024
	ds_read_b128 v[210:213], v165 offset:2048
	ds_read_b128 v[214:217], v165 offset:3072
	ds_read_b128 v[218:221], v165 offset:4096
	ds_read_b128 v[222:225], v165 offset:5120
	ds_read_b128 v[226:229], v165 offset:6144
	ds_read_b128 v[230:233], v165 offset:7168
	global_load_lds_dwordx4 v144, s[50:51]
	s_mov_b32 m0, s84
	s_nop 0
	global_load_lds_dwordx4 v146, s[50:51]
	s_waitcnt vmcnt(8)
	s_waitcnt lgkmcnt(0)
	s_barrier
	s_waitcnt lgkmcnt(0)
	v_mfma_f32_16x16x32_bf16 v[14:17], v[130:133], v[202:205], v[14:17]
	v_mfma_f32_16x16x32_bf16 v[14:17], v[156:159], v[206:209], v[14:17]
	v_mfma_f32_16x16x32_bf16 v[38:41], v[156:159], v[214:217], v[38:41]
	v_mfma_f32_16x16x32_bf16 v[38:41], v[130:133], v[210:213], v[38:41]
	v_mfma_f32_16x16x32_bf16 v[70:73], v[130:133], v[218:221], v[70:73]
	v_mfma_f32_16x16x32_bf16 v[70:73], v[156:159], v[222:225], v[70:73]
	v_mfma_f32_16x16x32_bf16 v[94:97], v[156:159], v[230:233], v[94:97]
	v_mfma_f32_16x16x32_bf16 v[94:97], v[130:133], v[226:229], v[94:97]
	v_mfma_f32_16x16x32_bf16 v[90:93], v[168:171], v[226:229], v[90:93]
	v_mfma_f32_16x16x32_bf16 v[90:93], v[172:175], v[230:233], v[90:93]
	v_mfma_f32_16x16x32_bf16 v[66:69], v[172:175], v[222:225], v[66:69]
	v_mfma_f32_16x16x32_bf16 v[66:69], v[168:171], v[218:221], v[66:69]
	v_mfma_f32_16x16x32_bf16 v[34:37], v[168:171], v[210:213], v[34:37]
	v_mfma_f32_16x16x32_bf16 v[34:37], v[172:175], v[214:217], v[34:37]
	v_mfma_f32_16x16x32_bf16 v[10:13], v[172:175], v[206:209], v[10:13]
	v_mfma_f32_16x16x32_bf16 v[10:13], v[168:171], v[202:205], v[10:13]
	v_mfma_f32_16x16x32_bf16 v[30:33], v[180:183], v[202:205], v[30:33]
	v_mfma_f32_16x16x32_bf16 v[30:33], v[184:187], v[206:209], v[30:33]
	v_mfma_f32_16x16x32_bf16 v[54:57], v[184:187], v[214:217], v[54:57]
	v_mfma_f32_16x16x32_bf16 v[54:57], v[180:183], v[210:213], v[54:57]
	v_mfma_f32_16x16x32_bf16 v[86:89], v[180:183], v[218:221], v[86:89]
	v_mfma_f32_16x16x32_bf16 v[86:89], v[184:187], v[222:225], v[86:89]
	v_mfma_f32_16x16x32_bf16 v[110:113], v[184:187], v[230:233], v[110:113]
	v_mfma_f32_16x16x32_bf16 v[110:113], v[180:183], v[226:229], v[110:113]
	v_mfma_f32_16x16x32_bf16 v[106:109], v[188:191], v[226:229], v[106:109]
	v_mfma_f32_16x16x32_bf16 v[106:109], v[198:201], v[230:233], v[106:109]
	v_mfma_f32_16x16x32_bf16 v[82:85], v[198:201], v[222:225], v[82:85]
	v_mfma_f32_16x16x32_bf16 v[82:85], v[188:191], v[218:221], v[82:85]
	v_mfma_f32_16x16x32_bf16 v[50:53], v[188:191], v[210:213], v[50:53]
	v_mfma_f32_16x16x32_bf16 v[50:53], v[198:201], v[214:217], v[50:53]
	v_mfma_f32_16x16x32_bf16 v[26:29], v[198:201], v[206:209], v[26:29]
	v_mfma_f32_16x16x32_bf16 v[26:29], v[188:191], v[202:205], v[26:29]
	s_barrier
	s_mov_b32 m0, s85
	s_add_u32 s58, s70, 0x4000
	ds_read_b128 v[202:205], v165 offset:16384
	ds_read_b128 v[206:209], v165 offset:17408
	ds_read_b128 v[210:213], v165 offset:18432
	ds_read_b128 v[214:217], v165 offset:19456
	ds_read_b128 v[218:221], v165 offset:20480
	ds_read_b128 v[222:225], v165 offset:21504
	ds_read_b128 v[226:229], v165 offset:22528
	ds_read_b128 v[230:233], v165 offset:23552
	global_load_lds_dwordx4 v136, s[70:71]
	s_mov_b32 m0, s86
	s_addc_u32 s59, s71, 0
	global_load_lds_dwordx4 v140, s[70:71]
	s_mov_b32 m0, s87
	s_nop 0
	global_load_lds_dwordx4 v136, s[58:59]
	s_mov_b32 m0, s88
	s_nop 0
	global_load_lds_dwordx4 v140, s[58:59]
	s_mov_b32 m0, s29
	s_nop 0
	global_load_lds_dwordx4 v134, s[72:73]
	s_mov_b32 m0, s30
	s_nop 0
	global_load_lds_dwordx4 v138, s[72:73]
	s_waitcnt vmcnt(8)
	s_waitcnt lgkmcnt(0)
	s_barrier
	s_waitcnt lgkmcnt(0)
	v_mfma_f32_16x16x32_bf16 v[126:129], v[130:133], v[202:205], v[126:129]
	v_mfma_f32_16x16x32_bf16 v[126:129], v[156:159], v[206:209], v[126:129]
	v_mfma_f32_16x16x32_bf16 v[102:105], v[156:159], v[214:217], v[102:105]
	v_mfma_f32_16x16x32_bf16 v[102:105], v[130:133], v[210:213], v[102:105]
	v_mfma_f32_16x16x32_bf16 v[62:65], v[130:133], v[218:221], v[62:65]
	v_mfma_f32_16x16x32_bf16 v[62:65], v[156:159], v[222:225], v[62:65]
	v_mfma_f32_16x16x32_bf16 v[22:25], v[156:159], v[230:233], v[22:25]
	v_mfma_f32_16x16x32_bf16 v[22:25], v[130:133], v[226:229], v[22:25]
	v_mfma_f32_16x16x32_bf16 v[18:21], v[168:171], v[226:229], v[18:21]
	v_mfma_f32_16x16x32_bf16 v[18:21], v[172:175], v[230:233], v[18:21]
	v_mfma_f32_16x16x32_bf16 v[58:61], v[172:175], v[222:225], v[58:61]
	v_mfma_f32_16x16x32_bf16 v[58:61], v[168:171], v[218:221], v[58:61]
	v_mfma_f32_16x16x32_bf16 v[98:101], v[168:171], v[210:213], v[98:101]
	v_mfma_f32_16x16x32_bf16 v[98:101], v[172:175], v[214:217], v[98:101]
	v_mfma_f32_16x16x32_bf16 v[122:125], v[172:175], v[206:209], v[122:125]
	v_mfma_f32_16x16x32_bf16 v[122:125], v[168:171], v[202:205], v[122:125]
	v_mfma_f32_16x16x32_bf16 v[118:121], v[180:183], v[202:205], v[118:121]
	v_mfma_f32_16x16x32_bf16 v[118:121], v[184:187], v[206:209], v[118:121]
	v_mfma_f32_16x16x32_bf16 v[78:81], v[184:187], v[214:217], v[78:81]
	v_mfma_f32_16x16x32_bf16 v[78:81], v[180:183], v[210:213], v[78:81]
	v_mfma_f32_16x16x32_bf16 v[46:49], v[180:183], v[218:221], v[46:49]
	v_mfma_f32_16x16x32_bf16 v[46:49], v[184:187], v[222:225], v[46:49]
	v_mfma_f32_16x16x32_bf16 v[6:9], v[184:187], v[230:233], v[6:9]
	v_mfma_f32_16x16x32_bf16 v[6:9], v[180:183], v[226:229], v[6:9]
	v_mfma_f32_16x16x32_bf16 v[2:5], v[188:191], v[226:229], v[2:5]
	v_mfma_f32_16x16x32_bf16 v[2:5], v[198:201], v[230:233], v[2:5]
	v_mfma_f32_16x16x32_bf16 v[42:45], v[198:201], v[222:225], v[42:45]
	v_mfma_f32_16x16x32_bf16 v[42:45], v[188:191], v[218:221], v[42:45]
	v_mfma_f32_16x16x32_bf16 v[74:77], v[188:191], v[210:213], v[74:77]
	v_mfma_f32_16x16x32_bf16 v[74:77], v[198:201], v[214:217], v[74:77]
	v_mfma_f32_16x16x32_bf16 v[114:117], v[198:201], v[206:209], v[114:117]
	v_mfma_f32_16x16x32_bf16 v[114:117], v[188:191], v[202:205], v[114:117]
	s_barrier
; #define PG8_STAGE(bufoff, gbase, voff) do { _Pragma("unroll") for (int _i = 0; _i < 2; ++_i) \
;         __builtin_amdgcn_global_load_lds((const unsigned*)((const char*)(gbase) + (voff)[_i]), (PG8_LAS unsigned*)(lds + (bufoff) + ldsw + _i * 8192), 16, 0, 0); } while (0)
; #define PG8_LDA(dst, b, h) do { _Pragma("unroll") for (int m = 0; m < 4; ++m) _Pragma("unroll") for (int k = 0; k < 2; ++k) dst[m][k] = *(const PG8_LAS bf16x8*)(lds + PG8_SA(b, h) + aoff + m * 2048 + k * 1024); } while (0)
; #define PG8_LDB(dst, b, h) do { _Pragma("unroll") for (int n = 0; n < 2; ++n) _Pragma("unroll") for (int k = 0; k < 2; ++k) dst[n][k] = *(const PG8_LAS bf16x8*)(lds + PG8_SB(b, h) + boff + n * 2048 + k * 1024); } while (0)
; #define PG8_MMA(ai, bj, At, Bt) do { __builtin_amdgcn_s_setprio(1); _Pragma("unroll") for (int m = 0; m < 4; ++m) _Pragma("unroll") for (int n = 0; n < 2; ++n) _Pragma("unroll") for (int k = 0; k < 2; ++k) \
;         acc[ai][bj][m][n] = __builtin_amdgcn_mfma_f32_16x16x32_bf16(Bt[n][k], At[m][k], acc[ai][bj][m][n], 0, 0, 0); __builtin_amdgcn_s_setprio(0); } while (0)
; #define PG8_WAIT_V(n) asm volatile("s_waitcnt vmcnt(" #n ")" ::: "memory")
; #define PG8_WAIT_L(n) asm volatile("s_waitcnt lgkmcnt(" #n ")" ::: "memory")
; #define PG8_BAR __builtin_amdgcn_s_barrier()
; #define PG8_SCHED __builtin_amdgcn_sched_barrier(0)
; template <class Epi, class Sched, bool ALIGN_EPI = false, bool SP2 = false>
; __device__ __forceinline__ void gemm_phase(PG8_LAS unsigned char* lds, const Gemm g, const Sched& S, const Epi& E) {
;     ...
;             PG8_LDB(B0, 1, 0); PG8_LDB(B1, 1, 1); PG8_SCHED; PG8_LDA(At, 1, 0); PG8_STAGE(PG8_SA(0, 1), a2 + hstep, voffA);
;             PG8_WAIT_V(8); PG8_WAIT_L(0); PG8_BAR; PG8_MMA(0, 0, At, B0); PG8_MMA(0, 1, At, B1); PG8_BAR; PG8_SCHED;
;             PG8_LDA(At, 1, 1); PG8_STAGE(PG8_SB(1, 0), b3, voffB); PG8_STAGE(PG8_SB(1, 1), b3 + hstep, voffB); PG8_STAGE(PG8_SA(1, 0), a3, voffA);
;             PG8_WAIT_V(8); PG8_WAIT_L(0); PG8_BAR; PG8_MMA(1, 0, At, B0); PG8_MMA(1, 1, At, B1); PG8_BAR; PG8_SCHED;
	ds_read_b128 v[130:133], v142
	ds_read_b128 v[156:159], v142 offset:1024
	ds_read_b128 v[168:171], v142 offset:2048
	ds_read_b128 v[172:175], v142 offset:3072
	ds_read_b128 v[180:183], v167
	ds_read_b128 v[184:187], v167 offset:1024
	ds_read_b128 v[188:191], v167 offset:2048
	ds_read_b128 v[198:201], v167 offset:3072
	s_add_u32 s58, s72, 0x4000
	s_addc_u32 s59, s73, 0
	s_mov_b32 m0, s31
	ds_read_b128 v[202:205], v165 offset:32768
	ds_read_b128 v[206:209], v165 offset:33792
	ds_read_b128 v[210:213], v165 offset:34816
	ds_read_b128 v[214:217], v165 offset:35840
	ds_read_b128 v[218:221], v165 offset:36864
	ds_read_b128 v[222:225], v165 offset:37888
	ds_read_b128 v[226:229], v165 offset:38912
	ds_read_b128 v[230:233], v165 offset:39936
	global_load_lds_dwordx4 v134, s[58:59]
	s_mov_b32 m0, s35
	s_nop 0
	global_load_lds_dwordx4 v138, s[58:59]
	s_waitcnt vmcnt(8)
	s_waitcnt lgkmcnt(0)
	s_barrier
	s_waitcnt lgkmcnt(0)
	v_mfma_f32_16x16x32_bf16 v[14:17], v[130:133], v[202:205], v[14:17]
	v_mfma_f32_16x16x32_bf16 v[14:17], v[156:159], v[206:209], v[14:17]
	v_mfma_f32_16x16x32_bf16 v[38:41], v[156:159], v[214:217], v[38:41]
	v_mfma_f32_16x16x32_bf16 v[38:41], v[130:133], v[210:213], v[38:41]
	v_mfma_f32_16x16x32_bf16 v[70:73], v[130:133], v[218:221], v[70:73]
	v_mfma_f32_16x16x32_bf16 v[70:73], v[156:159], v[222:225], v[70:73]
	v_mfma_f32_16x16x32_bf16 v[94:97], v[156:159], v[230:233], v[94:97]
	v_mfma_f32_16x16x32_bf16 v[94:97], v[130:133], v[226:229], v[94:97]
	v_mfma_f32_16x16x32_bf16 v[90:93], v[168:171], v[226:229], v[90:93]
	v_mfma_f32_16x16x32_bf16 v[90:93], v[172:175], v[230:233], v[90:93]
	v_mfma_f32_16x16x32_bf16 v[66:69], v[172:175], v[222:225], v[66:69]
	v_mfma_f32_16x16x32_bf16 v[66:69], v[168:171], v[218:221], v[66:69]
	v_mfma_f32_16x16x32_bf16 v[34:37], v[168:171], v[210:213], v[34:37]
	v_mfma_f32_16x16x32_bf16 v[34:37], v[172:175], v[214:217], v[34:37]
	v_mfma_f32_16x16x32_bf16 v[10:13], v[172:175], v[206:209], v[10:13]
	v_mfma_f32_16x16x32_bf16 v[10:13], v[168:171], v[202:205], v[10:13]
	v_mfma_f32_16x16x32_bf16 v[30:33], v[180:183], v[202:205], v[30:33]
	v_mfma_f32_16x16x32_bf16 v[30:33], v[184:187], v[206:209], v[30:33]
	v_mfma_f32_16x16x32_bf16 v[54:57], v[184:187], v[214:217], v[54:57]
	v_mfma_f32_16x16x32_bf16 v[54:57], v[180:183], v[210:213], v[54:57]
	v_mfma_f32_16x16x32_bf16 v[86:89], v[180:183], v[218:221], v[86:89]
	v_mfma_f32_16x16x32_bf16 v[86:89], v[184:187], v[222:225], v[86:89]
	v_mfma_f32_16x16x32_bf16 v[110:113], v[184:187], v[230:233], v[110:113]
	v_mfma_f32_16x16x32_bf16 v[110:113], v[180:183], v[226:229], v[110:113]
	v_mfma_f32_16x16x32_bf16 v[106:109], v[188:191], v[226:229], v[106:109]
	v_mfma_f32_16x16x32_bf16 v[106:109], v[198:201], v[230:233], v[106:109]
	v_mfma_f32_16x16x32_bf16 v[82:85], v[198:201], v[222:225], v[82:85]
	v_mfma_f32_16x16x32_bf16 v[82:85], v[188:191], v[218:221], v[82:85]
	v_mfma_f32_16x16x32_bf16 v[50:53], v[188:191], v[210:213], v[50:53]
	v_mfma_f32_16x16x32_bf16 v[50:53], v[198:201], v[214:217], v[50:53]
	v_mfma_f32_16x16x32_bf16 v[26:29], v[198:201], v[206:209], v[26:29]
	v_mfma_f32_16x16x32_bf16 v[26:29], v[188:191], v[202:205], v[26:29]
	s_barrier
	s_add_u32 s58, s70, 0x8000
	s_addc_u32 s59, s71, 0
	s_mov_b32 m0, s89
	ds_read_b128 v[202:205], v165 offset:49152
	ds_read_b128 v[206:209], v165 offset:50176
	ds_read_b128 v[210:213], v165 offset:51200
	ds_read_b128 v[214:217], v165 offset:52224
	ds_read_b128 v[218:221], v165 offset:53248
	ds_read_b128 v[222:225], v165 offset:54272
	ds_read_b128 v[226:229], v165 offset:55296
	ds_read_b128 v[230:233], v165 offset:56320
	global_load_lds_dwordx4 v136, s[58:59]
	v_lshl_add_u64 v[176:177], s[58:59], 0, v[140:141]
	s_add_u32 s58, s70, 0xc000
	s_mov_b32 m0, s90
	s_addc_u32 s59, s71, 0
	global_load_lds_dwordx4 v[176:177], off
	s_mov_b32 m0, s91
	s_nop 0
	global_load_lds_dwordx4 v136, s[58:59]
	s_mov_b32 m0, s92
	s_nop 0
	global_load_lds_dwordx4 v140, s[58:59]
	s_mov_b32 m0, s75
	s_nop 0
	global_load_lds_dwordx4 v134, s[48:49]
	s_mov_b32 m0, s76
	s_nop 0
	global_load_lds_dwordx4 v138, s[48:49]
	s_waitcnt vmcnt(8)
	s_waitcnt lgkmcnt(0)
	s_barrier
	s_waitcnt lgkmcnt(0)
	v_mfma_f32_16x16x32_bf16 v[126:129], v[130:133], v[202:205], v[126:129]
	v_mfma_f32_16x16x32_bf16 v[126:129], v[156:159], v[206:209], v[126:129]
	v_mfma_f32_16x16x32_bf16 v[102:105], v[156:159], v[214:217], v[102:105]
	v_mfma_f32_16x16x32_bf16 v[102:105], v[130:133], v[210:213], v[102:105]
	v_mfma_f32_16x16x32_bf16 v[62:65], v[130:133], v[218:221], v[62:65]
	v_mfma_f32_16x16x32_bf16 v[62:65], v[156:159], v[222:225], v[62:65]
	v_mfma_f32_16x16x32_bf16 v[22:25], v[156:159], v[230:233], v[22:25]
	v_mfma_f32_16x16x32_bf16 v[22:25], v[130:133], v[226:229], v[22:25]
	v_mfma_f32_16x16x32_bf16 v[18:21], v[168:171], v[226:229], v[18:21]
	v_mfma_f32_16x16x32_bf16 v[18:21], v[172:175], v[230:233], v[18:21]
	v_mfma_f32_16x16x32_bf16 v[58:61], v[172:175], v[222:225], v[58:61]
	v_mfma_f32_16x16x32_bf16 v[58:61], v[168:171], v[218:221], v[58:61]
	v_mfma_f32_16x16x32_bf16 v[98:101], v[168:171], v[210:213], v[98:101]
	v_mfma_f32_16x16x32_bf16 v[98:101], v[172:175], v[214:217], v[98:101]
	v_mfma_f32_16x16x32_bf16 v[122:125], v[172:175], v[206:209], v[122:125]
	v_mfma_f32_16x16x32_bf16 v[122:125], v[168:171], v[202:205], v[122:125]
	v_mfma_f32_16x16x32_bf16 v[118:121], v[180:183], v[202:205], v[118:121]
	v_mfma_f32_16x16x32_bf16 v[118:121], v[184:187], v[206:209], v[118:121]
	v_mfma_f32_16x16x32_bf16 v[78:81], v[184:187], v[214:217], v[78:81]
	v_mfma_f32_16x16x32_bf16 v[78:81], v[180:183], v[210:213], v[78:81]
	v_mfma_f32_16x16x32_bf16 v[46:49], v[180:183], v[218:221], v[46:49]
	v_mfma_f32_16x16x32_bf16 v[46:49], v[184:187], v[222:225], v[46:49]
	v_mfma_f32_16x16x32_bf16 v[6:9], v[184:187], v[230:233], v[6:9]
	v_mfma_f32_16x16x32_bf16 v[6:9], v[180:183], v[226:229], v[6:9]
	v_mfma_f32_16x16x32_bf16 v[2:5], v[188:191], v[226:229], v[2:5]
	v_mfma_f32_16x16x32_bf16 v[2:5], v[198:201], v[230:233], v[2:5]
	v_mfma_f32_16x16x32_bf16 v[42:45], v[198:201], v[222:225], v[42:45]
	v_mfma_f32_16x16x32_bf16 v[42:45], v[188:191], v[218:221], v[42:45]
	v_mfma_f32_16x16x32_bf16 v[74:77], v[188:191], v[210:213], v[74:77]
	v_mfma_f32_16x16x32_bf16 v[74:77], v[198:201], v[214:217], v[74:77]
	v_mfma_f32_16x16x32_bf16 v[114:117], v[198:201], v[206:209], v[114:117]
	v_mfma_f32_16x16x32_bf16 v[114:117], v[188:191], v[202:205], v[114:117]
	s_barrier
	s_add_i32 s56, s56, 2
	s_add_u32 s50, s50, 0x10000
	s_addc_u32 s51, s51, 0
	s_add_u32 s26, s26, 0x10000
	s_addc_u32 s33, s33, 0
	s_cmp_lt_u32 s56, 62
	s_cbranch_scc1 .LBB0_684
	s_andn2_b64 vcc, exec, s[12:13]
	s_cbranch_vccnz .LBB0_687
	s_barrier

; #define PG8_STAGE(bufoff, gbase, voff) do { _Pragma("unroll") for (int _i = 0; _i < 2; ++_i) \
;         __builtin_amdgcn_global_load_lds((const unsigned*)((const char*)(gbase) + (voff)[_i]), (PG8_LAS unsigned*)(lds + (bufoff) + ldsw + _i * 8192), 16, 0, 0); } while (0)
; #define PG8_LDA(dst, b, h) do { _Pragma("unroll") for (int m = 0; m < 4; ++m) _Pragma("unroll") for (int k = 0; k < 2; ++k) dst[m][k] = *(const PG8_LAS bf16x8*)(lds + PG8_SA(b, h) + aoff + m * 2048 + k * 1024); } while (0)
; #define PG8_LDB(dst, b, h) do { _Pragma("unroll") for (int n = 0; n < 2; ++n) _Pragma("unroll") for (int k = 0; k < 2; ++k) dst[n][k] = *(const PG8_LAS bf16x8*)(lds + PG8_SB(b, h) + boff + n * 2048 + k * 1024); } while (0)
; #define PG8_MMA(ai, bj, At, Bt) do { __builtin_amdgcn_s_setprio(1); _Pragma("unroll") for (int m = 0; m < 4; ++m) _Pragma("unroll") for (int n = 0; n < 2; ++n) _Pragma("unroll") for (int k = 0; k < 2; ++k) \
;         acc[ai][bj][m][n] = __builtin_amdgcn_mfma_f32_16x16x32_bf16(Bt[n][k], At[m][k], acc[ai][bj][m][n], 0, 0, 0); __builtin_amdgcn_s_setprio(0); } while (0)
; #define PG8_WAIT_V(n) asm volatile("s_waitcnt vmcnt(" #n ")" ::: "memory")
; #define PG8_WAIT_L(n) asm volatile("s_waitcnt lgkmcnt(" #n ")" ::: "memory")
; #define PG8_BAR __builtin_amdgcn_s_barrier()
; #define PG8_SCHED __builtin_amdgcn_sched_barrier(0)
; template <class Epi, class Sched, bool ALIGN_EPI = false, bool SP2 = false>
; __device__ __forceinline__ void gemm_phase(PG8_LAS unsigned char* lds, const Gemm g, const Sched& S, const Epi& E) {
;     ...
;             PG8_LDB(B0, 0, 0); PG8_LDB(B1, 0, 1); PG8_SCHED; PG8_LDA(At, 0, 0); PG8_STAGE(PG8_SA(1, 1), a1 + hstep, voffA);
;             PG8_WAIT_V(8); PG8_WAIT_L(0); PG8_BAR; PG8_MMA(0, 0, At, B0); PG8_MMA(0, 1, At, B1); PG8_BAR; PG8_SCHED;
;             PG8_LDA(At, 0, 1); PG8_STAGE(PG8_SB(0, 0), b2, voffB); PG8_STAGE(PG8_SB(0, 1), b2 + hstep, voffB); PG8_STAGE(PG8_SA(0, 0), a2, voffA);
;             PG8_WAIT_V(8); PG8_WAIT_L(0); PG8_BAR; PG8_MMA(1, 0, At, B0); PG8_MMA(1, 1, At, B1); PG8_BAR; PG8_SCHED;
.LBB0_757:
	ds_read_b128 v[154:157], v149
	ds_read_b128 v[158:161], v149 offset:1024
	ds_read_b128 v[162:165], v149 offset:2048
	ds_read_b128 v[166:169], v149 offset:3072
	ds_read_b128 v[170:173], v150
	ds_read_b128 v[174:177], v150 offset:1024
	ds_read_b128 v[180:183], v150 offset:2048
	ds_read_b128 v[184:187], v150 offset:3072
	s_add_u32 s46, s44, 0x4000
	s_addc_u32 s47, s45, 0
	s_cmp_eq_u32 s70, 60
	s_cselect_b32 s50, s39, s46
	s_cselect_b32 s51, s17, s47
	s_cselect_b32 s48, s41, s68
	s_cselect_b32 s49, s15, s69
	s_add_u32 s46, s50, 0x8000
	s_addc_u32 s47, s51, 0
	s_sub_u32 s46, s44, 0x4000
	s_subb_u32 s47, s45, 0
	s_mov_b32 m0, s57
	s_nop 0
	global_load_lds_dwordx4 v130, s[46:47]
	s_mov_b32 m0, s58
	s_nop 0
	global_load_lds_dwordx4 v134, s[46:47]
	s_add_i32 m0, s26, 0xc000
	ds_read_b128 v[188:191], v151
	ds_read_b128 v[198:201], v151 offset:1024
	ds_read_b128 v[202:205], v151 offset:2048
	ds_read_b128 v[206:209], v151 offset:3072
	ds_read_b128 v[210:213], v151 offset:4096
	ds_read_b128 v[214:217], v151 offset:5120
	ds_read_b128 v[218:221], v151 offset:6144
	ds_read_b128 v[222:225], v151 offset:7168
	global_load_lds_dwordx4 v138, s[44:45]
	s_add_i32 m0, s26, 0xe000
	s_nop 0
	global_load_lds_dwordx4 v140, s[44:45]
	s_waitcnt vmcnt(8)
	s_waitcnt lgkmcnt(0)
	s_barrier
	s_waitcnt lgkmcnt(0)
	v_mfma_f32_16x16x32_bf16 v[126:129], v[154:157], v[188:191], v[126:129]
	v_mfma_f32_16x16x32_bf16 v[126:129], v[158:161], v[198:201], v[126:129]
	v_mfma_f32_16x16x32_bf16 v[110:113], v[158:161], v[206:209], v[110:113]
	v_mfma_f32_16x16x32_bf16 v[110:113], v[154:157], v[202:205], v[110:113]
	v_mfma_f32_16x16x32_bf16 v[94:97], v[154:157], v[210:213], v[94:97]
	v_mfma_f32_16x16x32_bf16 v[94:97], v[158:161], v[214:217], v[94:97]
	v_mfma_f32_16x16x32_bf16 v[78:81], v[158:161], v[222:225], v[78:81]
	v_mfma_f32_16x16x32_bf16 v[78:81], v[154:157], v[218:221], v[78:81]
	v_mfma_f32_16x16x32_bf16 v[74:77], v[162:165], v[218:221], v[74:77]
	v_mfma_f32_16x16x32_bf16 v[74:77], v[166:169], v[222:225], v[74:77]
	v_mfma_f32_16x16x32_bf16 v[90:93], v[166:169], v[214:217], v[90:93]
	v_mfma_f32_16x16x32_bf16 v[90:93], v[162:165], v[210:213], v[90:93]
	v_mfma_f32_16x16x32_bf16 v[106:109], v[162:165], v[202:205], v[106:109]
	v_mfma_f32_16x16x32_bf16 v[106:109], v[166:169], v[206:209], v[106:109]
	v_mfma_f32_16x16x32_bf16 v[122:125], v[166:169], v[198:201], v[122:125]
	v_mfma_f32_16x16x32_bf16 v[122:125], v[162:165], v[188:191], v[122:125]
	v_mfma_f32_16x16x32_bf16 v[118:121], v[170:173], v[188:191], v[118:121]
	v_mfma_f32_16x16x32_bf16 v[118:121], v[174:177], v[198:201], v[118:121]
	v_mfma_f32_16x16x32_bf16 v[102:105], v[174:177], v[206:209], v[102:105]
	v_mfma_f32_16x16x32_bf16 v[102:105], v[170:173], v[202:205], v[102:105]
	v_mfma_f32_16x16x32_bf16 v[86:89], v[170:173], v[210:213], v[86:89]
	v_mfma_f32_16x16x32_bf16 v[86:89], v[174:177], v[214:217], v[86:89]
	v_mfma_f32_16x16x32_bf16 v[70:73], v[174:177], v[222:225], v[70:73]
	v_mfma_f32_16x16x32_bf16 v[70:73], v[170:173], v[218:221], v[70:73]
	v_mfma_f32_16x16x32_bf16 v[66:69], v[180:183], v[218:221], v[66:69]
	v_mfma_f32_16x16x32_bf16 v[66:69], v[184:187], v[222:225], v[66:69]
	v_mfma_f32_16x16x32_bf16 v[82:85], v[184:187], v[214:217], v[82:85]
	v_mfma_f32_16x16x32_bf16 v[82:85], v[180:183], v[210:213], v[82:85]
	v_mfma_f32_16x16x32_bf16 v[98:101], v[180:183], v[202:205], v[98:101]
	v_mfma_f32_16x16x32_bf16 v[98:101], v[184:187], v[206:209], v[98:101]
	v_mfma_f32_16x16x32_bf16 v[114:117], v[184:187], v[198:201], v[114:117]
	v_mfma_f32_16x16x32_bf16 v[114:117], v[180:183], v[188:191], v[114:117]
	s_barrier
	s_add_i32 s71, s59, s3
	s_mov_b32 m0, s71
	ds_read_b128 v[188:191], v151 offset:16384
	ds_read_b128 v[198:201], v151 offset:17408
	ds_read_b128 v[202:205], v151 offset:18432
	ds_read_b128 v[206:209], v151 offset:19456
	ds_read_b128 v[210:213], v151 offset:20480
	ds_read_b128 v[214:217], v151 offset:21504
	ds_read_b128 v[218:221], v151 offset:22528
	ds_read_b128 v[222:225], v151 offset:23552
	global_load_lds_dwordx4 v132, s[48:49]
	s_add_i32 m0, s71, 0x2000
	s_add_u32 s72, s48, 0x4000
	s_addc_u32 s73, s49, 0
	s_add_i32 s71, s61, s3
	global_load_lds_dwordx4 v136, s[48:49]
	s_mov_b32 m0, s71
	s_nop 0
	global_load_lds_dwordx4 v132, s[72:73]
	s_add_i32 m0, s71, 0x2000
	s_nop 0
	global_load_lds_dwordx4 v136, s[72:73]
	s_waitcnt vmcnt(6)
	s_waitcnt lgkmcnt(0)
	s_barrier
	s_waitcnt lgkmcnt(0)
	v_mfma_f32_16x16x32_bf16 v[62:65], v[154:157], v[188:191], v[62:65]
	v_mfma_f32_16x16x32_bf16 v[62:65], v[158:161], v[198:201], v[62:65]
	v_mfma_f32_16x16x32_bf16 v[46:49], v[158:161], v[206:209], v[46:49]
	v_mfma_f32_16x16x32_bf16 v[46:49], v[154:157], v[202:205], v[46:49]
	v_mfma_f32_16x16x32_bf16 v[30:33], v[154:157], v[210:213], v[30:33]
	v_mfma_f32_16x16x32_bf16 v[30:33], v[158:161], v[214:217], v[30:33]
	v_mfma_f32_16x16x32_bf16 v[14:17], v[158:161], v[222:225], v[14:17]
	v_mfma_f32_16x16x32_bf16 v[14:17], v[154:157], v[218:221], v[14:17]
	v_mfma_f32_16x16x32_bf16 v[10:13], v[162:165], v[218:221], v[10:13]
	v_mfma_f32_16x16x32_bf16 v[10:13], v[166:169], v[222:225], v[10:13]
	v_mfma_f32_16x16x32_bf16 v[26:29], v[166:169], v[214:217], v[26:29]
	v_mfma_f32_16x16x32_bf16 v[26:29], v[162:165], v[210:213], v[26:29]
	v_mfma_f32_16x16x32_bf16 v[42:45], v[162:165], v[202:205], v[42:45]
	v_mfma_f32_16x16x32_bf16 v[42:45], v[166:169], v[206:209], v[42:45]
	v_mfma_f32_16x16x32_bf16 v[58:61], v[166:169], v[198:201], v[58:61]
	v_mfma_f32_16x16x32_bf16 v[58:61], v[162:165], v[188:191], v[58:61]
	v_mfma_f32_16x16x32_bf16 v[54:57], v[170:173], v[188:191], v[54:57]
	v_mfma_f32_16x16x32_bf16 v[54:57], v[174:177], v[198:201], v[54:57]
	v_mfma_f32_16x16x32_bf16 v[38:41], v[174:177], v[206:209], v[38:41]
	v_mfma_f32_16x16x32_bf16 v[38:41], v[170:173], v[202:205], v[38:41]
	v_mfma_f32_16x16x32_bf16 v[22:25], v[170:173], v[210:213], v[22:25]
	v_mfma_f32_16x16x32_bf16 v[22:25], v[174:177], v[214:217], v[22:25]
	v_mfma_f32_16x16x32_bf16 v[6:9], v[174:177], v[222:225], v[6:9]
	v_mfma_f32_16x16x32_bf16 v[6:9], v[170:173], v[218:221], v[6:9]
	v_mfma_f32_16x16x32_bf16 v[2:5], v[180:183], v[218:221], v[2:5]
	v_mfma_f32_16x16x32_bf16 v[2:5], v[184:187], v[222:225], v[2:5]
	v_mfma_f32_16x16x32_bf16 v[18:21], v[184:187], v[214:217], v[18:21]
	v_mfma_f32_16x16x32_bf16 v[18:21], v[180:183], v[210:213], v[18:21]
	v_mfma_f32_16x16x32_bf16 v[34:37], v[180:183], v[202:205], v[34:37]
	v_mfma_f32_16x16x32_bf16 v[34:37], v[184:187], v[206:209], v[34:37]
	v_mfma_f32_16x16x32_bf16 v[50:53], v[184:187], v[198:201], v[50:53]
	v_mfma_f32_16x16x32_bf16 v[50:53], v[180:183], v[188:191], v[50:53]
	s_barrier
; #define PG8_STAGE(bufoff, gbase, voff) do { _Pragma("unroll") for (int _i = 0; _i < 2; ++_i) \
;         __builtin_amdgcn_global_load_lds((const unsigned*)((const char*)(gbase) + (voff)[_i]), (PG8_LAS unsigned*)(lds + (bufoff) + ldsw + _i * 8192), 16, 0, 0); } while (0)
; #define PG8_LDA(dst, b, h) do { _Pragma("unroll") for (int m = 0; m < 4; ++m) _Pragma("unroll") for (int k = 0; k < 2; ++k) dst[m][k] = *(const PG8_LAS bf16x8*)(lds + PG8_SA(b, h) + aoff + m * 2048 + k * 1024); } while (0)
; #define PG8_LDB(dst, b, h) do { _Pragma("unroll") for (int n = 0; n < 2; ++n) _Pragma("unroll") for (int k = 0; k < 2; ++k) dst[n][k] = *(const PG8_LAS bf16x8*)(lds + PG8_SB(b, h) + boff + n * 2048 + k * 1024); } while (0)
; #define PG8_MMA(ai, bj, At, Bt) do { __builtin_amdgcn_s_setprio(1); _Pragma("unroll") for (int m = 0; m < 4; ++m) _Pragma("unroll") for (int n = 0; n < 2; ++n) _Pragma("unroll") for (int k = 0; k < 2; ++k) \
;         acc[ai][bj][m][n] = __builtin_amdgcn_mfma_f32_16x16x32_bf16(Bt[n][k], At[m][k], acc[ai][bj][m][n], 0, 0, 0); __builtin_amdgcn_s_setprio(0); } while (0)
; #define PG8_WAIT_V(n) asm volatile("s_waitcnt vmcnt(" #n ")" ::: "memory")
; #define PG8_WAIT_L(n) asm volatile("s_waitcnt lgkmcnt(" #n ")" ::: "memory")
; #define PG8_BAR __builtin_amdgcn_s_barrier()
; #define PG8_SCHED __builtin_amdgcn_sched_barrier(0)
; template <class Epi, class Sched, bool ALIGN_EPI = false, bool SP2 = false>
; __device__ __forceinline__ void gemm_phase(PG8_LAS unsigned char* lds, const Gemm g, const Sched& S, const Epi& E) {
;     ...
;             PG8_LDB(B0, 1, 0); PG8_LDB(B1, 1, 1); PG8_SCHED; PG8_LDA(At, 1, 0); PG8_STAGE(PG8_SA(0, 1), a2 + hstep, voffA);
;             PG8_WAIT_V(8); PG8_WAIT_L(0); PG8_BAR; PG8_MMA(0, 0, At, B0); PG8_MMA(0, 1, At, B1); PG8_BAR; PG8_SCHED;
;             PG8_LDA(At, 1, 1); PG8_STAGE(PG8_SB(1, 0), b3, voffB); PG8_STAGE(PG8_SB(1, 1), b3 + hstep, voffB); PG8_STAGE(PG8_SA(1, 0), a3, voffA);
;             PG8_WAIT_V(8); PG8_WAIT_L(0); PG8_BAR; PG8_MMA(1, 0, At, B0); PG8_MMA(1, 1, At, B1); PG8_BAR; PG8_SCHED;
	s_add_i32 s71, 0, 0x18000
	v_add_u32_e32 v146, s71, v1
	s_add_i32 s72, 0, 0x1c000
	ds_read_b128 v[154:157], v146
	ds_read_b128 v[158:161], v146 offset:1024
	ds_read_b128 v[162:165], v146 offset:2048
	ds_read_b128 v[166:169], v146 offset:3072
	v_add_u32_e32 v146, s72, v1
	ds_read_b128 v[170:173], v146
	ds_read_b128 v[174:177], v146 offset:1024
	ds_read_b128 v[180:183], v146 offset:2048
	ds_read_b128 v[184:187], v146 offset:3072
	s_mov_b32 m0, s26
	s_nop 0
	global_load_lds_dwordx4 v130, s[50:51]
	s_mov_b32 m0, s27
	s_nop 0
	global_load_lds_dwordx4 v134, s[50:51]
	s_add_u32 s50, s50, 0x4000
	s_addc_u32 s51, s51, 0
	s_mov_b32 m0, s28
	ds_read_b128 v[188:191], v151 offset:32768
	ds_read_b128 v[198:201], v151 offset:33792
	ds_read_b128 v[202:205], v151 offset:34816
	ds_read_b128 v[206:209], v151 offset:35840
	ds_read_b128 v[210:213], v151 offset:36864
	ds_read_b128 v[214:217], v151 offset:37888
	ds_read_b128 v[218:221], v151 offset:38912
	ds_read_b128 v[222:225], v151 offset:39936
	global_load_lds_dwordx4 v130, s[50:51]
	s_mov_b32 m0, s29
	s_nop 0
	global_load_lds_dwordx4 v134, s[50:51]
	s_waitcnt vmcnt(8)
	s_waitcnt lgkmcnt(0)
	s_barrier
	s_waitcnt lgkmcnt(0)
	v_mfma_f32_16x16x32_bf16 v[126:129], v[154:157], v[188:191], v[126:129]
	v_mfma_f32_16x16x32_bf16 v[126:129], v[158:161], v[198:201], v[126:129]
	v_mfma_f32_16x16x32_bf16 v[110:113], v[158:161], v[206:209], v[110:113]
	v_mfma_f32_16x16x32_bf16 v[110:113], v[154:157], v[202:205], v[110:113]
	v_mfma_f32_16x16x32_bf16 v[94:97], v[154:157], v[210:213], v[94:97]
	v_mfma_f32_16x16x32_bf16 v[94:97], v[158:161], v[214:217], v[94:97]
	v_mfma_f32_16x16x32_bf16 v[78:81], v[158:161], v[222:225], v[78:81]
	v_mfma_f32_16x16x32_bf16 v[78:81], v[154:157], v[218:221], v[78:81]
	v_mfma_f32_16x16x32_bf16 v[74:77], v[162:165], v[218:221], v[74:77]
	v_mfma_f32_16x16x32_bf16 v[74:77], v[166:169], v[222:225], v[74:77]
	v_mfma_f32_16x16x32_bf16 v[90:93], v[166:169], v[214:217], v[90:93]
	v_mfma_f32_16x16x32_bf16 v[90:93], v[162:165], v[210:213], v[90:93]
	v_mfma_f32_16x16x32_bf16 v[106:109], v[162:165], v[202:205], v[106:109]
	v_mfma_f32_16x16x32_bf16 v[106:109], v[166:169], v[206:209], v[106:109]
	v_mfma_f32_16x16x32_bf16 v[122:125], v[166:169], v[198:201], v[122:125]
	v_mfma_f32_16x16x32_bf16 v[122:125], v[162:165], v[188:191], v[122:125]
	v_mfma_f32_16x16x32_bf16 v[118:121], v[170:173], v[188:191], v[118:121]
	v_mfma_f32_16x16x32_bf16 v[118:121], v[174:177], v[198:201], v[118:121]
	v_mfma_f32_16x16x32_bf16 v[102:105], v[174:177], v[206:209], v[102:105]
	v_mfma_f32_16x16x32_bf16 v[102:105], v[170:173], v[202:205], v[102:105]
	v_mfma_f32_16x16x32_bf16 v[86:89], v[170:173], v[210:213], v[86:89]
	v_mfma_f32_16x16x32_bf16 v[86:89], v[174:177], v[214:217], v[86:89]
	v_mfma_f32_16x16x32_bf16 v[70:73], v[174:177], v[222:225], v[70:73]
	v_mfma_f32_16x16x32_bf16 v[70:73], v[170:173], v[218:221], v[70:73]
	v_mfma_f32_16x16x32_bf16 v[66:69], v[180:183], v[218:221], v[66:69]
	v_mfma_f32_16x16x32_bf16 v[66:69], v[184:187], v[222:225], v[66:69]
	v_mfma_f32_16x16x32_bf16 v[82:85], v[184:187], v[214:217], v[82:85]
	v_mfma_f32_16x16x32_bf16 v[82:85], v[180:183], v[210:213], v[82:85]
	v_mfma_f32_16x16x32_bf16 v[98:101], v[180:183], v[202:205], v[98:101]
	v_mfma_f32_16x16x32_bf16 v[98:101], v[184:187], v[206:209], v[98:101]
	v_mfma_f32_16x16x32_bf16 v[114:117], v[184:187], v[198:201], v[114:117]
	v_mfma_f32_16x16x32_bf16 v[114:117], v[180:183], v[188:191], v[114:117]
	s_barrier
	s_add_u32 s50, s48, 0x8000
	s_addc_u32 s51, s49, 0
	s_add_i32 s71, s71, s3
	s_mov_b32 m0, s71
	ds_read_b128 v[188:191], v151 offset:49152
	ds_read_b128 v[198:201], v151 offset:50176
	ds_read_b128 v[202:205], v151 offset:51200
	ds_read_b128 v[206:209], v151 offset:52224
	ds_read_b128 v[210:213], v151 offset:53248
	ds_read_b128 v[214:217], v151 offset:54272
	ds_read_b128 v[218:221], v151 offset:55296
	ds_read_b128 v[222:225], v151 offset:56320
	global_load_lds_dwordx4 v132, s[50:51]
	s_add_i32 m0, s71, 0x2000
	s_add_u32 s48, s48, 0xc000
	v_lshl_add_u64 v[146:147], s[50:51], 0, v[136:137]
	s_addc_u32 s49, s49, 0
	s_add_i32 s50, s72, s3
	global_load_lds_dwordx4 v[146:147], off
	s_mov_b32 m0, s50
	s_nop 0
	global_load_lds_dwordx4 v132, s[48:49]
	s_add_i32 m0, s50, 0x2000
	s_nop 0
	global_load_lds_dwordx4 v136, s[48:49]
	s_waitcnt vmcnt(6)
	s_waitcnt lgkmcnt(0)
	s_barrier
	s_waitcnt lgkmcnt(0)
	v_mfma_f32_16x16x32_bf16 v[62:65], v[154:157], v[188:191], v[62:65]
	v_mfma_f32_16x16x32_bf16 v[62:65], v[158:161], v[198:201], v[62:65]
	v_mfma_f32_16x16x32_bf16 v[46:49], v[158:161], v[206:209], v[46:49]
	v_mfma_f32_16x16x32_bf16 v[46:49], v[154:157], v[202:205], v[46:49]
	v_mfma_f32_16x16x32_bf16 v[30:33], v[154:157], v[210:213], v[30:33]
	v_mfma_f32_16x16x32_bf16 v[30:33], v[158:161], v[214:217], v[30:33]
	v_mfma_f32_16x16x32_bf16 v[14:17], v[158:161], v[222:225], v[14:17]
	v_mfma_f32_16x16x32_bf16 v[14:17], v[154:157], v[218:221], v[14:17]
	v_mfma_f32_16x16x32_bf16 v[10:13], v[162:165], v[218:221], v[10:13]
	v_mfma_f32_16x16x32_bf16 v[10:13], v[166:169], v[222:225], v[10:13]
	v_mfma_f32_16x16x32_bf16 v[26:29], v[166:169], v[214:217], v[26:29]
	v_mfma_f32_16x16x32_bf16 v[26:29], v[162:165], v[210:213], v[26:29]
	v_mfma_f32_16x16x32_bf16 v[42:45], v[162:165], v[202:205], v[42:45]
	v_mfma_f32_16x16x32_bf16 v[42:45], v[166:169], v[206:209], v[42:45]
	v_mfma_f32_16x16x32_bf16 v[58:61], v[166:169], v[198:201], v[58:61]
	v_mfma_f32_16x16x32_bf16 v[58:61], v[162:165], v[188:191], v[58:61]
	v_mfma_f32_16x16x32_bf16 v[54:57], v[170:173], v[188:191], v[54:57]
	v_mfma_f32_16x16x32_bf16 v[54:57], v[174:177], v[198:201], v[54:57]
	v_mfma_f32_16x16x32_bf16 v[38:41], v[174:177], v[206:209], v[38:41]
	v_mfma_f32_16x16x32_bf16 v[38:41], v[170:173], v[202:205], v[38:41]
	v_mfma_f32_16x16x32_bf16 v[22:25], v[170:173], v[210:213], v[22:25]
	v_mfma_f32_16x16x32_bf16 v[22:25], v[174:177], v[214:217], v[22:25]
	v_mfma_f32_16x16x32_bf16 v[6:9], v[174:177], v[222:225], v[6:9]
	v_mfma_f32_16x16x32_bf16 v[6:9], v[170:173], v[218:221], v[6:9]
	v_mfma_f32_16x16x32_bf16 v[2:5], v[180:183], v[218:221], v[2:5]
	v_mfma_f32_16x16x32_bf16 v[2:5], v[184:187], v[222:225], v[2:5]
	v_mfma_f32_16x16x32_bf16 v[18:21], v[184:187], v[214:217], v[18:21]
	v_mfma_f32_16x16x32_bf16 v[18:21], v[180:183], v[210:213], v[18:21]
	v_mfma_f32_16x16x32_bf16 v[34:37], v[180:183], v[202:205], v[34:37]
	v_mfma_f32_16x16x32_bf16 v[34:37], v[184:187], v[206:209], v[34:37]
	v_mfma_f32_16x16x32_bf16 v[50:53], v[184:187], v[198:201], v[50:53]
	v_mfma_f32_16x16x32_bf16 v[50:53], v[180:183], v[188:191], v[50:53]
	s_barrier
	s_add_i32 s70, s70, 2
	s_add_u32 s44, s44, 0x10000
	s_addc_u32 s45, s45, 0
	s_add_u32 s68, s68, 0x10000
	s_addc_u32 s69, s69, 0
	s_cmp_gt_u32 s70, 61
	s_cbranch_scc0 .LBB0_757
	s_and_b64 vcc, exec, s[12:13]
	s_cbranch_vccz .LBB0_760
	s_barrier

; #define PG8_STAGE(bufoff, gbase, voff) do { _Pragma("unroll") for (int _i = 0; _i < 2; ++_i) \
;         __builtin_amdgcn_global_load_lds((const unsigned*)((const char*)(gbase) + (voff)[_i]), (PG8_LAS unsigned*)(lds + (bufoff) + ldsw + _i * 8192), 16, 0, 0); } while (0)
; #define PG8_LDA(dst, b, h) do { _Pragma("unroll") for (int m = 0; m < 4; ++m) _Pragma("unroll") for (int k = 0; k < 2; ++k) dst[m][k] = *(const PG8_LAS bf16x8*)(lds + PG8_SA(b, h) + aoff + m * 2048 + k * 1024); } while (0)
; #define PG8_LDB(dst, b, h) do { _Pragma("unroll") for (int n = 0; n < 2; ++n) _Pragma("unroll") for (int k = 0; k < 2; ++k) dst[n][k] = *(const PG8_LAS bf16x8*)(lds + PG8_SB(b, h) + boff + n * 2048 + k * 1024); } while (0)
; #define PG8_MMA(ai, bj, At, Bt) do { __builtin_amdgcn_s_setprio(1); _Pragma("unroll") for (int m = 0; m < 4; ++m) _Pragma("unroll") for (int n = 0; n < 2; ++n) _Pragma("unroll") for (int k = 0; k < 2; ++k) \
;         acc[ai][bj][m][n] = __builtin_amdgcn_mfma_f32_16x16x32_bf16(Bt[n][k], At[m][k], acc[ai][bj][m][n], 0, 0, 0); __builtin_amdgcn_s_setprio(0); } while (0)
; #define PG8_WAIT_V(n) asm volatile("s_waitcnt vmcnt(" #n ")" ::: "memory")
; #define PG8_WAIT_L(n) asm volatile("s_waitcnt lgkmcnt(" #n ")" ::: "memory")
; #define PG8_BAR __builtin_amdgcn_s_barrier()
; #define PG8_SCHED __builtin_amdgcn_sched_barrier(0)
; template <class Epi, class Sched, bool ALIGN_EPI = false, bool SP2 = false>
; __device__ __forceinline__ void gemm_phase(PG8_LAS unsigned char* lds, const Gemm g, const Sched& S, const Epi& E) {
;     ...
;             PG8_LDB(B0, 0, 0); PG8_LDB(B1, 0, 1); PG8_SCHED; PG8_LDA(At, 0, 0); PG8_STAGE(PG8_SA(1, 1), a1 + hstep, voffA);
;             PG8_WAIT_V(8); PG8_WAIT_L(0); PG8_BAR; PG8_MMA(0, 0, At, B0); PG8_MMA(0, 1, At, B1); PG8_BAR; PG8_SCHED;
;             PG8_LDA(At, 0, 1); PG8_STAGE(PG8_SB(0, 0), b2, voffB); PG8_STAGE(PG8_SB(0, 1), b2 + hstep, voffB); PG8_STAGE(PG8_SA(0, 0), a2, voffA);
;             PG8_WAIT_V(8); PG8_WAIT_L(0); PG8_BAR; PG8_MMA(1, 0, At, B0); PG8_MMA(1, 1, At, B1); PG8_BAR; PG8_SCHED;
.LBB0_840:
	ds_read_b128 v[148:151], v153
	ds_read_b128 v[158:161], v153 offset:1024
	ds_read_b128 v[162:165], v153 offset:2048
	ds_read_b128 v[166:169], v153 offset:3072
	ds_read_b128 v[170:173], v154
	ds_read_b128 v[174:177], v154 offset:1024
	ds_read_b128 v[180:183], v154 offset:2048
	ds_read_b128 v[184:187], v154 offset:3072
	s_add_u32 s42, s40, 0x4000
	s_addc_u32 s43, s41, 0
	s_cmp_eq_u32 s69, 60
	s_cselect_b32 s46, s65, s42
	s_cselect_b32 s47, s23, s43
	s_cselect_b32 s44, s66, s67
	s_cselect_b32 s45, s17, s68
	s_add_u32 s42, s46, 0x8000
	s_addc_u32 s43, s47, 0
	s_sub_u32 s42, s40, 0x4000
	s_subb_u32 s43, s41, 0
	s_mov_b32 m0, s50
	s_nop 0
	global_load_lds_dwordx4 v130, s[42:43]
	s_mov_b32 m0, s51
	s_nop 0
	global_load_lds_dwordx4 v134, s[42:43]
	s_add_i32 m0, s28, 0xc000
	ds_read_b128 v[188:191], v155
	ds_read_b128 v[198:201], v155 offset:1024
	ds_read_b128 v[202:205], v155 offset:2048
	ds_read_b128 v[206:209], v155 offset:3072
	ds_read_b128 v[210:213], v155 offset:4096
	ds_read_b128 v[214:217], v155 offset:5120
	ds_read_b128 v[218:221], v155 offset:6144
	ds_read_b128 v[222:225], v155 offset:7168
	global_load_lds_dwordx4 v140, s[40:41]
	s_add_i32 m0, s28, 0xe000
	s_nop 0
	global_load_lds_dwordx4 v142, s[40:41]
	s_waitcnt vmcnt(8)
	s_waitcnt lgkmcnt(0)
	s_barrier
	s_waitcnt lgkmcnt(0)
	v_mfma_f32_16x16x32_bf16 v[126:129], v[148:151], v[188:191], v[126:129]
	v_mfma_f32_16x16x32_bf16 v[126:129], v[158:161], v[198:201], v[126:129]
	v_mfma_f32_16x16x32_bf16 v[110:113], v[158:161], v[206:209], v[110:113]
	v_mfma_f32_16x16x32_bf16 v[110:113], v[148:151], v[202:205], v[110:113]
	v_mfma_f32_16x16x32_bf16 v[94:97], v[148:151], v[210:213], v[94:97]
	v_mfma_f32_16x16x32_bf16 v[94:97], v[158:161], v[214:217], v[94:97]
	v_mfma_f32_16x16x32_bf16 v[78:81], v[158:161], v[222:225], v[78:81]
	v_mfma_f32_16x16x32_bf16 v[78:81], v[148:151], v[218:221], v[78:81]
	v_mfma_f32_16x16x32_bf16 v[74:77], v[162:165], v[218:221], v[74:77]
	v_mfma_f32_16x16x32_bf16 v[74:77], v[166:169], v[222:225], v[74:77]
	v_mfma_f32_16x16x32_bf16 v[90:93], v[166:169], v[214:217], v[90:93]
	v_mfma_f32_16x16x32_bf16 v[90:93], v[162:165], v[210:213], v[90:93]
	v_mfma_f32_16x16x32_bf16 v[106:109], v[162:165], v[202:205], v[106:109]
	v_mfma_f32_16x16x32_bf16 v[106:109], v[166:169], v[206:209], v[106:109]
	v_mfma_f32_16x16x32_bf16 v[122:125], v[166:169], v[198:201], v[122:125]
	v_mfma_f32_16x16x32_bf16 v[122:125], v[162:165], v[188:191], v[122:125]
	v_mfma_f32_16x16x32_bf16 v[118:121], v[170:173], v[188:191], v[118:121]
	v_mfma_f32_16x16x32_bf16 v[118:121], v[174:177], v[198:201], v[118:121]
	v_mfma_f32_16x16x32_bf16 v[102:105], v[174:177], v[206:209], v[102:105]
	v_mfma_f32_16x16x32_bf16 v[102:105], v[170:173], v[202:205], v[102:105]
	v_mfma_f32_16x16x32_bf16 v[86:89], v[170:173], v[210:213], v[86:89]
	v_mfma_f32_16x16x32_bf16 v[86:89], v[174:177], v[214:217], v[86:89]
	v_mfma_f32_16x16x32_bf16 v[70:73], v[174:177], v[222:225], v[70:73]
	v_mfma_f32_16x16x32_bf16 v[70:73], v[170:173], v[218:221], v[70:73]
	v_mfma_f32_16x16x32_bf16 v[66:69], v[180:183], v[218:221], v[66:69]
	v_mfma_f32_16x16x32_bf16 v[66:69], v[184:187], v[222:225], v[66:69]
	v_mfma_f32_16x16x32_bf16 v[82:85], v[184:187], v[214:217], v[82:85]
	v_mfma_f32_16x16x32_bf16 v[82:85], v[180:183], v[210:213], v[82:85]
	v_mfma_f32_16x16x32_bf16 v[98:101], v[180:183], v[202:205], v[98:101]
	v_mfma_f32_16x16x32_bf16 v[98:101], v[184:187], v[206:209], v[98:101]
	v_mfma_f32_16x16x32_bf16 v[114:117], v[184:187], v[198:201], v[114:117]
	v_mfma_f32_16x16x32_bf16 v[114:117], v[180:183], v[188:191], v[114:117]
	s_barrier
	s_add_i32 s70, s56, s3
	s_mov_b32 m0, s70
	ds_read_b128 v[188:191], v155 offset:16384
	ds_read_b128 v[198:201], v155 offset:17408
	ds_read_b128 v[202:205], v155 offset:18432
	ds_read_b128 v[206:209], v155 offset:19456
	ds_read_b128 v[210:213], v155 offset:20480
	ds_read_b128 v[214:217], v155 offset:21504
	ds_read_b128 v[218:221], v155 offset:22528
	ds_read_b128 v[222:225], v155 offset:23552
	global_load_lds_dwordx4 v132, s[44:45]
	s_add_i32 m0, s70, 0x2000
	s_add_u32 s70, s44, 0x4000
	s_addc_u32 s71, s45, 0
	s_add_i32 s72, s57, s3
	global_load_lds_dwordx4 v136, s[44:45]
	s_mov_b32 m0, s72
	s_nop 0
	global_load_lds_dwordx4 v132, s[70:71]
	s_add_i32 m0, s72, 0x2000
	s_nop 0
	global_load_lds_dwordx4 v136, s[70:71]
	s_waitcnt vmcnt(6)
	s_waitcnt lgkmcnt(0)
	s_barrier
	s_waitcnt lgkmcnt(0)
	v_mfma_f32_16x16x32_bf16 v[62:65], v[148:151], v[188:191], v[62:65]
	v_mfma_f32_16x16x32_bf16 v[62:65], v[158:161], v[198:201], v[62:65]
	v_mfma_f32_16x16x32_bf16 v[46:49], v[158:161], v[206:209], v[46:49]
	v_mfma_f32_16x16x32_bf16 v[46:49], v[148:151], v[202:205], v[46:49]
	v_mfma_f32_16x16x32_bf16 v[30:33], v[148:151], v[210:213], v[30:33]
	v_mfma_f32_16x16x32_bf16 v[30:33], v[158:161], v[214:217], v[30:33]
	v_mfma_f32_16x16x32_bf16 v[14:17], v[158:161], v[222:225], v[14:17]
	v_mfma_f32_16x16x32_bf16 v[14:17], v[148:151], v[218:221], v[14:17]
	v_mfma_f32_16x16x32_bf16 v[10:13], v[162:165], v[218:221], v[10:13]
	v_mfma_f32_16x16x32_bf16 v[10:13], v[166:169], v[222:225], v[10:13]
	v_mfma_f32_16x16x32_bf16 v[26:29], v[166:169], v[214:217], v[26:29]
	v_mfma_f32_16x16x32_bf16 v[26:29], v[162:165], v[210:213], v[26:29]
	v_mfma_f32_16x16x32_bf16 v[42:45], v[162:165], v[202:205], v[42:45]
	v_mfma_f32_16x16x32_bf16 v[42:45], v[166:169], v[206:209], v[42:45]
	v_mfma_f32_16x16x32_bf16 v[58:61], v[166:169], v[198:201], v[58:61]
	v_mfma_f32_16x16x32_bf16 v[58:61], v[162:165], v[188:191], v[58:61]
	v_mfma_f32_16x16x32_bf16 v[54:57], v[170:173], v[188:191], v[54:57]
	v_mfma_f32_16x16x32_bf16 v[54:57], v[174:177], v[198:201], v[54:57]
	v_mfma_f32_16x16x32_bf16 v[38:41], v[174:177], v[206:209], v[38:41]
	v_mfma_f32_16x16x32_bf16 v[38:41], v[170:173], v[202:205], v[38:41]
	v_mfma_f32_16x16x32_bf16 v[22:25], v[170:173], v[210:213], v[22:25]
	v_mfma_f32_16x16x32_bf16 v[22:25], v[174:177], v[214:217], v[22:25]
	v_mfma_f32_16x16x32_bf16 v[6:9], v[174:177], v[222:225], v[6:9]
	v_mfma_f32_16x16x32_bf16 v[6:9], v[170:173], v[218:221], v[6:9]
	v_mfma_f32_16x16x32_bf16 v[2:5], v[180:183], v[218:221], v[2:5]
	v_mfma_f32_16x16x32_bf16 v[2:5], v[184:187], v[222:225], v[2:5]
	v_mfma_f32_16x16x32_bf16 v[18:21], v[184:187], v[214:217], v[18:21]
	v_mfma_f32_16x16x32_bf16 v[18:21], v[180:183], v[210:213], v[18:21]
	v_mfma_f32_16x16x32_bf16 v[34:37], v[180:183], v[202:205], v[34:37]
	v_mfma_f32_16x16x32_bf16 v[34:37], v[184:187], v[206:209], v[34:37]
	v_mfma_f32_16x16x32_bf16 v[50:53], v[184:187], v[198:201], v[50:53]
	v_mfma_f32_16x16x32_bf16 v[50:53], v[180:183], v[188:191], v[50:53]
	s_barrier
; #define PG8_STAGE(bufoff, gbase, voff) do { _Pragma("unroll") for (int _i = 0; _i < 2; ++_i) \
;         __builtin_amdgcn_global_load_lds((const unsigned*)((const char*)(gbase) + (voff)[_i]), (PG8_LAS unsigned*)(lds + (bufoff) + ldsw + _i * 8192), 16, 0, 0); } while (0)
; #define PG8_LDA(dst, b, h) do { _Pragma("unroll") for (int m = 0; m < 4; ++m) _Pragma("unroll") for (int k = 0; k < 2; ++k) dst[m][k] = *(const PG8_LAS bf16x8*)(lds + PG8_SA(b, h) + aoff + m * 2048 + k * 1024); } while (0)
; #define PG8_LDB(dst, b, h) do { _Pragma("unroll") for (int n = 0; n < 2; ++n) _Pragma("unroll") for (int k = 0; k < 2; ++k) dst[n][k] = *(const PG8_LAS bf16x8*)(lds + PG8_SB(b, h) + boff + n * 2048 + k * 1024); } while (0)
; #define PG8_MMA(ai, bj, At, Bt) do { __builtin_amdgcn_s_setprio(1); _Pragma("unroll") for (int m = 0; m < 4; ++m) _Pragma("unroll") for (int n = 0; n < 2; ++n) _Pragma("unroll") for (int k = 0; k < 2; ++k) \
;         acc[ai][bj][m][n] = __builtin_amdgcn_mfma_f32_16x16x32_bf16(Bt[n][k], At[m][k], acc[ai][bj][m][n], 0, 0, 0); __builtin_amdgcn_s_setprio(0); } while (0)
; #define PG8_WAIT_V(n) asm volatile("s_waitcnt vmcnt(" #n ")" ::: "memory")
; #define PG8_WAIT_L(n) asm volatile("s_waitcnt lgkmcnt(" #n ")" ::: "memory")
; #define PG8_BAR __builtin_amdgcn_s_barrier()
; #define PG8_SCHED __builtin_amdgcn_sched_barrier(0)
; template <class Epi, class Sched, bool ALIGN_EPI = false, bool SP2 = false>
; __device__ __forceinline__ void gemm_phase(PG8_LAS unsigned char* lds, const Gemm g, const Sched& S, const Epi& E) {
;     ...
;             PG8_LDB(B0, 1, 0); PG8_LDB(B1, 1, 1); PG8_SCHED; PG8_LDA(At, 1, 0); PG8_STAGE(PG8_SA(0, 1), a2 + hstep, voffA);
;             PG8_WAIT_V(8); PG8_WAIT_L(0); PG8_BAR; PG8_MMA(0, 0, At, B0); PG8_MMA(0, 1, At, B1); PG8_BAR; PG8_SCHED;
;             PG8_LDA(At, 1, 1); PG8_STAGE(PG8_SB(1, 0), b3, voffB); PG8_STAGE(PG8_SB(1, 1), b3 + hstep, voffB); PG8_STAGE(PG8_SA(1, 0), a3, voffA);
;             PG8_WAIT_V(8); PG8_WAIT_L(0); PG8_BAR; PG8_MMA(1, 0, At, B0); PG8_MMA(1, 1, At, B1); PG8_BAR; PG8_SCHED;
	s_add_i32 s70, 0, 0x18000
	v_add_u32_e32 v138, s70, v1
	s_add_i32 s71, 0, 0x1c000
	ds_read_b128 v[148:151], v138
	ds_read_b128 v[158:161], v138 offset:1024
	ds_read_b128 v[162:165], v138 offset:2048
	ds_read_b128 v[166:169], v138 offset:3072
	v_add_u32_e32 v138, s71, v1
	ds_read_b128 v[170:173], v138
	ds_read_b128 v[174:177], v138 offset:1024
	ds_read_b128 v[180:183], v138 offset:2048
	ds_read_b128 v[184:187], v138 offset:3072
	s_mov_b32 m0, s28
	s_nop 0
	global_load_lds_dwordx4 v130, s[46:47]
	s_mov_b32 m0, s29
	s_nop 0
	global_load_lds_dwordx4 v134, s[46:47]
	s_add_u32 s46, s46, 0x4000
	s_addc_u32 s47, s47, 0
	s_mov_b32 m0, s30
	ds_read_b128 v[188:191], v155 offset:32768
	ds_read_b128 v[198:201], v155 offset:33792
	ds_read_b128 v[202:205], v155 offset:34816
	ds_read_b128 v[206:209], v155 offset:35840
	ds_read_b128 v[210:213], v155 offset:36864
	ds_read_b128 v[214:217], v155 offset:37888
	ds_read_b128 v[218:221], v155 offset:38912
	ds_read_b128 v[222:225], v155 offset:39936
	global_load_lds_dwordx4 v130, s[46:47]
	s_mov_b32 m0, s31
	s_nop 0
	global_load_lds_dwordx4 v134, s[46:47]
	s_waitcnt vmcnt(8)
	s_waitcnt lgkmcnt(0)
	s_barrier
	s_waitcnt lgkmcnt(0)
	v_mfma_f32_16x16x32_bf16 v[126:129], v[148:151], v[188:191], v[126:129]
	v_mfma_f32_16x16x32_bf16 v[126:129], v[158:161], v[198:201], v[126:129]
	v_mfma_f32_16x16x32_bf16 v[110:113], v[158:161], v[206:209], v[110:113]
	v_mfma_f32_16x16x32_bf16 v[110:113], v[148:151], v[202:205], v[110:113]
	v_mfma_f32_16x16x32_bf16 v[94:97], v[148:151], v[210:213], v[94:97]
	v_mfma_f32_16x16x32_bf16 v[94:97], v[158:161], v[214:217], v[94:97]
	v_mfma_f32_16x16x32_bf16 v[78:81], v[158:161], v[222:225], v[78:81]
	v_mfma_f32_16x16x32_bf16 v[78:81], v[148:151], v[218:221], v[78:81]
	v_mfma_f32_16x16x32_bf16 v[74:77], v[162:165], v[218:221], v[74:77]
	v_mfma_f32_16x16x32_bf16 v[74:77], v[166:169], v[222:225], v[74:77]
	v_mfma_f32_16x16x32_bf16 v[90:93], v[166:169], v[214:217], v[90:93]
	v_mfma_f32_16x16x32_bf16 v[90:93], v[162:165], v[210:213], v[90:93]
	v_mfma_f32_16x16x32_bf16 v[106:109], v[162:165], v[202:205], v[106:109]
	v_mfma_f32_16x16x32_bf16 v[106:109], v[166:169], v[206:209], v[106:109]
	v_mfma_f32_16x16x32_bf16 v[122:125], v[166:169], v[198:201], v[122:125]
	v_mfma_f32_16x16x32_bf16 v[122:125], v[162:165], v[188:191], v[122:125]
	v_mfma_f32_16x16x32_bf16 v[118:121], v[170:173], v[188:191], v[118:121]
	v_mfma_f32_16x16x32_bf16 v[118:121], v[174:177], v[198:201], v[118:121]
	v_mfma_f32_16x16x32_bf16 v[102:105], v[174:177], v[206:209], v[102:105]
	v_mfma_f32_16x16x32_bf16 v[102:105], v[170:173], v[202:205], v[102:105]
	v_mfma_f32_16x16x32_bf16 v[86:89], v[170:173], v[210:213], v[86:89]
	v_mfma_f32_16x16x32_bf16 v[86:89], v[174:177], v[214:217], v[86:89]
	v_mfma_f32_16x16x32_bf16 v[70:73], v[174:177], v[222:225], v[70:73]
	v_mfma_f32_16x16x32_bf16 v[70:73], v[170:173], v[218:221], v[70:73]
	v_mfma_f32_16x16x32_bf16 v[66:69], v[180:183], v[218:221], v[66:69]
	v_mfma_f32_16x16x32_bf16 v[66:69], v[184:187], v[222:225], v[66:69]
	v_mfma_f32_16x16x32_bf16 v[82:85], v[184:187], v[214:217], v[82:85]
	v_mfma_f32_16x16x32_bf16 v[82:85], v[180:183], v[210:213], v[82:85]
	v_mfma_f32_16x16x32_bf16 v[98:101], v[180:183], v[202:205], v[98:101]
	v_mfma_f32_16x16x32_bf16 v[98:101], v[184:187], v[206:209], v[98:101]
	v_mfma_f32_16x16x32_bf16 v[114:117], v[184:187], v[198:201], v[114:117]
	v_mfma_f32_16x16x32_bf16 v[114:117], v[180:183], v[188:191], v[114:117]
	s_barrier
	s_add_u32 s46, s44, 0x8000
	s_addc_u32 s47, s45, 0
	s_add_i32 s70, s70, s3
	s_mov_b32 m0, s70
	ds_read_b128 v[188:191], v155 offset:49152
	ds_read_b128 v[198:201], v155 offset:50176
	ds_read_b128 v[202:205], v155 offset:51200
	ds_read_b128 v[206:209], v155 offset:52224
	ds_read_b128 v[210:213], v155 offset:53248
	ds_read_b128 v[214:217], v155 offset:54272
	ds_read_b128 v[218:221], v155 offset:55296
	ds_read_b128 v[222:225], v155 offset:56320
	global_load_lds_dwordx4 v132, s[46:47]
	s_add_i32 m0, s70, 0x2000
	s_add_u32 s44, s44, 0xc000
	v_lshl_add_u64 v[226:227], s[46:47], 0, v[136:137]
	s_addc_u32 s45, s45, 0
	s_add_i32 s46, s71, s3
	global_load_lds_dwordx4 v[226:227], off
	s_mov_b32 m0, s46
	s_nop 0
	global_load_lds_dwordx4 v132, s[44:45]
	s_add_i32 m0, s46, 0x2000
	s_nop 0
	global_load_lds_dwordx4 v136, s[44:45]
	s_waitcnt vmcnt(6)
	s_waitcnt lgkmcnt(0)
	s_barrier
	s_waitcnt lgkmcnt(0)
	v_mfma_f32_16x16x32_bf16 v[62:65], v[148:151], v[188:191], v[62:65]
	v_mfma_f32_16x16x32_bf16 v[62:65], v[158:161], v[198:201], v[62:65]
	v_mfma_f32_16x16x32_bf16 v[46:49], v[158:161], v[206:209], v[46:49]
	v_mfma_f32_16x16x32_bf16 v[46:49], v[148:151], v[202:205], v[46:49]
	v_mfma_f32_16x16x32_bf16 v[30:33], v[148:151], v[210:213], v[30:33]
	v_mfma_f32_16x16x32_bf16 v[30:33], v[158:161], v[214:217], v[30:33]
	v_mfma_f32_16x16x32_bf16 v[14:17], v[158:161], v[222:225], v[14:17]
	v_mfma_f32_16x16x32_bf16 v[14:17], v[148:151], v[218:221], v[14:17]
	v_mfma_f32_16x16x32_bf16 v[10:13], v[162:165], v[218:221], v[10:13]
	v_mfma_f32_16x16x32_bf16 v[10:13], v[166:169], v[222:225], v[10:13]
	v_mfma_f32_16x16x32_bf16 v[26:29], v[166:169], v[214:217], v[26:29]
	v_mfma_f32_16x16x32_bf16 v[26:29], v[162:165], v[210:213], v[26:29]
	v_mfma_f32_16x16x32_bf16 v[42:45], v[162:165], v[202:205], v[42:45]
	v_mfma_f32_16x16x32_bf16 v[42:45], v[166:169], v[206:209], v[42:45]
	v_mfma_f32_16x16x32_bf16 v[58:61], v[166:169], v[198:201], v[58:61]
	v_mfma_f32_16x16x32_bf16 v[58:61], v[162:165], v[188:191], v[58:61]
	v_mfma_f32_16x16x32_bf16 v[54:57], v[170:173], v[188:191], v[54:57]
	v_mfma_f32_16x16x32_bf16 v[54:57], v[174:177], v[198:201], v[54:57]
	v_mfma_f32_16x16x32_bf16 v[38:41], v[174:177], v[206:209], v[38:41]
	v_mfma_f32_16x16x32_bf16 v[38:41], v[170:173], v[202:205], v[38:41]
	v_mfma_f32_16x16x32_bf16 v[22:25], v[170:173], v[210:213], v[22:25]
	v_mfma_f32_16x16x32_bf16 v[22:25], v[174:177], v[214:217], v[22:25]
	v_mfma_f32_16x16x32_bf16 v[6:9], v[174:177], v[222:225], v[6:9]
	v_mfma_f32_16x16x32_bf16 v[6:9], v[170:173], v[218:221], v[6:9]
	v_mfma_f32_16x16x32_bf16 v[2:5], v[180:183], v[218:221], v[2:5]
	v_mfma_f32_16x16x32_bf16 v[2:5], v[184:187], v[222:225], v[2:5]
	v_mfma_f32_16x16x32_bf16 v[18:21], v[184:187], v[214:217], v[18:21]
	v_mfma_f32_16x16x32_bf16 v[18:21], v[180:183], v[210:213], v[18:21]
	v_mfma_f32_16x16x32_bf16 v[34:37], v[180:183], v[202:205], v[34:37]
	v_mfma_f32_16x16x32_bf16 v[34:37], v[184:187], v[206:209], v[34:37]
	v_mfma_f32_16x16x32_bf16 v[50:53], v[184:187], v[198:201], v[50:53]
	v_mfma_f32_16x16x32_bf16 v[50:53], v[180:183], v[188:191], v[50:53]
	s_barrier
	s_add_i32 s69, s69, 2
	s_add_u32 s40, s40, 0x10000
	s_addc_u32 s41, s41, 0
	s_add_u32 s67, s67, 0x10000
	s_addc_u32 s68, s68, 0
	s_cmp_gt_u32 s69, 61
	s_cbranch_scc0 .LBB0_840
	s_and_b64 vcc, exec, s[14:15]
	s_cbranch_vccz .LBB0_843
	s_barrier

; #define PG8_STAGE(bufoff, gbase, voff) do { _Pragma("unroll") for (int _i = 0; _i < 2; ++_i) \
;         __builtin_amdgcn_global_load_lds((const unsigned*)((const char*)(gbase) + (voff)[_i]), (PG8_LAS unsigned*)(lds + (bufoff) + ldsw + _i * 8192), 16, 0, 0); } while (0)
; #define PG8_LDA(dst, b, h) do { _Pragma("unroll") for (int m = 0; m < 4; ++m) _Pragma("unroll") for (int k = 0; k < 2; ++k) dst[m][k] = *(const PG8_LAS bf16x8*)(lds + PG8_SA(b, h) + aoff + m * 2048 + k * 1024); } while (0)
; #define PG8_LDB(dst, b, h) do { _Pragma("unroll") for (int n = 0; n < 2; ++n) _Pragma("unroll") for (int k = 0; k < 2; ++k) dst[n][k] = *(const PG8_LAS bf16x8*)(lds + PG8_SB(b, h) + boff + n * 2048 + k * 1024); } while (0)
; #define PG8_MMA(ai, bj, At, Bt) do { __builtin_amdgcn_s_setprio(1); _Pragma("unroll") for (int m = 0; m < 4; ++m) _Pragma("unroll") for (int n = 0; n < 2; ++n) _Pragma("unroll") for (int k = 0; k < 2; ++k) \
;         acc[ai][bj][m][n] = __builtin_amdgcn_mfma_f32_16x16x32_bf16(Bt[n][k], At[m][k], acc[ai][bj][m][n], 0, 0, 0); __builtin_amdgcn_s_setprio(0); } while (0)
; #define PG8_WAIT_V(n) asm volatile("s_waitcnt vmcnt(" #n ")" ::: "memory")
; #define PG8_WAIT_L(n) asm volatile("s_waitcnt lgkmcnt(" #n ")" ::: "memory")
; template <class Epi, class Sched, bool ALIGN_EPI = false, bool SP2 = false>
; __device__ __forceinline__ void gemm_phase(PG8_LAS unsigned char* lds, const Gemm g, const Sched& S, const Epi& E) {
;     ...
;             const bool last = (t == nt - 2);
;             const char* a1 = cA + (size_t)(t + 1) * kstep;
;             const char* a2 = last ? nA : cA + (size_t)(t + 2) * kstep; const char* b2 = last ? nB : cB + (size_t)(t + 2) * kstep;
;             const char* a3 = a2 + kstep; const char* b3 = b2 + kstep;
;             if (last && has_next) S.a_ready(nxt);
;             if constexpr (SP2) {
;             PG8_LDB(B0, 0, 0); PG8_LDB(B1, 0, 1); PG8_SCHED; PG8_LDA(At, 0, 0); PG8_STAGE(PG8_SA(1, 1), a1 + hstep, voffA);
;             PG8_WAIT_V(8); PG8_WAIT_L(0); PG8_BAR; PG8_MMA(0, 0, At, B0); PG8_MMA(0, 1, At, B1); PG8_BAR; PG8_SCHED;
;             PG8_LDA(At, 0, 1); PG8_STAGE(PG8_SB(0, 0), b2, voffB); PG8_STAGE(PG8_SB(0, 1), b2 + hstep, voffB); PG8_STAGE(PG8_SA(0, 0), a2, voffA);
;             PG8_WAIT_V(8); PG8_WAIT_L(0); PG8_BAR; PG8_MMA(1, 0, At, B0); PG8_MMA(1, 1, At, B1); PG8_BAR; PG8_SCHED;
.LBB0_939:
	s_or_b32 s24, s59, 1
	s_lshl_b64 s[62:63], s[24:25], 15
	s_add_i32 s24, s59, 2
	ds_read_b128 v[156:159], v193
	ds_read_b128 v[160:163], v193 offset:1024
	ds_read_b128 v[196:199], v193 offset:2048
	ds_read_b128 v[200:203], v193 offset:3072
	ds_read_b128 v[204:207], v194
	ds_read_b128 v[208:211], v194 offset:1024
	ds_read_b128 v[212:215], v194 offset:2048
	ds_read_b128 v[216:219], v194 offset:3072
	s_lshl_b64 s[8:9], s[24:25], 15
	s_add_u32 s44, s6, s8
	s_addc_u32 s45, s7, s9
	s_cmpk_eq_i32 s59, 0xaa
	s_cselect_b32 s46, s58, s44
	s_cselect_b32 s47, s56, s45
	s_cselect_b32 s44, 0, s8
	s_cselect_b32 s45, 0, s9
	s_add_u32 s8, s46, 0x8000
	s_addc_u32 s9, s47, 0
	s_add_u32 s44, s14, s44
	s_addc_u32 s45, s15, s45
	s_add_u32 s62, s6, s62
	s_addc_u32 s63, s7, s63
	s_add_u32 s62, s62, 0x4000
	s_addc_u32 s63, s63, 0
	s_sub_u32 s8, s62, 0x4000
	s_subb_u32 s9, s63, 0
	s_mov_b32 m0, s51
	s_nop 0
	global_load_lds_dwordx4 v130, s[8:9]
	s_mov_b32 m0, s57
	s_nop 0
	global_load_lds_dwordx4 v134, s[8:9]
	s_add_i32 m0, s30, 0xc000
	ds_read_b128 v[220:223], v186
	ds_read_b128 v[224:227], v186 offset:1024
	ds_read_b128 v[228:231], v186 offset:2048
	ds_read_b128 v[232:235], v186 offset:3072
	ds_read_b128 v[236:239], v186 offset:4096
	ds_read_b128 v[240:243], v186 offset:5120
	ds_read_b128 v[244:247], v186 offset:6144
	ds_read_b128 v[248:251], v186 offset:7168
	global_load_lds_dwordx4 v130, s[62:63]
	s_add_i32 m0, s30, 0xe000
	s_nop 0
	global_load_lds_dwordx4 v134, s[62:63]
	s_waitcnt vmcnt(8)
	s_waitcnt lgkmcnt(0)
	s_barrier
	s_waitcnt lgkmcnt(0)
	v_mfma_f32_16x16x32_bf16 v[126:129], v[156:159], v[220:223], v[126:129]
	v_mfma_f32_16x16x32_bf16 v[126:129], v[160:163], v[224:227], v[126:129]
	v_mfma_f32_16x16x32_bf16 v[110:113], v[160:163], v[232:235], v[110:113]
	v_mfma_f32_16x16x32_bf16 v[110:113], v[156:159], v[228:231], v[110:113]
	v_mfma_f32_16x16x32_bf16 v[94:97], v[156:159], v[236:239], v[94:97]
	v_mfma_f32_16x16x32_bf16 v[94:97], v[160:163], v[240:243], v[94:97]
	v_mfma_f32_16x16x32_bf16 v[78:81], v[160:163], v[248:251], v[78:81]
	v_mfma_f32_16x16x32_bf16 v[78:81], v[156:159], v[244:247], v[78:81]
	v_mfma_f32_16x16x32_bf16 v[74:77], v[196:199], v[244:247], v[74:77]
	v_mfma_f32_16x16x32_bf16 v[74:77], v[200:203], v[248:251], v[74:77]
	v_mfma_f32_16x16x32_bf16 v[90:93], v[200:203], v[240:243], v[90:93]
	v_mfma_f32_16x16x32_bf16 v[90:93], v[196:199], v[236:239], v[90:93]
	v_mfma_f32_16x16x32_bf16 v[106:109], v[196:199], v[228:231], v[106:109]
	v_mfma_f32_16x16x32_bf16 v[106:109], v[200:203], v[232:235], v[106:109]
	v_mfma_f32_16x16x32_bf16 v[122:125], v[200:203], v[224:227], v[122:125]
	v_mfma_f32_16x16x32_bf16 v[122:125], v[196:199], v[220:223], v[122:125]
	v_mfma_f32_16x16x32_bf16 v[118:121], v[204:207], v[220:223], v[118:121]
	v_mfma_f32_16x16x32_bf16 v[118:121], v[208:211], v[224:227], v[118:121]
	v_mfma_f32_16x16x32_bf16 v[102:105], v[208:211], v[232:235], v[102:105]
	v_mfma_f32_16x16x32_bf16 v[102:105], v[204:207], v[228:231], v[102:105]
	v_mfma_f32_16x16x32_bf16 v[86:89], v[204:207], v[236:239], v[86:89]
	v_mfma_f32_16x16x32_bf16 v[86:89], v[208:211], v[240:243], v[86:89]
	v_mfma_f32_16x16x32_bf16 v[70:73], v[208:211], v[248:251], v[70:73]
	v_mfma_f32_16x16x32_bf16 v[70:73], v[204:207], v[244:247], v[70:73]
	v_mfma_f32_16x16x32_bf16 v[66:69], v[212:215], v[244:247], v[66:69]
	v_mfma_f32_16x16x32_bf16 v[66:69], v[216:219], v[248:251], v[66:69]
	v_mfma_f32_16x16x32_bf16 v[82:85], v[216:219], v[240:243], v[82:85]
	v_mfma_f32_16x16x32_bf16 v[82:85], v[212:215], v[236:239], v[82:85]
	v_mfma_f32_16x16x32_bf16 v[98:101], v[212:215], v[228:231], v[98:101]
	v_mfma_f32_16x16x32_bf16 v[98:101], v[216:219], v[232:235], v[98:101]
	v_mfma_f32_16x16x32_bf16 v[114:117], v[216:219], v[224:227], v[114:117]
	v_mfma_f32_16x16x32_bf16 v[114:117], v[212:215], v[220:223], v[114:117]
	s_barrier
	s_add_i32 s62, s67, s29
	s_mov_b32 m0, s62
	ds_read_b128 v[220:223], v186 offset:16384
	ds_read_b128 v[224:227], v186 offset:17408
	ds_read_b128 v[228:231], v186 offset:18432
	ds_read_b128 v[232:235], v186 offset:19456
	ds_read_b128 v[236:239], v186 offset:20480
	ds_read_b128 v[240:243], v186 offset:21504
	ds_read_b128 v[244:247], v186 offset:22528
	ds_read_b128 v[248:251], v186 offset:23552
	global_load_lds_dwordx4 v132, s[44:45]
	s_add_i32 m0, s62, 0x2000
	s_add_u32 s62, s44, 0x4000
	s_addc_u32 s63, s45, 0
	s_add_i32 s72, s68, s29
	global_load_lds_dwordx4 v136, s[44:45]
	s_mov_b32 m0, s72
	s_nop 0
	global_load_lds_dwordx4 v132, s[62:63]
	s_add_i32 m0, s72, 0x2000
	s_nop 0
	global_load_lds_dwordx4 v136, s[62:63]
	s_waitcnt vmcnt(6)
	s_waitcnt lgkmcnt(0)
	s_barrier
; #define PG8_STAGE(bufoff, gbase, voff) do { _Pragma("unroll") for (int _i = 0; _i < 2; ++_i) \
;         __builtin_amdgcn_global_load_lds((const unsigned*)((const char*)(gbase) + (voff)[_i]), (PG8_LAS unsigned*)(lds + (bufoff) + ldsw + _i * 8192), 16, 0, 0); } while (0)
; #define PG8_LDA(dst, b, h) do { _Pragma("unroll") for (int m = 0; m < 4; ++m) _Pragma("unroll") for (int k = 0; k < 2; ++k) dst[m][k] = *(const PG8_LAS bf16x8*)(lds + PG8_SA(b, h) + aoff + m * 2048 + k * 1024); } while (0)
; #define PG8_LDB(dst, b, h) do { _Pragma("unroll") for (int n = 0; n < 2; ++n) _Pragma("unroll") for (int k = 0; k < 2; ++k) dst[n][k] = *(const PG8_LAS bf16x8*)(lds + PG8_SB(b, h) + boff + n * 2048 + k * 1024); } while (0)
; #define PG8_MMA(ai, bj, At, Bt) do { __builtin_amdgcn_s_setprio(1); _Pragma("unroll") for (int m = 0; m < 4; ++m) _Pragma("unroll") for (int n = 0; n < 2; ++n) _Pragma("unroll") for (int k = 0; k < 2; ++k) \
;         acc[ai][bj][m][n] = __builtin_amdgcn_mfma_f32_16x16x32_bf16(Bt[n][k], At[m][k], acc[ai][bj][m][n], 0, 0, 0); __builtin_amdgcn_s_setprio(0); } while (0)
; #define PG8_WAIT_V(n) asm volatile("s_waitcnt vmcnt(" #n ")" ::: "memory")
; #define PG8_WAIT_L(n) asm volatile("s_waitcnt lgkmcnt(" #n ")" ::: "memory")
; #define PG8_BAR __builtin_amdgcn_s_barrier()
; #define PG8_SCHED __builtin_amdgcn_sched_barrier(0)
; template <class Epi, class Sched, bool ALIGN_EPI = false, bool SP2 = false>
; __device__ __forceinline__ void gemm_phase(PG8_LAS unsigned char* lds, const Gemm g, const Sched& S, const Epi& E) {
;     ...
;             PG8_WAIT_V(8); PG8_WAIT_L(0); PG8_BAR; PG8_MMA(1, 0, At, B0); PG8_MMA(1, 1, At, B1); PG8_BAR; PG8_SCHED;
;             PG8_LDB(B0, 1, 0); PG8_LDB(B1, 1, 1); PG8_SCHED; PG8_LDA(At, 1, 0); PG8_STAGE(PG8_SA(0, 1), a2 + hstep, voffA);
;             PG8_WAIT_V(8); PG8_WAIT_L(0); PG8_BAR; PG8_MMA(0, 0, At, B0); PG8_MMA(0, 1, At, B1); PG8_BAR; PG8_SCHED;
	s_waitcnt lgkmcnt(0)
	v_mfma_f32_16x16x32_bf16 v[62:65], v[156:159], v[220:223], v[62:65]
	v_mfma_f32_16x16x32_bf16 v[62:65], v[160:163], v[224:227], v[62:65]
	v_mfma_f32_16x16x32_bf16 v[46:49], v[160:163], v[232:235], v[46:49]
	v_mfma_f32_16x16x32_bf16 v[46:49], v[156:159], v[228:231], v[46:49]
	v_mfma_f32_16x16x32_bf16 v[30:33], v[156:159], v[236:239], v[30:33]
	v_mfma_f32_16x16x32_bf16 v[30:33], v[160:163], v[240:243], v[30:33]
	v_mfma_f32_16x16x32_bf16 v[14:17], v[160:163], v[248:251], v[14:17]
	v_mfma_f32_16x16x32_bf16 v[14:17], v[156:159], v[244:247], v[14:17]
	v_mfma_f32_16x16x32_bf16 v[10:13], v[196:199], v[244:247], v[10:13]
	v_mfma_f32_16x16x32_bf16 v[10:13], v[200:203], v[248:251], v[10:13]
	v_mfma_f32_16x16x32_bf16 v[26:29], v[200:203], v[240:243], v[26:29]
	v_mfma_f32_16x16x32_bf16 v[26:29], v[196:199], v[236:239], v[26:29]
	v_mfma_f32_16x16x32_bf16 v[42:45], v[196:199], v[228:231], v[42:45]
	v_mfma_f32_16x16x32_bf16 v[42:45], v[200:203], v[232:235], v[42:45]
	v_mfma_f32_16x16x32_bf16 v[58:61], v[200:203], v[224:227], v[58:61]
	v_mfma_f32_16x16x32_bf16 v[58:61], v[196:199], v[220:223], v[58:61]
	v_mfma_f32_16x16x32_bf16 v[54:57], v[204:207], v[220:223], v[54:57]
	v_mfma_f32_16x16x32_bf16 v[54:57], v[208:211], v[224:227], v[54:57]
	v_mfma_f32_16x16x32_bf16 v[38:41], v[208:211], v[232:235], v[38:41]
	v_mfma_f32_16x16x32_bf16 v[38:41], v[204:207], v[228:231], v[38:41]
	v_mfma_f32_16x16x32_bf16 v[22:25], v[204:207], v[236:239], v[22:25]
	v_mfma_f32_16x16x32_bf16 v[22:25], v[208:211], v[240:243], v[22:25]
	v_mfma_f32_16x16x32_bf16 v[6:9], v[208:211], v[248:251], v[6:9]
	v_mfma_f32_16x16x32_bf16 v[6:9], v[204:207], v[244:247], v[6:9]
	v_mfma_f32_16x16x32_bf16 v[2:5], v[212:215], v[244:247], v[2:5]
	v_mfma_f32_16x16x32_bf16 v[2:5], v[216:219], v[248:251], v[2:5]
	v_mfma_f32_16x16x32_bf16 v[18:21], v[216:219], v[240:243], v[18:21]
	v_mfma_f32_16x16x32_bf16 v[18:21], v[212:215], v[236:239], v[18:21]
	v_mfma_f32_16x16x32_bf16 v[34:37], v[212:215], v[228:231], v[34:37]
	v_mfma_f32_16x16x32_bf16 v[34:37], v[216:219], v[232:235], v[34:37]
	v_mfma_f32_16x16x32_bf16 v[50:53], v[216:219], v[224:227], v[50:53]
	v_mfma_f32_16x16x32_bf16 v[50:53], v[212:215], v[220:223], v[50:53]
	s_barrier
	s_add_i32 s62, 0, 0x18000
	v_add_u32_e32 v145, s62, v166
	s_add_i32 s63, 0, 0x1c000
	ds_read_b128 v[156:159], v145
	ds_read_b128 v[160:163], v145 offset:1024
	ds_read_b128 v[196:199], v145 offset:2048
	ds_read_b128 v[200:203], v145 offset:3072
	v_add_u32_e32 v145, s63, v166
	ds_read_b128 v[204:207], v145
	ds_read_b128 v[208:211], v145 offset:1024
	ds_read_b128 v[212:215], v145 offset:2048
	ds_read_b128 v[216:219], v145 offset:3072
	s_mov_b32 m0, s30
	s_nop 0
	global_load_lds_dwordx4 v130, s[46:47]
	s_mov_b32 m0, s31
	s_nop 0
	global_load_lds_dwordx4 v134, s[46:47]
	s_add_u32 s46, s46, 0x4000
	s_addc_u32 s47, s47, 0
	s_mov_b32 m0, s35
	ds_read_b128 v[220:223], v186 offset:32768
	ds_read_b128 v[224:227], v186 offset:33792
	ds_read_b128 v[228:231], v186 offset:34816
	ds_read_b128 v[232:235], v186 offset:35840
	ds_read_b128 v[236:239], v186 offset:36864
	ds_read_b128 v[240:243], v186 offset:37888
	ds_read_b128 v[244:247], v186 offset:38912
	ds_read_b128 v[248:251], v186 offset:39936
	global_load_lds_dwordx4 v130, s[46:47]
	s_mov_b32 m0, s48
	s_nop 0
	global_load_lds_dwordx4 v134, s[46:47]
	s_waitcnt vmcnt(8)
	s_waitcnt lgkmcnt(0)
	s_barrier
; #define PG8_STAGE(bufoff, gbase, voff) do { _Pragma("unroll") for (int _i = 0; _i < 2; ++_i) \
;         __builtin_amdgcn_global_load_lds((const unsigned*)((const char*)(gbase) + (voff)[_i]), (PG8_LAS unsigned*)(lds + (bufoff) + ldsw + _i * 8192), 16, 0, 0); } while (0)
; #define PG8_LDA(dst, b, h) do { _Pragma("unroll") for (int m = 0; m < 4; ++m) _Pragma("unroll") for (int k = 0; k < 2; ++k) dst[m][k] = *(const PG8_LAS bf16x8*)(lds + PG8_SA(b, h) + aoff + m * 2048 + k * 1024); } while (0)
; #define PG8_MMA(ai, bj, At, Bt) do { __builtin_amdgcn_s_setprio(1); _Pragma("unroll") for (int m = 0; m < 4; ++m) _Pragma("unroll") for (int n = 0; n < 2; ++n) _Pragma("unroll") for (int k = 0; k < 2; ++k) \
;         acc[ai][bj][m][n] = __builtin_amdgcn_mfma_f32_16x16x32_bf16(Bt[n][k], At[m][k], acc[ai][bj][m][n], 0, 0, 0); __builtin_amdgcn_s_setprio(0); } while (0)
; #define PG8_WAIT_V(n) asm volatile("s_waitcnt vmcnt(" #n ")" ::: "memory")
; #define PG8_WAIT_L(n) asm volatile("s_waitcnt lgkmcnt(" #n ")" ::: "memory")
; #define PG8_BAR __builtin_amdgcn_s_barrier()
; #define PG8_SCHED __builtin_amdgcn_sched_barrier(0)
; template <class Epi, class Sched, bool ALIGN_EPI = false, bool SP2 = false>
; __device__ __forceinline__ void gemm_phase(PG8_LAS unsigned char* lds, const Gemm g, const Sched& S, const Epi& E) {
;     ...
;             PG8_WAIT_V(8); PG8_WAIT_L(0); PG8_BAR; PG8_MMA(0, 0, At, B0); PG8_MMA(0, 1, At, B1); PG8_BAR; PG8_SCHED;
;             PG8_LDA(At, 1, 1); PG8_STAGE(PG8_SB(1, 0), b3, voffB); PG8_STAGE(PG8_SB(1, 1), b3 + hstep, voffB); PG8_STAGE(PG8_SA(1, 0), a3, voffA);
;             PG8_WAIT_V(8); PG8_WAIT_L(0); PG8_BAR; PG8_MMA(1, 0, At, B0); PG8_MMA(1, 1, At, B1); PG8_BAR; PG8_SCHED;
	s_waitcnt lgkmcnt(0)
	v_mfma_f32_16x16x32_bf16 v[126:129], v[156:159], v[220:223], v[126:129]
	v_mfma_f32_16x16x32_bf16 v[126:129], v[160:163], v[224:227], v[126:129]
	v_mfma_f32_16x16x32_bf16 v[110:113], v[160:163], v[232:235], v[110:113]
	v_mfma_f32_16x16x32_bf16 v[110:113], v[156:159], v[228:231], v[110:113]
	v_mfma_f32_16x16x32_bf16 v[94:97], v[156:159], v[236:239], v[94:97]
	v_mfma_f32_16x16x32_bf16 v[94:97], v[160:163], v[240:243], v[94:97]
	v_mfma_f32_16x16x32_bf16 v[78:81], v[160:163], v[248:251], v[78:81]
	v_mfma_f32_16x16x32_bf16 v[78:81], v[156:159], v[244:247], v[78:81]
	v_mfma_f32_16x16x32_bf16 v[74:77], v[196:199], v[244:247], v[74:77]
	v_mfma_f32_16x16x32_bf16 v[74:77], v[200:203], v[248:251], v[74:77]
	v_mfma_f32_16x16x32_bf16 v[90:93], v[200:203], v[240:243], v[90:93]
	v_mfma_f32_16x16x32_bf16 v[90:93], v[196:199], v[236:239], v[90:93]
	v_mfma_f32_16x16x32_bf16 v[106:109], v[196:199], v[228:231], v[106:109]
	v_mfma_f32_16x16x32_bf16 v[106:109], v[200:203], v[232:235], v[106:109]
	v_mfma_f32_16x16x32_bf16 v[122:125], v[200:203], v[224:227], v[122:125]
	v_mfma_f32_16x16x32_bf16 v[122:125], v[196:199], v[220:223], v[122:125]
	v_mfma_f32_16x16x32_bf16 v[118:121], v[204:207], v[220:223], v[118:121]
	v_mfma_f32_16x16x32_bf16 v[118:121], v[208:211], v[224:227], v[118:121]
	v_mfma_f32_16x16x32_bf16 v[102:105], v[208:211], v[232:235], v[102:105]
	v_mfma_f32_16x16x32_bf16 v[102:105], v[204:207], v[228:231], v[102:105]
	v_mfma_f32_16x16x32_bf16 v[86:89], v[204:207], v[236:239], v[86:89]
	v_mfma_f32_16x16x32_bf16 v[86:89], v[208:211], v[240:243], v[86:89]
	v_mfma_f32_16x16x32_bf16 v[70:73], v[208:211], v[248:251], v[70:73]
	v_mfma_f32_16x16x32_bf16 v[70:73], v[204:207], v[244:247], v[70:73]
	v_mfma_f32_16x16x32_bf16 v[66:69], v[212:215], v[244:247], v[66:69]
	v_mfma_f32_16x16x32_bf16 v[66:69], v[216:219], v[248:251], v[66:69]
	v_mfma_f32_16x16x32_bf16 v[82:85], v[216:219], v[240:243], v[82:85]
	v_mfma_f32_16x16x32_bf16 v[82:85], v[212:215], v[236:239], v[82:85]
	v_mfma_f32_16x16x32_bf16 v[98:101], v[212:215], v[228:231], v[98:101]
	v_mfma_f32_16x16x32_bf16 v[98:101], v[216:219], v[232:235], v[98:101]
	v_mfma_f32_16x16x32_bf16 v[114:117], v[216:219], v[224:227], v[114:117]
	v_mfma_f32_16x16x32_bf16 v[114:117], v[212:215], v[220:223], v[114:117]
	s_barrier
	s_add_u32 s46, s44, 0x8000
	s_addc_u32 s47, s45, 0
	s_add_i32 s62, s62, s29
	s_mov_b32 m0, s62
	ds_read_b128 v[220:223], v186 offset:49152
	ds_read_b128 v[224:227], v186 offset:50176
	ds_read_b128 v[228:231], v186 offset:51200
	ds_read_b128 v[232:235], v186 offset:52224
	ds_read_b128 v[236:239], v186 offset:53248
	ds_read_b128 v[240:243], v186 offset:54272
	ds_read_b128 v[244:247], v186 offset:55296
	ds_read_b128 v[248:251], v186 offset:56320
	global_load_lds_dwordx4 v132, s[46:47]
	s_add_i32 m0, s62, 0x2000
	s_add_u32 s44, s44, 0xc000
	v_lshl_add_u64 v[164:165], s[46:47], 0, v[136:137]
	s_addc_u32 s45, s45, 0
	s_add_i32 s46, s63, s29
	global_load_lds_dwordx4 v[164:165], off
	s_mov_b32 m0, s46
	s_nop 0
	global_load_lds_dwordx4 v132, s[44:45]
	s_add_i32 m0, s46, 0x2000
	s_nop 0
	global_load_lds_dwordx4 v136, s[44:45]
	s_waitcnt vmcnt(6)
	s_waitcnt lgkmcnt(0)
	s_barrier
	s_waitcnt lgkmcnt(0)
	v_mfma_f32_16x16x32_bf16 v[62:65], v[156:159], v[220:223], v[62:65]
	v_mfma_f32_16x16x32_bf16 v[62:65], v[160:163], v[224:227], v[62:65]
	v_mfma_f32_16x16x32_bf16 v[46:49], v[160:163], v[232:235], v[46:49]
	v_mfma_f32_16x16x32_bf16 v[46:49], v[156:159], v[228:231], v[46:49]
	v_mfma_f32_16x16x32_bf16 v[30:33], v[156:159], v[236:239], v[30:33]
	v_mfma_f32_16x16x32_bf16 v[30:33], v[160:163], v[240:243], v[30:33]
	v_mfma_f32_16x16x32_bf16 v[14:17], v[160:163], v[248:251], v[14:17]
	v_mfma_f32_16x16x32_bf16 v[14:17], v[156:159], v[244:247], v[14:17]
	v_mfma_f32_16x16x32_bf16 v[10:13], v[196:199], v[244:247], v[10:13]
	v_mfma_f32_16x16x32_bf16 v[10:13], v[200:203], v[248:251], v[10:13]
	v_mfma_f32_16x16x32_bf16 v[26:29], v[200:203], v[240:243], v[26:29]
	v_mfma_f32_16x16x32_bf16 v[26:29], v[196:199], v[236:239], v[26:29]
	v_mfma_f32_16x16x32_bf16 v[42:45], v[196:199], v[228:231], v[42:45]
	v_mfma_f32_16x16x32_bf16 v[42:45], v[200:203], v[232:235], v[42:45]
	v_mfma_f32_16x16x32_bf16 v[58:61], v[200:203], v[224:227], v[58:61]
	v_mfma_f32_16x16x32_bf16 v[58:61], v[196:199], v[220:223], v[58:61]
	v_mfma_f32_16x16x32_bf16 v[54:57], v[204:207], v[220:223], v[54:57]
	v_mfma_f32_16x16x32_bf16 v[54:57], v[208:211], v[224:227], v[54:57]
	v_mfma_f32_16x16x32_bf16 v[38:41], v[208:211], v[232:235], v[38:41]
	v_mfma_f32_16x16x32_bf16 v[38:41], v[204:207], v[228:231], v[38:41]
	v_mfma_f32_16x16x32_bf16 v[22:25], v[204:207], v[236:239], v[22:25]
	v_mfma_f32_16x16x32_bf16 v[22:25], v[208:211], v[240:243], v[22:25]
	v_mfma_f32_16x16x32_bf16 v[6:9], v[208:211], v[248:251], v[6:9]
	v_mfma_f32_16x16x32_bf16 v[6:9], v[204:207], v[244:247], v[6:9]
	v_mfma_f32_16x16x32_bf16 v[2:5], v[212:215], v[244:247], v[2:5]
	v_mfma_f32_16x16x32_bf16 v[2:5], v[216:219], v[248:251], v[2:5]
	v_mfma_f32_16x16x32_bf16 v[18:21], v[216:219], v[240:243], v[18:21]
	v_mfma_f32_16x16x32_bf16 v[18:21], v[212:215], v[236:239], v[18:21]
	v_mfma_f32_16x16x32_bf16 v[34:37], v[212:215], v[228:231], v[34:37]
	v_mfma_f32_16x16x32_bf16 v[34:37], v[216:219], v[232:235], v[34:37]
	v_mfma_f32_16x16x32_bf16 v[50:53], v[216:219], v[224:227], v[50:53]
	v_mfma_f32_16x16x32_bf16 v[50:53], v[212:215], v[220:223], v[50:53]
	s_barrier
	s_cmpk_gt_u32 s59, 0xa9
	s_mov_b32 s59, s24
	s_cbranch_scc0 .LBB0_939
	s_and_b64 vcc, exec, s[38:39]
	s_cbranch_vccz .LBB0_942
	s_barrier
